# s_setprio 2 during the inproj GEMM main loops (epilogue waves of the co-resident block yield to the MFMA loop)
# speedup vs baseline: 1.0526x; 1.0043x over previous
.LBB0_171:
	s_lshr_b32 s88, s75, 3
	s_lshl_b32 s88, s88, 4
	s_and_b32 s90, s75, 7
	s_or_b32 s88, s88, s90
	s_lshl_b32 s90, s89, 3
	s_add_i32 s88, s88, s90
	s_ashr_i32 s1, s88, 31
	s_lshr_b32 s1, s1, 23
	s_add_i32 s1, s88, s1
	s_ashr_i32 s1, s1, 9
	s_and_b32 s0, s88, 7
	s_lshl_b32 s1, s1, 3
	s_or_b32 s34, s1, s0
	s_mul_hi_i32 s0, s34, 0x92492493
	s_add_i32 s0, s0, s34
	s_lshr_b32 s1, s0, 31
	s_ashr_i32 s70, s0, 2
	s_add_i32 s70, s70, s1
	s_lshl_b32 s0, s70, 3
	s_bfe_u32 s1, s88, 0x30003
	s_or_b32 s66, s0, s1
	s_mul_i32 s0, s70, 7
	s_sub_i32 s77, s34, s0
	s_lshl_b32 s0, s77, 3
	s_bfe_u32 s76, s88, 0x30006
	s_or_b32 s0, s0, s76
	s_ashr_i32 s67, s66, 31
	s_ashr_i32 s1, s0, 31
	s_lshl_b64 s[4:5], s[0:1], 18
	s_lshl_b64 s[6:7], s[66:67], 18
	s_cmp_lg_u32 s89, 0
	s_cbranch_scc1 .Lmy_ip0_pass2
	s_barrier
	s_setprio 2
	s_lshl_b64 s[64:65], s[66:67], 17
	s_add_u32 s84, s50, 0x3a00000
	s_addc_u32 s85, s51, 0
	s_add_u32 s84, s84, s6
	s_addc_u32 s85, s85, s7
	s_add_u32 s92, s84, 0x40000
	s_addc_u32 s93, s85, 0
	s_add_u32 s86, s50, 0x1a00000
	s_addc_u32 s87, s51, 0
	s_add_u32 s86, s86, s4
	s_addc_u32 s87, s87, s5
	v_readfirstlane_b32 s1, v129
	v_and_b32_e32 v200, 15, v131
	v_bfe_u32 v201, v131, 4, 2
	v_and_b32_e32 v202, 63, v131
	v_lshlrev_b32_e32 v202, 4, v202
	v_lshrrev_b32_e32 v203, 6, v131
	v_lshl_add_u32 v142, v203, 16, v202
	v_add_u32_e32 v150, 0x8000, v142
	v_bfe_u32 v202, v131, 1, 3
	v_xor_b32_e32 v202, v201, v202
	v_lshlrev_b32_e32 v202, 4, v202
	v_lshl_or_b32 v212, v200, 7, v202
	v_xor_b32_e32 v213, 64, v212
	v_bfe_u32 v200, v131, 4, 3
	v_and_b32_e32 v201, 7, v131
	v_xor_b32_e32 v200, v200, v201
	v_lshlrev_b32_e32 v200, 4, v200
	v_lshrrev_b32_e32 v201, 3, v131
	v_lshl_or_b32 v151, v201, 11, v200
	v_add_u32_e32 v156, 65536, v151
	v_add_u32_e32 v158, 131072, v151
	v_add_u32_e32 v159, 196608, v151
	s_add_u32 m0, s1, 0
	v_mov_b32_e32 v0, 0
	v_mov_b32_e32 v1, 0
	global_load_lds_dwordx4 v151, s[86:87]
	v_mov_b32_e32 v2, 0
	v_mov_b32_e32 v3, 0
	v_mov_b32_e32 v4, 0
	s_add_u32 m0, s1, 4096
	v_mov_b32_e32 v5, 0
	v_mov_b32_e32 v6, 0
	global_load_lds_dwordx4 v156, s[86:87]
	v_mov_b32_e32 v7, 0
	v_mov_b32_e32 v8, 0
	v_mov_b32_e32 v9, 0
	s_add_u32 m0, s1, 8192
	v_mov_b32_e32 v10, 0
	v_mov_b32_e32 v11, 0
	global_load_lds_dwordx4 v158, s[86:87]
	v_mov_b32_e32 v12, 0
	v_mov_b32_e32 v13, 0
	v_mov_b32_e32 v14, 0
	s_add_u32 m0, s1, 12288
	v_mov_b32_e32 v15, 0
	v_mov_b32_e32 v16, 0
	global_load_lds_dwordx4 v159, s[86:87]
	s_add_u32 s86, s86, 128
	s_addc_u32 s87, s87, 0
	v_mov_b32_e32 v17, 0
	v_mov_b32_e32 v18, 0
	v_mov_b32_e32 v19, 0
	global_load_dwordx4 v[64:67], v142, s[84:85] offset:0
	v_mov_b32_e32 v20, 0
	v_mov_b32_e32 v21, 0
	v_mov_b32_e32 v22, 0
	global_load_dwordx4 v[68:71], v150, s[84:85] offset:0
	v_mov_b32_e32 v23, 0
	v_mov_b32_e32 v24, 0
	v_mov_b32_e32 v25, 0
	global_load_dwordx4 v[72:75], v142, s[92:93] offset:0
	v_mov_b32_e32 v26, 0
	v_mov_b32_e32 v27, 0
	v_mov_b32_e32 v28, 0
	global_load_dwordx4 v[76:79], v150, s[92:93] offset:0
	v_mov_b32_e32 v29, 0
	v_mov_b32_e32 v30, 0
	v_mov_b32_e32 v31, 0
	global_load_dwordx4 v[80:83], v142, s[84:85] offset:1024
	v_mov_b32_e32 v32, 0
	v_mov_b32_e32 v33, 0
	v_mov_b32_e32 v34, 0
	global_load_dwordx4 v[84:87], v150, s[84:85] offset:1024
	v_mov_b32_e32 v35, 0
	v_mov_b32_e32 v36, 0
	v_mov_b32_e32 v37, 0
	global_load_dwordx4 v[88:91], v142, s[92:93] offset:1024
	v_mov_b32_e32 v38, 0
	v_mov_b32_e32 v39, 0
	v_mov_b32_e32 v40, 0
	global_load_dwordx4 v[92:95], v150, s[92:93] offset:1024
	s_add_u32 s84, s84, 0x800
	s_addc_u32 s85, s85, 0
	s_add_u32 s92, s92, 0x800
	s_addc_u32 s93, s93, 0
	v_mov_b32_e32 v41, 0
	v_mov_b32_e32 v42, 0
	v_mov_b32_e32 v43, 0
	s_add_u32 m0, s1, 16384
	v_mov_b32_e32 v44, 0
	v_mov_b32_e32 v45, 0
	global_load_lds_dwordx4 v151, s[86:87]
	v_mov_b32_e32 v46, 0
	v_mov_b32_e32 v47, 0
	v_mov_b32_e32 v48, 0
	s_add_u32 m0, s1, 20480
	v_mov_b32_e32 v49, 0
	v_mov_b32_e32 v50, 0
	global_load_lds_dwordx4 v156, s[86:87]
	v_mov_b32_e32 v51, 0
	v_mov_b32_e32 v52, 0
	v_mov_b32_e32 v53, 0
	s_add_u32 m0, s1, 24576
	v_mov_b32_e32 v54, 0
	v_mov_b32_e32 v55, 0
	global_load_lds_dwordx4 v158, s[86:87]
	v_mov_b32_e32 v56, 0
	v_mov_b32_e32 v57, 0
	v_mov_b32_e32 v58, 0
	s_add_u32 m0, s1, 28672
	v_mov_b32_e32 v59, 0
	v_mov_b32_e32 v60, 0
	global_load_lds_dwordx4 v159, s[86:87]
	s_add_u32 s86, s86, 128
	s_addc_u32 s87, s87, 0
	v_mov_b32_e32 v61, 0
	v_mov_b32_e32 v62, 0
	v_mov_b32_e32 v63, 0
	s_add_u32 m0, s1, 32768
	v_mov_b32_e32 v144, 0
	v_mov_b32_e32 v145, 0
	global_load_lds_dwordx4 v151, s[86:87]
	v_mov_b32_e32 v146, 0
	v_mov_b32_e32 v147, 0
	v_mov_b32_e32 v184, 0
	s_add_u32 m0, s1, 36864
	v_mov_b32_e32 v185, 0
	v_mov_b32_e32 v186, 0
	global_load_lds_dwordx4 v156, s[86:87]
	v_mov_b32_e32 v187, 0
	v_mov_b32_e32 v204, 0
	v_mov_b32_e32 v205, 0
	s_add_u32 m0, s1, 40960
	v_mov_b32_e32 v206, 0
	v_mov_b32_e32 v207, 0
	global_load_lds_dwordx4 v158, s[86:87]
	v_mov_b32_e32 v208, 0
	v_mov_b32_e32 v209, 0
	v_mov_b32_e32 v210, 0
	s_add_u32 m0, s1, 45056
	v_mov_b32_e32 v211, 0
	v_mov_b32_e32 v232, 0
	global_load_lds_dwordx4 v159, s[86:87]
	s_add_u32 s86, s86, 128
	s_addc_u32 s87, s87, 0
	v_mov_b32_e32 v233, 0
	v_mov_b32_e32 v234, 0
	v_mov_b32_e32 v235, 0
	v_mov_b32_e32 v236, 0
	v_mov_b32_e32 v237, 0
	v_mov_b32_e32 v238, 0
	v_mov_b32_e32 v239, 0
	v_mov_b32_e32 v240, 0
	v_mov_b32_e32 v241, 0
	v_mov_b32_e32 v242, 0
	v_mov_b32_e32 v243, 0
	v_mov_b32_e32 v248, 0
	v_mov_b32_e32 v249, 0
	v_mov_b32_e32 v250, 0
	v_mov_b32_e32 v251, 0
	v_mov_b32_e32 v252, 0
	v_mov_b32_e32 v253, 0
	v_mov_b32_e32 v254, 0
	v_mov_b32_e32 v255, 0
	v_mov_b32_e32 v100, 0
	v_mov_b32_e32 v101, 0
	v_mov_b32_e32 v102, 0
	v_mov_b32_e32 v103, 0
	v_mov_b32_e32 v104, 0
	v_mov_b32_e32 v105, 0
	v_mov_b32_e32 v106, 0
	v_mov_b32_e32 v107, 0
	v_mov_b32_e32 v108, 0
	v_mov_b32_e32 v109, 0
	v_mov_b32_e32 v110, 0
	v_mov_b32_e32 v111, 0
	v_mov_b32_e32 v112, 0
	v_mov_b32_e32 v113, 0
	v_mov_b32_e32 v114, 0
	v_mov_b32_e32 v115, 0
	v_mov_b32_e32 v116, 0
	v_mov_b32_e32 v117, 0
	v_mov_b32_e32 v118, 0
	v_mov_b32_e32 v119, 0
	v_mov_b32_e32 v120, 0
	v_mov_b32_e32 v121, 0
	v_mov_b32_e32 v122, 0
	v_mov_b32_e32 v123, 0
	v_mov_b32_e32 v124, 0
	v_mov_b32_e32 v125, 0
	v_mov_b32_e32 v126, 0
	v_mov_b32_e32 v127, 0
	s_waitcnt vmcnt(12)
	s_barrier
	ds_read_b128 v[160:163], v212 offset:0
	ds_read_b128 v[176:179], v212 offset:2048
	ds_read_b128 v[180:183], v212 offset:4096
	ds_read_b128 v[188:191], v212 offset:6144
	ds_read_b128 v[192:195], v212 offset:8192
	global_load_dwordx4 v[96:99], v142, s[84:85] offset:0
	s_waitcnt lgkmcnt(4)
	v_mfma_f32_16x16x32_bf16 v[0:3], v[64:67], v[160:163], v[0:3]
	v_mfma_f32_16x16x32_bf16 v[32:35], v[68:71], v[160:163], v[32:35]
	v_mfma_f32_16x16x32_bf16 v[144:147], v[72:75], v[160:163], v[144:147]
	v_mfma_f32_16x16x32_bf16 v[252:255], v[76:79], v[160:163], v[252:255]
	ds_read_b128 v[196:199], v212 offset:10240
	global_load_dwordx4 v[164:167], v150, s[84:85] offset:0
	s_waitcnt lgkmcnt(4)
	v_mfma_f32_16x16x32_bf16 v[4:7], v[64:67], v[176:179], v[4:7]
	v_mfma_f32_16x16x32_bf16 v[36:39], v[68:71], v[176:179], v[36:39]
	v_mfma_f32_16x16x32_bf16 v[184:187], v[72:75], v[176:179], v[184:187]
	v_mfma_f32_16x16x32_bf16 v[100:103], v[76:79], v[176:179], v[100:103]
	ds_read_b128 v[160:163], v212 offset:12288
	global_load_dwordx4 v[168:171], v142, s[92:93] offset:0
	s_waitcnt lgkmcnt(4)
	v_mfma_f32_16x16x32_bf16 v[8:11], v[64:67], v[180:183], v[8:11]
	v_mfma_f32_16x16x32_bf16 v[40:43], v[68:71], v[180:183], v[40:43]
	v_mfma_f32_16x16x32_bf16 v[204:207], v[72:75], v[180:183], v[204:207]
	v_mfma_f32_16x16x32_bf16 v[104:107], v[76:79], v[180:183], v[104:107]
	ds_read_b128 v[176:179], v212 offset:14336
	global_load_dwordx4 v[172:175], v150, s[92:93] offset:0
	s_waitcnt lgkmcnt(4)
	v_mfma_f32_16x16x32_bf16 v[12:15], v[64:67], v[188:191], v[12:15]
	v_mfma_f32_16x16x32_bf16 v[44:47], v[68:71], v[188:191], v[44:47]
	v_mfma_f32_16x16x32_bf16 v[208:211], v[72:75], v[188:191], v[208:211]
	v_mfma_f32_16x16x32_bf16 v[108:111], v[76:79], v[188:191], v[108:111]
	ds_read_b128 v[180:183], v213 offset:0
	s_waitcnt lgkmcnt(4)
	v_mfma_f32_16x16x32_bf16 v[16:19], v[64:67], v[192:195], v[16:19]
	v_mfma_f32_16x16x32_bf16 v[48:51], v[68:71], v[192:195], v[48:51]
	v_mfma_f32_16x16x32_bf16 v[232:235], v[72:75], v[192:195], v[232:235]
	v_mfma_f32_16x16x32_bf16 v[112:115], v[76:79], v[192:195], v[112:115]
	ds_read_b128 v[188:191], v213 offset:2048
	s_waitcnt lgkmcnt(4)
	v_mfma_f32_16x16x32_bf16 v[20:23], v[64:67], v[196:199], v[20:23]
	v_mfma_f32_16x16x32_bf16 v[52:55], v[68:71], v[196:199], v[52:55]
	v_mfma_f32_16x16x32_bf16 v[236:239], v[72:75], v[196:199], v[236:239]
	v_mfma_f32_16x16x32_bf16 v[116:119], v[76:79], v[196:199], v[116:119]
	ds_read_b128 v[192:195], v213 offset:4096
	s_waitcnt lgkmcnt(4)
	v_mfma_f32_16x16x32_bf16 v[24:27], v[64:67], v[160:163], v[24:27]
	v_mfma_f32_16x16x32_bf16 v[56:59], v[68:71], v[160:163], v[56:59]
	v_mfma_f32_16x16x32_bf16 v[240:243], v[72:75], v[160:163], v[240:243]
	v_mfma_f32_16x16x32_bf16 v[120:123], v[76:79], v[160:163], v[120:123]
	ds_read_b128 v[196:199], v213 offset:6144
	s_waitcnt lgkmcnt(4)
	v_mfma_f32_16x16x32_bf16 v[28:31], v[64:67], v[176:179], v[28:31]
	v_mfma_f32_16x16x32_bf16 v[60:63], v[68:71], v[176:179], v[60:63]
	v_mfma_f32_16x16x32_bf16 v[248:251], v[72:75], v[176:179], v[248:251]
	v_mfma_f32_16x16x32_bf16 v[124:127], v[76:79], v[176:179], v[124:127]
	s_waitcnt vmcnt(8)
	s_barrier
	s_waitcnt vmcnt(12)
	ds_read_b128 v[160:163], v213 offset:8192
	global_load_dwordx4 v[64:67], v142, s[84:85] offset:1024
	s_waitcnt lgkmcnt(4)
	v_mfma_f32_16x16x32_bf16 v[0:3], v[80:83], v[180:183], v[0:3]
	v_mfma_f32_16x16x32_bf16 v[32:35], v[84:87], v[180:183], v[32:35]
	v_mfma_f32_16x16x32_bf16 v[144:147], v[88:91], v[180:183], v[144:147]
	v_mfma_f32_16x16x32_bf16 v[252:255], v[92:95], v[180:183], v[252:255]
	ds_read_b128 v[176:179], v213 offset:10240
	global_load_dwordx4 v[68:71], v150, s[84:85] offset:1024
	s_waitcnt lgkmcnt(4)
	v_mfma_f32_16x16x32_bf16 v[4:7], v[80:83], v[188:191], v[4:7]
	v_mfma_f32_16x16x32_bf16 v[36:39], v[84:87], v[188:191], v[36:39]
	v_mfma_f32_16x16x32_bf16 v[184:187], v[88:91], v[188:191], v[184:187]
	v_mfma_f32_16x16x32_bf16 v[100:103], v[92:95], v[188:191], v[100:103]
	ds_read_b128 v[180:183], v213 offset:12288
	global_load_dwordx4 v[72:75], v142, s[92:93] offset:1024
	s_waitcnt lgkmcnt(4)
	v_mfma_f32_16x16x32_bf16 v[8:11], v[80:83], v[192:195], v[8:11]
	v_mfma_f32_16x16x32_bf16 v[40:43], v[84:87], v[192:195], v[40:43]
	v_mfma_f32_16x16x32_bf16 v[204:207], v[88:91], v[192:195], v[204:207]
	v_mfma_f32_16x16x32_bf16 v[104:107], v[92:95], v[192:195], v[104:107]
	ds_read_b128 v[188:191], v213 offset:14336
	global_load_dwordx4 v[76:79], v150, s[92:93] offset:1024
	s_add_u32 s84, s84, 0x800
	s_addc_u32 s85, s85, 0
	s_add_u32 s92, s92, 0x800
	s_addc_u32 s93, s93, 0
	s_waitcnt lgkmcnt(4)
	v_mfma_f32_16x16x32_bf16 v[12:15], v[80:83], v[196:199], v[12:15]
	v_mfma_f32_16x16x32_bf16 v[44:47], v[84:87], v[196:199], v[44:47]
	v_mfma_f32_16x16x32_bf16 v[208:211], v[88:91], v[196:199], v[208:211]
	v_mfma_f32_16x16x32_bf16 v[108:111], v[92:95], v[196:199], v[108:111]
	ds_read_b128 v[192:195], v212 offset:16384
	s_add_u32 m0, s1, 49152
	s_nop 0
	global_load_lds_dwordx4 v151, s[86:87]
	s_waitcnt lgkmcnt(4)
	v_mfma_f32_16x16x32_bf16 v[16:19], v[80:83], v[160:163], v[16:19]
	v_mfma_f32_16x16x32_bf16 v[48:51], v[84:87], v[160:163], v[48:51]
	v_mfma_f32_16x16x32_bf16 v[232:235], v[88:91], v[160:163], v[232:235]
	v_mfma_f32_16x16x32_bf16 v[112:115], v[92:95], v[160:163], v[112:115]
	ds_read_b128 v[196:199], v212 offset:18432
	s_add_u32 m0, s1, 53248
	s_nop 0
	global_load_lds_dwordx4 v156, s[86:87]
	s_waitcnt lgkmcnt(4)
	v_mfma_f32_16x16x32_bf16 v[20:23], v[80:83], v[176:179], v[20:23]
	v_mfma_f32_16x16x32_bf16 v[52:55], v[84:87], v[176:179], v[52:55]
	v_mfma_f32_16x16x32_bf16 v[236:239], v[88:91], v[176:179], v[236:239]
	v_mfma_f32_16x16x32_bf16 v[116:119], v[92:95], v[176:179], v[116:119]
	ds_read_b128 v[160:163], v212 offset:20480
	s_add_u32 m0, s1, 57344
	s_nop 0
	global_load_lds_dwordx4 v158, s[86:87]
	s_waitcnt lgkmcnt(4)
	v_mfma_f32_16x16x32_bf16 v[24:27], v[80:83], v[180:183], v[24:27]
	v_mfma_f32_16x16x32_bf16 v[56:59], v[84:87], v[180:183], v[56:59]
	v_mfma_f32_16x16x32_bf16 v[240:243], v[88:91], v[180:183], v[240:243]
	v_mfma_f32_16x16x32_bf16 v[120:123], v[92:95], v[180:183], v[120:123]
	ds_read_b128 v[176:179], v212 offset:22528
	s_add_u32 m0, s1, 61440
	s_nop 0
	global_load_lds_dwordx4 v159, s[86:87]
	s_add_u32 s86, s86, 128
	s_addc_u32 s87, s87, 0
	s_waitcnt lgkmcnt(4)
	v_mfma_f32_16x16x32_bf16 v[28:31], v[80:83], v[188:191], v[28:31]
	v_mfma_f32_16x16x32_bf16 v[60:63], v[84:87], v[188:191], v[60:63]
	v_mfma_f32_16x16x32_bf16 v[248:251], v[88:91], v[188:191], v[248:251]
	v_mfma_f32_16x16x32_bf16 v[124:127], v[92:95], v[188:191], v[124:127]
	s_waitcnt vmcnt(8)
	ds_read_b128 v[180:183], v212 offset:24576
	global_load_dwordx4 v[80:83], v142, s[84:85] offset:0
	s_waitcnt lgkmcnt(4)
	v_mfma_f32_16x16x32_bf16 v[0:3], v[96:99], v[192:195], v[0:3]
	v_mfma_f32_16x16x32_bf16 v[32:35], v[164:167], v[192:195], v[32:35]
	v_mfma_f32_16x16x32_bf16 v[144:147], v[168:171], v[192:195], v[144:147]
	v_mfma_f32_16x16x32_bf16 v[252:255], v[172:175], v[192:195], v[252:255]
	ds_read_b128 v[188:191], v212 offset:26624
	global_load_dwordx4 v[84:87], v150, s[84:85] offset:0
	s_waitcnt lgkmcnt(4)
	v_mfma_f32_16x16x32_bf16 v[4:7], v[96:99], v[196:199], v[4:7]
	v_mfma_f32_16x16x32_bf16 v[36:39], v[164:167], v[196:199], v[36:39]
	v_mfma_f32_16x16x32_bf16 v[184:187], v[168:171], v[196:199], v[184:187]
	v_mfma_f32_16x16x32_bf16 v[100:103], v[172:175], v[196:199], v[100:103]
	ds_read_b128 v[192:195], v212 offset:28672
	global_load_dwordx4 v[88:91], v142, s[92:93] offset:0
	s_waitcnt lgkmcnt(4)
	v_mfma_f32_16x16x32_bf16 v[8:11], v[96:99], v[160:163], v[8:11]
	v_mfma_f32_16x16x32_bf16 v[40:43], v[164:167], v[160:163], v[40:43]
	v_mfma_f32_16x16x32_bf16 v[204:207], v[168:171], v[160:163], v[204:207]
	v_mfma_f32_16x16x32_bf16 v[104:107], v[172:175], v[160:163], v[104:107]
	ds_read_b128 v[196:199], v212 offset:30720
	global_load_dwordx4 v[92:95], v150, s[92:93] offset:0
	s_waitcnt lgkmcnt(4)
	v_mfma_f32_16x16x32_bf16 v[12:15], v[96:99], v[176:179], v[12:15]
	v_mfma_f32_16x16x32_bf16 v[44:47], v[164:167], v[176:179], v[44:47]
	v_mfma_f32_16x16x32_bf16 v[208:211], v[168:171], v[176:179], v[208:211]
	v_mfma_f32_16x16x32_bf16 v[108:111], v[172:175], v[176:179], v[108:111]
	ds_read_b128 v[160:163], v213 offset:16384
	s_waitcnt lgkmcnt(4)
	v_mfma_f32_16x16x32_bf16 v[16:19], v[96:99], v[180:183], v[16:19]
	v_mfma_f32_16x16x32_bf16 v[48:51], v[164:167], v[180:183], v[48:51]
	v_mfma_f32_16x16x32_bf16 v[232:235], v[168:171], v[180:183], v[232:235]
	v_mfma_f32_16x16x32_bf16 v[112:115], v[172:175], v[180:183], v[112:115]
	ds_read_b128 v[176:179], v213 offset:18432
	s_waitcnt lgkmcnt(4)
	v_mfma_f32_16x16x32_bf16 v[20:23], v[96:99], v[188:191], v[20:23]
	v_mfma_f32_16x16x32_bf16 v[52:55], v[164:167], v[188:191], v[52:55]
	v_mfma_f32_16x16x32_bf16 v[236:239], v[168:171], v[188:191], v[236:239]
	v_mfma_f32_16x16x32_bf16 v[116:119], v[172:175], v[188:191], v[116:119]
	ds_read_b128 v[180:183], v213 offset:20480
	s_waitcnt lgkmcnt(4)
	v_mfma_f32_16x16x32_bf16 v[24:27], v[96:99], v[192:195], v[24:27]
	v_mfma_f32_16x16x32_bf16 v[56:59], v[164:167], v[192:195], v[56:59]
	v_mfma_f32_16x16x32_bf16 v[240:243], v[168:171], v[192:195], v[240:243]
	v_mfma_f32_16x16x32_bf16 v[120:123], v[172:175], v[192:195], v[120:123]
	ds_read_b128 v[188:191], v213 offset:22528
	s_waitcnt lgkmcnt(4)
	v_mfma_f32_16x16x32_bf16 v[28:31], v[96:99], v[196:199], v[28:31]
	v_mfma_f32_16x16x32_bf16 v[60:63], v[164:167], v[196:199], v[60:63]
	v_mfma_f32_16x16x32_bf16 v[248:251], v[168:171], v[196:199], v[248:251]
	v_mfma_f32_16x16x32_bf16 v[124:127], v[172:175], v[196:199], v[124:127]
	s_waitcnt vmcnt(16)
	s_barrier
	s_waitcnt vmcnt(8)
	ds_read_b128 v[192:195], v213 offset:24576
	global_load_dwordx4 v[96:99], v142, s[84:85] offset:1024
	s_waitcnt lgkmcnt(4)
	v_mfma_f32_16x16x32_bf16 v[0:3], v[64:67], v[160:163], v[0:3]
	v_mfma_f32_16x16x32_bf16 v[32:35], v[68:71], v[160:163], v[32:35]
	v_mfma_f32_16x16x32_bf16 v[144:147], v[72:75], v[160:163], v[144:147]
	v_mfma_f32_16x16x32_bf16 v[252:255], v[76:79], v[160:163], v[252:255]
	ds_read_b128 v[196:199], v213 offset:26624
	global_load_dwordx4 v[164:167], v150, s[84:85] offset:1024
	s_waitcnt lgkmcnt(4)
	v_mfma_f32_16x16x32_bf16 v[4:7], v[64:67], v[176:179], v[4:7]
	v_mfma_f32_16x16x32_bf16 v[36:39], v[68:71], v[176:179], v[36:39]
	v_mfma_f32_16x16x32_bf16 v[184:187], v[72:75], v[176:179], v[184:187]
	v_mfma_f32_16x16x32_bf16 v[100:103], v[76:79], v[176:179], v[100:103]
	ds_read_b128 v[160:163], v213 offset:28672
	global_load_dwordx4 v[168:171], v142, s[92:93] offset:1024
	s_waitcnt lgkmcnt(4)
	v_mfma_f32_16x16x32_bf16 v[8:11], v[64:67], v[180:183], v[8:11]
	v_mfma_f32_16x16x32_bf16 v[40:43], v[68:71], v[180:183], v[40:43]
	v_mfma_f32_16x16x32_bf16 v[204:207], v[72:75], v[180:183], v[204:207]
	v_mfma_f32_16x16x32_bf16 v[104:107], v[76:79], v[180:183], v[104:107]
	ds_read_b128 v[176:179], v213 offset:30720
	global_load_dwordx4 v[172:175], v150, s[92:93] offset:1024
	s_add_u32 s84, s84, 0x800
	s_addc_u32 s85, s85, 0
	s_add_u32 s92, s92, 0x800
	s_addc_u32 s93, s93, 0
	s_waitcnt lgkmcnt(4)
	v_mfma_f32_16x16x32_bf16 v[12:15], v[64:67], v[188:191], v[12:15]
	v_mfma_f32_16x16x32_bf16 v[44:47], v[68:71], v[188:191], v[44:47]
	v_mfma_f32_16x16x32_bf16 v[208:211], v[72:75], v[188:191], v[208:211]
	v_mfma_f32_16x16x32_bf16 v[108:111], v[76:79], v[188:191], v[108:111]
	ds_read_b128 v[180:183], v212 offset:32768
	s_add_u32 m0, s1, 0
	s_nop 0
	global_load_lds_dwordx4 v151, s[86:87]
	s_waitcnt lgkmcnt(4)
	v_mfma_f32_16x16x32_bf16 v[16:19], v[64:67], v[192:195], v[16:19]
	v_mfma_f32_16x16x32_bf16 v[48:51], v[68:71], v[192:195], v[48:51]
	v_mfma_f32_16x16x32_bf16 v[232:235], v[72:75], v[192:195], v[232:235]
	v_mfma_f32_16x16x32_bf16 v[112:115], v[76:79], v[192:195], v[112:115]
	ds_read_b128 v[188:191], v212 offset:34816
	s_add_u32 m0, s1, 4096
	s_nop 0
	global_load_lds_dwordx4 v156, s[86:87]
	s_waitcnt lgkmcnt(4)
	v_mfma_f32_16x16x32_bf16 v[20:23], v[64:67], v[196:199], v[20:23]
	v_mfma_f32_16x16x32_bf16 v[52:55], v[68:71], v[196:199], v[52:55]
	v_mfma_f32_16x16x32_bf16 v[236:239], v[72:75], v[196:199], v[236:239]
	v_mfma_f32_16x16x32_bf16 v[116:119], v[76:79], v[196:199], v[116:119]
	ds_read_b128 v[192:195], v212 offset:36864
	s_add_u32 m0, s1, 8192
	s_nop 0
	global_load_lds_dwordx4 v158, s[86:87]
	s_waitcnt lgkmcnt(4)
	v_mfma_f32_16x16x32_bf16 v[24:27], v[64:67], v[160:163], v[24:27]
	v_mfma_f32_16x16x32_bf16 v[56:59], v[68:71], v[160:163], v[56:59]
	v_mfma_f32_16x16x32_bf16 v[240:243], v[72:75], v[160:163], v[240:243]
	v_mfma_f32_16x16x32_bf16 v[120:123], v[76:79], v[160:163], v[120:123]
	ds_read_b128 v[196:199], v212 offset:38912
	s_add_u32 m0, s1, 12288
	s_nop 0
	global_load_lds_dwordx4 v159, s[86:87]
	s_add_u32 s86, s86, 128
	s_addc_u32 s87, s87, 0
	s_waitcnt lgkmcnt(4)
	v_mfma_f32_16x16x32_bf16 v[28:31], v[64:67], v[176:179], v[28:31]
	v_mfma_f32_16x16x32_bf16 v[60:63], v[68:71], v[176:179], v[60:63]
	v_mfma_f32_16x16x32_bf16 v[248:251], v[72:75], v[176:179], v[248:251]
	v_mfma_f32_16x16x32_bf16 v[124:127], v[76:79], v[176:179], v[124:127]
	s_waitcnt vmcnt(8)
	ds_read_b128 v[160:163], v212 offset:40960
	global_load_dwordx4 v[64:67], v142, s[84:85] offset:0
	s_waitcnt lgkmcnt(4)
	v_mfma_f32_16x16x32_bf16 v[0:3], v[80:83], v[180:183], v[0:3]
	v_mfma_f32_16x16x32_bf16 v[32:35], v[84:87], v[180:183], v[32:35]
	v_mfma_f32_16x16x32_bf16 v[144:147], v[88:91], v[180:183], v[144:147]
	v_mfma_f32_16x16x32_bf16 v[252:255], v[92:95], v[180:183], v[252:255]
	ds_read_b128 v[176:179], v212 offset:43008
	global_load_dwordx4 v[68:71], v150, s[84:85] offset:0
	s_waitcnt lgkmcnt(4)
	v_mfma_f32_16x16x32_bf16 v[4:7], v[80:83], v[188:191], v[4:7]
	v_mfma_f32_16x16x32_bf16 v[36:39], v[84:87], v[188:191], v[36:39]
	v_mfma_f32_16x16x32_bf16 v[184:187], v[88:91], v[188:191], v[184:187]
	v_mfma_f32_16x16x32_bf16 v[100:103], v[92:95], v[188:191], v[100:103]
	ds_read_b128 v[180:183], v212 offset:45056
	global_load_dwordx4 v[72:75], v142, s[92:93] offset:0
	s_waitcnt lgkmcnt(4)
	v_mfma_f32_16x16x32_bf16 v[8:11], v[80:83], v[192:195], v[8:11]
	v_mfma_f32_16x16x32_bf16 v[40:43], v[84:87], v[192:195], v[40:43]
	v_mfma_f32_16x16x32_bf16 v[204:207], v[88:91], v[192:195], v[204:207]
	v_mfma_f32_16x16x32_bf16 v[104:107], v[92:95], v[192:195], v[104:107]
	ds_read_b128 v[188:191], v212 offset:47104
	global_load_dwordx4 v[76:79], v150, s[92:93] offset:0
	s_waitcnt lgkmcnt(4)
	v_mfma_f32_16x16x32_bf16 v[12:15], v[80:83], v[196:199], v[12:15]
	v_mfma_f32_16x16x32_bf16 v[44:47], v[84:87], v[196:199], v[44:47]
	v_mfma_f32_16x16x32_bf16 v[208:211], v[88:91], v[196:199], v[208:211]
	v_mfma_f32_16x16x32_bf16 v[108:111], v[92:95], v[196:199], v[108:111]
	ds_read_b128 v[192:195], v213 offset:32768
	s_waitcnt lgkmcnt(4)
	v_mfma_f32_16x16x32_bf16 v[16:19], v[80:83], v[160:163], v[16:19]
	v_mfma_f32_16x16x32_bf16 v[48:51], v[84:87], v[160:163], v[48:51]
	v_mfma_f32_16x16x32_bf16 v[232:235], v[88:91], v[160:163], v[232:235]
	v_mfma_f32_16x16x32_bf16 v[112:115], v[92:95], v[160:163], v[112:115]
	ds_read_b128 v[196:199], v213 offset:34816
	s_waitcnt lgkmcnt(4)
	v_mfma_f32_16x16x32_bf16 v[20:23], v[80:83], v[176:179], v[20:23]
	v_mfma_f32_16x16x32_bf16 v[52:55], v[84:87], v[176:179], v[52:55]
	v_mfma_f32_16x16x32_bf16 v[236:239], v[88:91], v[176:179], v[236:239]
	v_mfma_f32_16x16x32_bf16 v[116:119], v[92:95], v[176:179], v[116:119]
	ds_read_b128 v[160:163], v213 offset:36864
	s_waitcnt lgkmcnt(4)
	v_mfma_f32_16x16x32_bf16 v[24:27], v[80:83], v[180:183], v[24:27]
	v_mfma_f32_16x16x32_bf16 v[56:59], v[84:87], v[180:183], v[56:59]
	v_mfma_f32_16x16x32_bf16 v[240:243], v[88:91], v[180:183], v[240:243]
	v_mfma_f32_16x16x32_bf16 v[120:123], v[92:95], v[180:183], v[120:123]
	ds_read_b128 v[176:179], v213 offset:38912
	s_waitcnt lgkmcnt(4)
	v_mfma_f32_16x16x32_bf16 v[28:31], v[80:83], v[188:191], v[28:31]
	v_mfma_f32_16x16x32_bf16 v[60:63], v[84:87], v[188:191], v[60:63]
	v_mfma_f32_16x16x32_bf16 v[248:251], v[88:91], v[188:191], v[248:251]
	v_mfma_f32_16x16x32_bf16 v[124:127], v[92:95], v[188:191], v[124:127]
	s_waitcnt vmcnt(16)
	s_barrier
	s_waitcnt vmcnt(8)
	ds_read_b128 v[180:183], v213 offset:40960
	global_load_dwordx4 v[80:83], v142, s[84:85] offset:1024
	s_waitcnt lgkmcnt(4)
	v_mfma_f32_16x16x32_bf16 v[0:3], v[96:99], v[192:195], v[0:3]
	v_mfma_f32_16x16x32_bf16 v[32:35], v[164:167], v[192:195], v[32:35]
	v_mfma_f32_16x16x32_bf16 v[144:147], v[168:171], v[192:195], v[144:147]
	v_mfma_f32_16x16x32_bf16 v[252:255], v[172:175], v[192:195], v[252:255]
	ds_read_b128 v[188:191], v213 offset:43008
	global_load_dwordx4 v[84:87], v150, s[84:85] offset:1024
	s_waitcnt lgkmcnt(4)
	v_mfma_f32_16x16x32_bf16 v[4:7], v[96:99], v[196:199], v[4:7]
	v_mfma_f32_16x16x32_bf16 v[36:39], v[164:167], v[196:199], v[36:39]
	v_mfma_f32_16x16x32_bf16 v[184:187], v[168:171], v[196:199], v[184:187]
	v_mfma_f32_16x16x32_bf16 v[100:103], v[172:175], v[196:199], v[100:103]
	ds_read_b128 v[192:195], v213 offset:45056
	global_load_dwordx4 v[88:91], v142, s[92:93] offset:1024
	s_waitcnt lgkmcnt(4)
	v_mfma_f32_16x16x32_bf16 v[8:11], v[96:99], v[160:163], v[8:11]
	v_mfma_f32_16x16x32_bf16 v[40:43], v[164:167], v[160:163], v[40:43]
	v_mfma_f32_16x16x32_bf16 v[204:207], v[168:171], v[160:163], v[204:207]
	v_mfma_f32_16x16x32_bf16 v[104:107], v[172:175], v[160:163], v[104:107]
	ds_read_b128 v[196:199], v213 offset:47104
	global_load_dwordx4 v[92:95], v150, s[92:93] offset:1024
	s_add_u32 s84, s84, 0x800
	s_addc_u32 s85, s85, 0
	s_add_u32 s92, s92, 0x800
	s_addc_u32 s93, s93, 0
	s_waitcnt lgkmcnt(4)
	v_mfma_f32_16x16x32_bf16 v[12:15], v[96:99], v[176:179], v[12:15]
	v_mfma_f32_16x16x32_bf16 v[44:47], v[164:167], v[176:179], v[44:47]
	v_mfma_f32_16x16x32_bf16 v[208:211], v[168:171], v[176:179], v[208:211]
	v_mfma_f32_16x16x32_bf16 v[108:111], v[172:175], v[176:179], v[108:111]
	ds_read_b128 v[160:163], v212 offset:49152
	s_add_u32 m0, s1, 16384
	s_nop 0
	global_load_lds_dwordx4 v151, s[86:87]
	s_waitcnt lgkmcnt(4)
	v_mfma_f32_16x16x32_bf16 v[16:19], v[96:99], v[180:183], v[16:19]
	v_mfma_f32_16x16x32_bf16 v[48:51], v[164:167], v[180:183], v[48:51]
	v_mfma_f32_16x16x32_bf16 v[232:235], v[168:171], v[180:183], v[232:235]
	v_mfma_f32_16x16x32_bf16 v[112:115], v[172:175], v[180:183], v[112:115]
	ds_read_b128 v[176:179], v212 offset:51200
	s_add_u32 m0, s1, 20480
	s_nop 0
	global_load_lds_dwordx4 v156, s[86:87]
	s_waitcnt lgkmcnt(4)
	v_mfma_f32_16x16x32_bf16 v[20:23], v[96:99], v[188:191], v[20:23]
	v_mfma_f32_16x16x32_bf16 v[52:55], v[164:167], v[188:191], v[52:55]
	v_mfma_f32_16x16x32_bf16 v[236:239], v[168:171], v[188:191], v[236:239]
	v_mfma_f32_16x16x32_bf16 v[116:119], v[172:175], v[188:191], v[116:119]
	ds_read_b128 v[180:183], v212 offset:53248
	s_add_u32 m0, s1, 24576
	s_nop 0
	global_load_lds_dwordx4 v158, s[86:87]
	s_waitcnt lgkmcnt(4)
	v_mfma_f32_16x16x32_bf16 v[24:27], v[96:99], v[192:195], v[24:27]
	v_mfma_f32_16x16x32_bf16 v[56:59], v[164:167], v[192:195], v[56:59]
	v_mfma_f32_16x16x32_bf16 v[240:243], v[168:171], v[192:195], v[240:243]
	v_mfma_f32_16x16x32_bf16 v[120:123], v[172:175], v[192:195], v[120:123]
	ds_read_b128 v[188:191], v212 offset:55296
	s_add_u32 m0, s1, 28672
	s_nop 0
	global_load_lds_dwordx4 v159, s[86:87]
	s_add_u32 s86, s86, 128
	s_addc_u32 s87, s87, 0
	s_waitcnt lgkmcnt(4)
	v_mfma_f32_16x16x32_bf16 v[28:31], v[96:99], v[196:199], v[28:31]
	v_mfma_f32_16x16x32_bf16 v[60:63], v[164:167], v[196:199], v[60:63]
	v_mfma_f32_16x16x32_bf16 v[248:251], v[168:171], v[196:199], v[248:251]
	v_mfma_f32_16x16x32_bf16 v[124:127], v[172:175], v[196:199], v[124:127]
	s_waitcnt vmcnt(8)
	ds_read_b128 v[192:195], v212 offset:57344
	global_load_dwordx4 v[96:99], v142, s[84:85] offset:0
	s_waitcnt lgkmcnt(4)
	v_mfma_f32_16x16x32_bf16 v[0:3], v[64:67], v[160:163], v[0:3]
	v_mfma_f32_16x16x32_bf16 v[32:35], v[68:71], v[160:163], v[32:35]
	v_mfma_f32_16x16x32_bf16 v[144:147], v[72:75], v[160:163], v[144:147]
	v_mfma_f32_16x16x32_bf16 v[252:255], v[76:79], v[160:163], v[252:255]
	ds_read_b128 v[196:199], v212 offset:59392
	global_load_dwordx4 v[164:167], v150, s[84:85] offset:0
	s_waitcnt lgkmcnt(4)
	v_mfma_f32_16x16x32_bf16 v[4:7], v[64:67], v[176:179], v[4:7]
	v_mfma_f32_16x16x32_bf16 v[36:39], v[68:71], v[176:179], v[36:39]
	v_mfma_f32_16x16x32_bf16 v[184:187], v[72:75], v[176:179], v[184:187]
	v_mfma_f32_16x16x32_bf16 v[100:103], v[76:79], v[176:179], v[100:103]
	ds_read_b128 v[160:163], v212 offset:61440
	global_load_dwordx4 v[168:171], v142, s[92:93] offset:0
	s_waitcnt lgkmcnt(4)
	v_mfma_f32_16x16x32_bf16 v[8:11], v[64:67], v[180:183], v[8:11]
	v_mfma_f32_16x16x32_bf16 v[40:43], v[68:71], v[180:183], v[40:43]
	v_mfma_f32_16x16x32_bf16 v[204:207], v[72:75], v[180:183], v[204:207]
	v_mfma_f32_16x16x32_bf16 v[104:107], v[76:79], v[180:183], v[104:107]
	ds_read_b128 v[176:179], v212 offset:63488
	global_load_dwordx4 v[172:175], v150, s[92:93] offset:0
	s_waitcnt lgkmcnt(4)
	v_mfma_f32_16x16x32_bf16 v[12:15], v[64:67], v[188:191], v[12:15]
	v_mfma_f32_16x16x32_bf16 v[44:47], v[68:71], v[188:191], v[44:47]
	v_mfma_f32_16x16x32_bf16 v[208:211], v[72:75], v[188:191], v[208:211]
	v_mfma_f32_16x16x32_bf16 v[108:111], v[76:79], v[188:191], v[108:111]
	ds_read_b128 v[180:183], v213 offset:49152
	s_waitcnt lgkmcnt(4)
	v_mfma_f32_16x16x32_bf16 v[16:19], v[64:67], v[192:195], v[16:19]
	v_mfma_f32_16x16x32_bf16 v[48:51], v[68:71], v[192:195], v[48:51]
	v_mfma_f32_16x16x32_bf16 v[232:235], v[72:75], v[192:195], v[232:235]
	v_mfma_f32_16x16x32_bf16 v[112:115], v[76:79], v[192:195], v[112:115]
	ds_read_b128 v[188:191], v213 offset:51200
	s_waitcnt lgkmcnt(4)
	v_mfma_f32_16x16x32_bf16 v[20:23], v[64:67], v[196:199], v[20:23]
	v_mfma_f32_16x16x32_bf16 v[52:55], v[68:71], v[196:199], v[52:55]
	v_mfma_f32_16x16x32_bf16 v[236:239], v[72:75], v[196:199], v[236:239]
	v_mfma_f32_16x16x32_bf16 v[116:119], v[76:79], v[196:199], v[116:119]
	ds_read_b128 v[192:195], v213 offset:53248
	s_waitcnt lgkmcnt(4)
	v_mfma_f32_16x16x32_bf16 v[24:27], v[64:67], v[160:163], v[24:27]
	v_mfma_f32_16x16x32_bf16 v[56:59], v[68:71], v[160:163], v[56:59]
	v_mfma_f32_16x16x32_bf16 v[240:243], v[72:75], v[160:163], v[240:243]
	v_mfma_f32_16x16x32_bf16 v[120:123], v[76:79], v[160:163], v[120:123]
	ds_read_b128 v[196:199], v213 offset:55296
	s_waitcnt lgkmcnt(4)
	v_mfma_f32_16x16x32_bf16 v[28:31], v[64:67], v[176:179], v[28:31]
	v_mfma_f32_16x16x32_bf16 v[60:63], v[68:71], v[176:179], v[60:63]
	v_mfma_f32_16x16x32_bf16 v[248:251], v[72:75], v[176:179], v[248:251]
	v_mfma_f32_16x16x32_bf16 v[124:127], v[76:79], v[176:179], v[124:127]
	s_waitcnt vmcnt(16)
	s_barrier
	s_waitcnt vmcnt(8)
	ds_read_b128 v[160:163], v213 offset:57344
	global_load_dwordx4 v[64:67], v142, s[84:85] offset:1024
	s_waitcnt lgkmcnt(4)
	v_mfma_f32_16x16x32_bf16 v[0:3], v[80:83], v[180:183], v[0:3]
	v_mfma_f32_16x16x32_bf16 v[32:35], v[84:87], v[180:183], v[32:35]
	v_mfma_f32_16x16x32_bf16 v[144:147], v[88:91], v[180:183], v[144:147]
	v_mfma_f32_16x16x32_bf16 v[252:255], v[92:95], v[180:183], v[252:255]
	ds_read_b128 v[176:179], v213 offset:59392
	global_load_dwordx4 v[68:71], v150, s[84:85] offset:1024
	s_waitcnt lgkmcnt(4)
	v_mfma_f32_16x16x32_bf16 v[4:7], v[80:83], v[188:191], v[4:7]
	v_mfma_f32_16x16x32_bf16 v[36:39], v[84:87], v[188:191], v[36:39]
	v_mfma_f32_16x16x32_bf16 v[184:187], v[88:91], v[188:191], v[184:187]
	v_mfma_f32_16x16x32_bf16 v[100:103], v[92:95], v[188:191], v[100:103]
	ds_read_b128 v[180:183], v213 offset:61440
	global_load_dwordx4 v[72:75], v142, s[92:93] offset:1024
	s_waitcnt lgkmcnt(4)
	v_mfma_f32_16x16x32_bf16 v[8:11], v[80:83], v[192:195], v[8:11]
	v_mfma_f32_16x16x32_bf16 v[40:43], v[84:87], v[192:195], v[40:43]
	v_mfma_f32_16x16x32_bf16 v[204:207], v[88:91], v[192:195], v[204:207]
	v_mfma_f32_16x16x32_bf16 v[104:107], v[92:95], v[192:195], v[104:107]
	ds_read_b128 v[188:191], v213 offset:63488
	global_load_dwordx4 v[76:79], v150, s[92:93] offset:1024
	s_add_u32 s84, s84, 0x800
	s_addc_u32 s85, s85, 0
	s_add_u32 s92, s92, 0x800
	s_addc_u32 s93, s93, 0
	s_waitcnt lgkmcnt(4)
	v_mfma_f32_16x16x32_bf16 v[12:15], v[80:83], v[196:199], v[12:15]
	v_mfma_f32_16x16x32_bf16 v[44:47], v[84:87], v[196:199], v[44:47]
	v_mfma_f32_16x16x32_bf16 v[208:211], v[88:91], v[196:199], v[208:211]
	v_mfma_f32_16x16x32_bf16 v[108:111], v[92:95], v[196:199], v[108:111]
	ds_read_b128 v[192:195], v212 offset:0
	s_add_u32 m0, s1, 32768
	s_nop 0
	global_load_lds_dwordx4 v151, s[86:87]
	s_waitcnt lgkmcnt(4)
	v_mfma_f32_16x16x32_bf16 v[16:19], v[80:83], v[160:163], v[16:19]
	v_mfma_f32_16x16x32_bf16 v[48:51], v[84:87], v[160:163], v[48:51]
	v_mfma_f32_16x16x32_bf16 v[232:235], v[88:91], v[160:163], v[232:235]
	v_mfma_f32_16x16x32_bf16 v[112:115], v[92:95], v[160:163], v[112:115]
	ds_read_b128 v[196:199], v212 offset:2048
	s_add_u32 m0, s1, 36864
	s_nop 0
	global_load_lds_dwordx4 v156, s[86:87]
	s_waitcnt lgkmcnt(4)
	v_mfma_f32_16x16x32_bf16 v[20:23], v[80:83], v[176:179], v[20:23]
	v_mfma_f32_16x16x32_bf16 v[52:55], v[84:87], v[176:179], v[52:55]
	v_mfma_f32_16x16x32_bf16 v[236:239], v[88:91], v[176:179], v[236:239]
	v_mfma_f32_16x16x32_bf16 v[116:119], v[92:95], v[176:179], v[116:119]
	ds_read_b128 v[160:163], v212 offset:4096
	s_add_u32 m0, s1, 40960
	s_nop 0
	global_load_lds_dwordx4 v158, s[86:87]
	s_waitcnt lgkmcnt(4)
	v_mfma_f32_16x16x32_bf16 v[24:27], v[80:83], v[180:183], v[24:27]
	v_mfma_f32_16x16x32_bf16 v[56:59], v[84:87], v[180:183], v[56:59]
	v_mfma_f32_16x16x32_bf16 v[240:243], v[88:91], v[180:183], v[240:243]
	v_mfma_f32_16x16x32_bf16 v[120:123], v[92:95], v[180:183], v[120:123]
	ds_read_b128 v[176:179], v212 offset:6144
	s_add_u32 m0, s1, 45056
	s_nop 0
	global_load_lds_dwordx4 v159, s[86:87]
	s_add_u32 s86, s86, 128
	s_addc_u32 s87, s87, 0
	s_waitcnt lgkmcnt(4)
	v_mfma_f32_16x16x32_bf16 v[28:31], v[80:83], v[188:191], v[28:31]
	v_mfma_f32_16x16x32_bf16 v[60:63], v[84:87], v[188:191], v[60:63]
	v_mfma_f32_16x16x32_bf16 v[248:251], v[88:91], v[188:191], v[248:251]
	v_mfma_f32_16x16x32_bf16 v[124:127], v[92:95], v[188:191], v[124:127]
	s_waitcnt vmcnt(8)
	ds_read_b128 v[180:183], v212 offset:8192
	global_load_dwordx4 v[80:83], v142, s[84:85] offset:0
	s_waitcnt lgkmcnt(4)
	v_mfma_f32_16x16x32_bf16 v[0:3], v[96:99], v[192:195], v[0:3]
	v_mfma_f32_16x16x32_bf16 v[32:35], v[164:167], v[192:195], v[32:35]
	v_mfma_f32_16x16x32_bf16 v[144:147], v[168:171], v[192:195], v[144:147]
	v_mfma_f32_16x16x32_bf16 v[252:255], v[172:175], v[192:195], v[252:255]
	ds_read_b128 v[188:191], v212 offset:10240
	global_load_dwordx4 v[84:87], v150, s[84:85] offset:0
	s_waitcnt lgkmcnt(4)
	v_mfma_f32_16x16x32_bf16 v[4:7], v[96:99], v[196:199], v[4:7]
	v_mfma_f32_16x16x32_bf16 v[36:39], v[164:167], v[196:199], v[36:39]
	v_mfma_f32_16x16x32_bf16 v[184:187], v[168:171], v[196:199], v[184:187]
	v_mfma_f32_16x16x32_bf16 v[100:103], v[172:175], v[196:199], v[100:103]
	ds_read_b128 v[192:195], v212 offset:12288
	global_load_dwordx4 v[88:91], v142, s[92:93] offset:0
	s_waitcnt lgkmcnt(4)
	v_mfma_f32_16x16x32_bf16 v[8:11], v[96:99], v[160:163], v[8:11]
	v_mfma_f32_16x16x32_bf16 v[40:43], v[164:167], v[160:163], v[40:43]
	v_mfma_f32_16x16x32_bf16 v[204:207], v[168:171], v[160:163], v[204:207]
	v_mfma_f32_16x16x32_bf16 v[104:107], v[172:175], v[160:163], v[104:107]
	ds_read_b128 v[196:199], v212 offset:14336
	global_load_dwordx4 v[92:95], v150, s[92:93] offset:0
	s_waitcnt lgkmcnt(4)
	v_mfma_f32_16x16x32_bf16 v[12:15], v[96:99], v[176:179], v[12:15]
	v_mfma_f32_16x16x32_bf16 v[44:47], v[164:167], v[176:179], v[44:47]
	v_mfma_f32_16x16x32_bf16 v[208:211], v[168:171], v[176:179], v[208:211]
	v_mfma_f32_16x16x32_bf16 v[108:111], v[172:175], v[176:179], v[108:111]
	ds_read_b128 v[160:163], v213 offset:0
	s_waitcnt lgkmcnt(4)
	v_mfma_f32_16x16x32_bf16 v[16:19], v[96:99], v[180:183], v[16:19]
	v_mfma_f32_16x16x32_bf16 v[48:51], v[164:167], v[180:183], v[48:51]
	v_mfma_f32_16x16x32_bf16 v[232:235], v[168:171], v[180:183], v[232:235]
	v_mfma_f32_16x16x32_bf16 v[112:115], v[172:175], v[180:183], v[112:115]
	ds_read_b128 v[176:179], v213 offset:2048
	s_waitcnt lgkmcnt(4)
	v_mfma_f32_16x16x32_bf16 v[20:23], v[96:99], v[188:191], v[20:23]
	v_mfma_f32_16x16x32_bf16 v[52:55], v[164:167], v[188:191], v[52:55]
	v_mfma_f32_16x16x32_bf16 v[236:239], v[168:171], v[188:191], v[236:239]
	v_mfma_f32_16x16x32_bf16 v[116:119], v[172:175], v[188:191], v[116:119]
	ds_read_b128 v[180:183], v213 offset:4096
	s_waitcnt lgkmcnt(4)
	v_mfma_f32_16x16x32_bf16 v[24:27], v[96:99], v[192:195], v[24:27]
	v_mfma_f32_16x16x32_bf16 v[56:59], v[164:167], v[192:195], v[56:59]
	v_mfma_f32_16x16x32_bf16 v[240:243], v[168:171], v[192:195], v[240:243]
	v_mfma_f32_16x16x32_bf16 v[120:123], v[172:175], v[192:195], v[120:123]
	ds_read_b128 v[188:191], v213 offset:6144
	s_waitcnt lgkmcnt(4)
	v_mfma_f32_16x16x32_bf16 v[28:31], v[96:99], v[196:199], v[28:31]
	v_mfma_f32_16x16x32_bf16 v[60:63], v[164:167], v[196:199], v[60:63]
	v_mfma_f32_16x16x32_bf16 v[248:251], v[168:171], v[196:199], v[248:251]
	v_mfma_f32_16x16x32_bf16 v[124:127], v[172:175], v[196:199], v[124:127]
	s_waitcnt vmcnt(16)
	s_barrier
	s_waitcnt vmcnt(8)
	ds_read_b128 v[192:195], v213 offset:8192
	global_load_dwordx4 v[96:99], v142, s[84:85] offset:1024
	s_waitcnt lgkmcnt(4)
	v_mfma_f32_16x16x32_bf16 v[0:3], v[64:67], v[160:163], v[0:3]
	v_mfma_f32_16x16x32_bf16 v[32:35], v[68:71], v[160:163], v[32:35]
	v_mfma_f32_16x16x32_bf16 v[144:147], v[72:75], v[160:163], v[144:147]
	v_mfma_f32_16x16x32_bf16 v[252:255], v[76:79], v[160:163], v[252:255]
	ds_read_b128 v[196:199], v213 offset:10240
	global_load_dwordx4 v[164:167], v150, s[84:85] offset:1024
	s_waitcnt lgkmcnt(4)
	v_mfma_f32_16x16x32_bf16 v[4:7], v[64:67], v[176:179], v[4:7]
	v_mfma_f32_16x16x32_bf16 v[36:39], v[68:71], v[176:179], v[36:39]
	v_mfma_f32_16x16x32_bf16 v[184:187], v[72:75], v[176:179], v[184:187]
	v_mfma_f32_16x16x32_bf16 v[100:103], v[76:79], v[176:179], v[100:103]
	ds_read_b128 v[160:163], v213 offset:12288
	global_load_dwordx4 v[168:171], v142, s[92:93] offset:1024
	s_waitcnt lgkmcnt(4)
	v_mfma_f32_16x16x32_bf16 v[8:11], v[64:67], v[180:183], v[8:11]
	v_mfma_f32_16x16x32_bf16 v[40:43], v[68:71], v[180:183], v[40:43]
	v_mfma_f32_16x16x32_bf16 v[204:207], v[72:75], v[180:183], v[204:207]
	v_mfma_f32_16x16x32_bf16 v[104:107], v[76:79], v[180:183], v[104:107]
	ds_read_b128 v[176:179], v213 offset:14336
	global_load_dwordx4 v[172:175], v150, s[92:93] offset:1024
	s_add_u32 s84, s84, 0x800
	s_addc_u32 s85, s85, 0
	s_add_u32 s92, s92, 0x800
	s_addc_u32 s93, s93, 0
	s_waitcnt lgkmcnt(4)
	v_mfma_f32_16x16x32_bf16 v[12:15], v[64:67], v[188:191], v[12:15]
	v_mfma_f32_16x16x32_bf16 v[44:47], v[68:71], v[188:191], v[44:47]
	v_mfma_f32_16x16x32_bf16 v[208:211], v[72:75], v[188:191], v[208:211]
	v_mfma_f32_16x16x32_bf16 v[108:111], v[76:79], v[188:191], v[108:111]
	ds_read_b128 v[180:183], v212 offset:16384
	s_add_u32 m0, s1, 49152
	s_nop 0
	global_load_lds_dwordx4 v151, s[86:87]
	s_waitcnt lgkmcnt(4)
	v_mfma_f32_16x16x32_bf16 v[16:19], v[64:67], v[192:195], v[16:19]
	v_mfma_f32_16x16x32_bf16 v[48:51], v[68:71], v[192:195], v[48:51]
	v_mfma_f32_16x16x32_bf16 v[232:235], v[72:75], v[192:195], v[232:235]
	v_mfma_f32_16x16x32_bf16 v[112:115], v[76:79], v[192:195], v[112:115]
	ds_read_b128 v[188:191], v212 offset:18432
	s_add_u32 m0, s1, 53248
	s_nop 0
	global_load_lds_dwordx4 v156, s[86:87]
	s_waitcnt lgkmcnt(4)
	v_mfma_f32_16x16x32_bf16 v[20:23], v[64:67], v[196:199], v[20:23]
	v_mfma_f32_16x16x32_bf16 v[52:55], v[68:71], v[196:199], v[52:55]
	v_mfma_f32_16x16x32_bf16 v[236:239], v[72:75], v[196:199], v[236:239]
	v_mfma_f32_16x16x32_bf16 v[116:119], v[76:79], v[196:199], v[116:119]
	ds_read_b128 v[192:195], v212 offset:20480
	s_add_u32 m0, s1, 57344
	s_nop 0
	global_load_lds_dwordx4 v158, s[86:87]
	s_waitcnt lgkmcnt(4)
	v_mfma_f32_16x16x32_bf16 v[24:27], v[64:67], v[160:163], v[24:27]
	v_mfma_f32_16x16x32_bf16 v[56:59], v[68:71], v[160:163], v[56:59]
	v_mfma_f32_16x16x32_bf16 v[240:243], v[72:75], v[160:163], v[240:243]
	v_mfma_f32_16x16x32_bf16 v[120:123], v[76:79], v[160:163], v[120:123]
	ds_read_b128 v[196:199], v212 offset:22528
	s_add_u32 m0, s1, 61440
	s_nop 0
	global_load_lds_dwordx4 v159, s[86:87]
	s_add_u32 s86, s86, 128
	s_addc_u32 s87, s87, 0
	s_waitcnt lgkmcnt(4)
	v_mfma_f32_16x16x32_bf16 v[28:31], v[64:67], v[176:179], v[28:31]
	v_mfma_f32_16x16x32_bf16 v[60:63], v[68:71], v[176:179], v[60:63]
	v_mfma_f32_16x16x32_bf16 v[248:251], v[72:75], v[176:179], v[248:251]
	v_mfma_f32_16x16x32_bf16 v[124:127], v[76:79], v[176:179], v[124:127]
	s_waitcnt vmcnt(8)
	ds_read_b128 v[160:163], v212 offset:24576
	global_load_dwordx4 v[64:67], v142, s[84:85] offset:0
	s_waitcnt lgkmcnt(4)
	v_mfma_f32_16x16x32_bf16 v[0:3], v[80:83], v[180:183], v[0:3]
	v_mfma_f32_16x16x32_bf16 v[32:35], v[84:87], v[180:183], v[32:35]
	v_mfma_f32_16x16x32_bf16 v[144:147], v[88:91], v[180:183], v[144:147]
	v_mfma_f32_16x16x32_bf16 v[252:255], v[92:95], v[180:183], v[252:255]
	ds_read_b128 v[176:179], v212 offset:26624
	global_load_dwordx4 v[68:71], v150, s[84:85] offset:0
	s_waitcnt lgkmcnt(4)
	v_mfma_f32_16x16x32_bf16 v[4:7], v[80:83], v[188:191], v[4:7]
	v_mfma_f32_16x16x32_bf16 v[36:39], v[84:87], v[188:191], v[36:39]
	v_mfma_f32_16x16x32_bf16 v[184:187], v[88:91], v[188:191], v[184:187]
	v_mfma_f32_16x16x32_bf16 v[100:103], v[92:95], v[188:191], v[100:103]
	ds_read_b128 v[180:183], v212 offset:28672
	global_load_dwordx4 v[72:75], v142, s[92:93] offset:0
	s_waitcnt lgkmcnt(4)
	v_mfma_f32_16x16x32_bf16 v[8:11], v[80:83], v[192:195], v[8:11]
	v_mfma_f32_16x16x32_bf16 v[40:43], v[84:87], v[192:195], v[40:43]
	v_mfma_f32_16x16x32_bf16 v[204:207], v[88:91], v[192:195], v[204:207]
	v_mfma_f32_16x16x32_bf16 v[104:107], v[92:95], v[192:195], v[104:107]
	ds_read_b128 v[188:191], v212 offset:30720
	global_load_dwordx4 v[76:79], v150, s[92:93] offset:0
	s_waitcnt lgkmcnt(4)
	v_mfma_f32_16x16x32_bf16 v[12:15], v[80:83], v[196:199], v[12:15]
	v_mfma_f32_16x16x32_bf16 v[44:47], v[84:87], v[196:199], v[44:47]
	v_mfma_f32_16x16x32_bf16 v[208:211], v[88:91], v[196:199], v[208:211]
	v_mfma_f32_16x16x32_bf16 v[108:111], v[92:95], v[196:199], v[108:111]
	ds_read_b128 v[192:195], v213 offset:16384
	s_waitcnt lgkmcnt(4)
	v_mfma_f32_16x16x32_bf16 v[16:19], v[80:83], v[160:163], v[16:19]
	v_mfma_f32_16x16x32_bf16 v[48:51], v[84:87], v[160:163], v[48:51]
	v_mfma_f32_16x16x32_bf16 v[232:235], v[88:91], v[160:163], v[232:235]
	v_mfma_f32_16x16x32_bf16 v[112:115], v[92:95], v[160:163], v[112:115]
	ds_read_b128 v[196:199], v213 offset:18432
	s_waitcnt lgkmcnt(4)
	v_mfma_f32_16x16x32_bf16 v[20:23], v[80:83], v[176:179], v[20:23]
	v_mfma_f32_16x16x32_bf16 v[52:55], v[84:87], v[176:179], v[52:55]
	v_mfma_f32_16x16x32_bf16 v[236:239], v[88:91], v[176:179], v[236:239]
	v_mfma_f32_16x16x32_bf16 v[116:119], v[92:95], v[176:179], v[116:119]
	ds_read_b128 v[160:163], v213 offset:20480
	s_waitcnt lgkmcnt(4)
	v_mfma_f32_16x16x32_bf16 v[24:27], v[80:83], v[180:183], v[24:27]
	v_mfma_f32_16x16x32_bf16 v[56:59], v[84:87], v[180:183], v[56:59]
	v_mfma_f32_16x16x32_bf16 v[240:243], v[88:91], v[180:183], v[240:243]
	v_mfma_f32_16x16x32_bf16 v[120:123], v[92:95], v[180:183], v[120:123]
	ds_read_b128 v[176:179], v213 offset:22528
	s_waitcnt lgkmcnt(4)
	v_mfma_f32_16x16x32_bf16 v[28:31], v[80:83], v[188:191], v[28:31]
	v_mfma_f32_16x16x32_bf16 v[60:63], v[84:87], v[188:191], v[60:63]
	v_mfma_f32_16x16x32_bf16 v[248:251], v[88:91], v[188:191], v[248:251]
	v_mfma_f32_16x16x32_bf16 v[124:127], v[92:95], v[188:191], v[124:127]
	s_waitcnt vmcnt(16)
	s_barrier
	s_waitcnt vmcnt(8)
	ds_read_b128 v[180:183], v213 offset:24576
	global_load_dwordx4 v[80:83], v142, s[84:85] offset:1024
	s_waitcnt lgkmcnt(4)
	v_mfma_f32_16x16x32_bf16 v[0:3], v[96:99], v[192:195], v[0:3]
	v_mfma_f32_16x16x32_bf16 v[32:35], v[164:167], v[192:195], v[32:35]
	v_mfma_f32_16x16x32_bf16 v[144:147], v[168:171], v[192:195], v[144:147]
	v_mfma_f32_16x16x32_bf16 v[252:255], v[172:175], v[192:195], v[252:255]
	ds_read_b128 v[188:191], v213 offset:26624
	global_load_dwordx4 v[84:87], v150, s[84:85] offset:1024
	s_waitcnt lgkmcnt(4)
	v_mfma_f32_16x16x32_bf16 v[4:7], v[96:99], v[196:199], v[4:7]
	v_mfma_f32_16x16x32_bf16 v[36:39], v[164:167], v[196:199], v[36:39]
	v_mfma_f32_16x16x32_bf16 v[184:187], v[168:171], v[196:199], v[184:187]
	v_mfma_f32_16x16x32_bf16 v[100:103], v[172:175], v[196:199], v[100:103]
	ds_read_b128 v[192:195], v213 offset:28672
	global_load_dwordx4 v[88:91], v142, s[92:93] offset:1024
	s_waitcnt lgkmcnt(4)
	v_mfma_f32_16x16x32_bf16 v[8:11], v[96:99], v[160:163], v[8:11]
	v_mfma_f32_16x16x32_bf16 v[40:43], v[164:167], v[160:163], v[40:43]
	v_mfma_f32_16x16x32_bf16 v[204:207], v[168:171], v[160:163], v[204:207]
	v_mfma_f32_16x16x32_bf16 v[104:107], v[172:175], v[160:163], v[104:107]
	ds_read_b128 v[196:199], v213 offset:30720
	global_load_dwordx4 v[92:95], v150, s[92:93] offset:1024
	s_add_u32 s84, s84, 0x800
	s_addc_u32 s85, s85, 0
	s_add_u32 s92, s92, 0x800
	s_addc_u32 s93, s93, 0
	s_waitcnt lgkmcnt(4)
	v_mfma_f32_16x16x32_bf16 v[12:15], v[96:99], v[176:179], v[12:15]
	v_mfma_f32_16x16x32_bf16 v[44:47], v[164:167], v[176:179], v[44:47]
	v_mfma_f32_16x16x32_bf16 v[208:211], v[168:171], v[176:179], v[208:211]
	v_mfma_f32_16x16x32_bf16 v[108:111], v[172:175], v[176:179], v[108:111]
	ds_read_b128 v[160:163], v212 offset:32768
	s_add_u32 m0, s1, 0
	s_nop 0
	global_load_lds_dwordx4 v151, s[86:87]
	s_waitcnt lgkmcnt(4)
	v_mfma_f32_16x16x32_bf16 v[16:19], v[96:99], v[180:183], v[16:19]
	v_mfma_f32_16x16x32_bf16 v[48:51], v[164:167], v[180:183], v[48:51]
	v_mfma_f32_16x16x32_bf16 v[232:235], v[168:171], v[180:183], v[232:235]
	v_mfma_f32_16x16x32_bf16 v[112:115], v[172:175], v[180:183], v[112:115]
	ds_read_b128 v[176:179], v212 offset:34816
	s_add_u32 m0, s1, 4096
	s_nop 0
	global_load_lds_dwordx4 v156, s[86:87]
	s_waitcnt lgkmcnt(4)
	v_mfma_f32_16x16x32_bf16 v[20:23], v[96:99], v[188:191], v[20:23]
	v_mfma_f32_16x16x32_bf16 v[52:55], v[164:167], v[188:191], v[52:55]
	v_mfma_f32_16x16x32_bf16 v[236:239], v[168:171], v[188:191], v[236:239]
	v_mfma_f32_16x16x32_bf16 v[116:119], v[172:175], v[188:191], v[116:119]
	ds_read_b128 v[180:183], v212 offset:36864
	s_add_u32 m0, s1, 8192
	s_nop 0
	global_load_lds_dwordx4 v158, s[86:87]
	s_waitcnt lgkmcnt(4)
	v_mfma_f32_16x16x32_bf16 v[24:27], v[96:99], v[192:195], v[24:27]
	v_mfma_f32_16x16x32_bf16 v[56:59], v[164:167], v[192:195], v[56:59]
	v_mfma_f32_16x16x32_bf16 v[240:243], v[168:171], v[192:195], v[240:243]
	v_mfma_f32_16x16x32_bf16 v[120:123], v[172:175], v[192:195], v[120:123]
	ds_read_b128 v[188:191], v212 offset:38912
	s_add_u32 m0, s1, 12288
	s_nop 0
	global_load_lds_dwordx4 v159, s[86:87]
	s_add_u32 s86, s86, 128
	s_addc_u32 s87, s87, 0
	s_waitcnt lgkmcnt(4)
	v_mfma_f32_16x16x32_bf16 v[28:31], v[96:99], v[196:199], v[28:31]
	v_mfma_f32_16x16x32_bf16 v[60:63], v[164:167], v[196:199], v[60:63]
	v_mfma_f32_16x16x32_bf16 v[248:251], v[168:171], v[196:199], v[248:251]
	v_mfma_f32_16x16x32_bf16 v[124:127], v[172:175], v[196:199], v[124:127]
	s_waitcnt vmcnt(8)
	ds_read_b128 v[192:195], v212 offset:40960
	global_load_dwordx4 v[96:99], v142, s[84:85] offset:0
	s_waitcnt lgkmcnt(4)
	v_mfma_f32_16x16x32_bf16 v[0:3], v[64:67], v[160:163], v[0:3]
	v_mfma_f32_16x16x32_bf16 v[32:35], v[68:71], v[160:163], v[32:35]
	v_mfma_f32_16x16x32_bf16 v[144:147], v[72:75], v[160:163], v[144:147]
	v_mfma_f32_16x16x32_bf16 v[252:255], v[76:79], v[160:163], v[252:255]
	ds_read_b128 v[196:199], v212 offset:43008
	global_load_dwordx4 v[164:167], v150, s[84:85] offset:0
	s_waitcnt lgkmcnt(4)
	v_mfma_f32_16x16x32_bf16 v[4:7], v[64:67], v[176:179], v[4:7]
	v_mfma_f32_16x16x32_bf16 v[36:39], v[68:71], v[176:179], v[36:39]
	v_mfma_f32_16x16x32_bf16 v[184:187], v[72:75], v[176:179], v[184:187]
	v_mfma_f32_16x16x32_bf16 v[100:103], v[76:79], v[176:179], v[100:103]
	ds_read_b128 v[160:163], v212 offset:45056
	global_load_dwordx4 v[168:171], v142, s[92:93] offset:0
	s_waitcnt lgkmcnt(4)
	v_mfma_f32_16x16x32_bf16 v[8:11], v[64:67], v[180:183], v[8:11]
	v_mfma_f32_16x16x32_bf16 v[40:43], v[68:71], v[180:183], v[40:43]
	v_mfma_f32_16x16x32_bf16 v[204:207], v[72:75], v[180:183], v[204:207]
	v_mfma_f32_16x16x32_bf16 v[104:107], v[76:79], v[180:183], v[104:107]
	ds_read_b128 v[176:179], v212 offset:47104
	global_load_dwordx4 v[172:175], v150, s[92:93] offset:0
	s_waitcnt lgkmcnt(4)
	v_mfma_f32_16x16x32_bf16 v[12:15], v[64:67], v[188:191], v[12:15]
	v_mfma_f32_16x16x32_bf16 v[44:47], v[68:71], v[188:191], v[44:47]
	v_mfma_f32_16x16x32_bf16 v[208:211], v[72:75], v[188:191], v[208:211]
	v_mfma_f32_16x16x32_bf16 v[108:111], v[76:79], v[188:191], v[108:111]
	ds_read_b128 v[180:183], v213 offset:32768
	s_waitcnt lgkmcnt(4)
	v_mfma_f32_16x16x32_bf16 v[16:19], v[64:67], v[192:195], v[16:19]
	v_mfma_f32_16x16x32_bf16 v[48:51], v[68:71], v[192:195], v[48:51]
	v_mfma_f32_16x16x32_bf16 v[232:235], v[72:75], v[192:195], v[232:235]
	v_mfma_f32_16x16x32_bf16 v[112:115], v[76:79], v[192:195], v[112:115]
	ds_read_b128 v[188:191], v213 offset:34816
	s_waitcnt lgkmcnt(4)
	v_mfma_f32_16x16x32_bf16 v[20:23], v[64:67], v[196:199], v[20:23]
	v_mfma_f32_16x16x32_bf16 v[52:55], v[68:71], v[196:199], v[52:55]
	v_mfma_f32_16x16x32_bf16 v[236:239], v[72:75], v[196:199], v[236:239]
	v_mfma_f32_16x16x32_bf16 v[116:119], v[76:79], v[196:199], v[116:119]
	ds_read_b128 v[192:195], v213 offset:36864
	s_waitcnt lgkmcnt(4)
	v_mfma_f32_16x16x32_bf16 v[24:27], v[64:67], v[160:163], v[24:27]
	v_mfma_f32_16x16x32_bf16 v[56:59], v[68:71], v[160:163], v[56:59]
	v_mfma_f32_16x16x32_bf16 v[240:243], v[72:75], v[160:163], v[240:243]
	v_mfma_f32_16x16x32_bf16 v[120:123], v[76:79], v[160:163], v[120:123]
	ds_read_b128 v[196:199], v213 offset:38912
	s_waitcnt lgkmcnt(4)
	v_mfma_f32_16x16x32_bf16 v[28:31], v[64:67], v[176:179], v[28:31]
	v_mfma_f32_16x16x32_bf16 v[60:63], v[68:71], v[176:179], v[60:63]
	v_mfma_f32_16x16x32_bf16 v[248:251], v[72:75], v[176:179], v[248:251]
	v_mfma_f32_16x16x32_bf16 v[124:127], v[76:79], v[176:179], v[124:127]
	s_waitcnt vmcnt(16)
	s_barrier
	s_waitcnt vmcnt(8)
	ds_read_b128 v[160:163], v213 offset:40960
	global_load_dwordx4 v[64:67], v142, s[84:85] offset:1024
	s_waitcnt lgkmcnt(4)
	v_mfma_f32_16x16x32_bf16 v[0:3], v[80:83], v[180:183], v[0:3]
	v_mfma_f32_16x16x32_bf16 v[32:35], v[84:87], v[180:183], v[32:35]
	v_mfma_f32_16x16x32_bf16 v[144:147], v[88:91], v[180:183], v[144:147]
	v_mfma_f32_16x16x32_bf16 v[252:255], v[92:95], v[180:183], v[252:255]
	ds_read_b128 v[176:179], v213 offset:43008
	global_load_dwordx4 v[68:71], v150, s[84:85] offset:1024
	s_waitcnt lgkmcnt(4)
	v_mfma_f32_16x16x32_bf16 v[4:7], v[80:83], v[188:191], v[4:7]
	v_mfma_f32_16x16x32_bf16 v[36:39], v[84:87], v[188:191], v[36:39]
	v_mfma_f32_16x16x32_bf16 v[184:187], v[88:91], v[188:191], v[184:187]
	v_mfma_f32_16x16x32_bf16 v[100:103], v[92:95], v[188:191], v[100:103]
	ds_read_b128 v[180:183], v213 offset:45056
	global_load_dwordx4 v[72:75], v142, s[92:93] offset:1024
	s_waitcnt lgkmcnt(4)
	v_mfma_f32_16x16x32_bf16 v[8:11], v[80:83], v[192:195], v[8:11]
	v_mfma_f32_16x16x32_bf16 v[40:43], v[84:87], v[192:195], v[40:43]
	v_mfma_f32_16x16x32_bf16 v[204:207], v[88:91], v[192:195], v[204:207]
	v_mfma_f32_16x16x32_bf16 v[104:107], v[92:95], v[192:195], v[104:107]
	ds_read_b128 v[188:191], v213 offset:47104
	global_load_dwordx4 v[76:79], v150, s[92:93] offset:1024
	s_add_u32 s84, s84, 0x800
	s_addc_u32 s85, s85, 0
	s_add_u32 s92, s92, 0x800
	s_addc_u32 s93, s93, 0
	s_waitcnt lgkmcnt(4)
	v_mfma_f32_16x16x32_bf16 v[12:15], v[80:83], v[196:199], v[12:15]
	v_mfma_f32_16x16x32_bf16 v[44:47], v[84:87], v[196:199], v[44:47]
	v_mfma_f32_16x16x32_bf16 v[208:211], v[88:91], v[196:199], v[208:211]
	v_mfma_f32_16x16x32_bf16 v[108:111], v[92:95], v[196:199], v[108:111]
	ds_read_b128 v[192:195], v212 offset:49152
	s_add_u32 m0, s1, 16384
	s_nop 0
	global_load_lds_dwordx4 v151, s[86:87]
	s_waitcnt lgkmcnt(4)
	v_mfma_f32_16x16x32_bf16 v[16:19], v[80:83], v[160:163], v[16:19]
	v_mfma_f32_16x16x32_bf16 v[48:51], v[84:87], v[160:163], v[48:51]
	v_mfma_f32_16x16x32_bf16 v[232:235], v[88:91], v[160:163], v[232:235]
	v_mfma_f32_16x16x32_bf16 v[112:115], v[92:95], v[160:163], v[112:115]
	ds_read_b128 v[196:199], v212 offset:51200
	s_add_u32 m0, s1, 20480
	s_nop 0
	global_load_lds_dwordx4 v156, s[86:87]
	s_waitcnt lgkmcnt(4)
	v_mfma_f32_16x16x32_bf16 v[20:23], v[80:83], v[176:179], v[20:23]
	v_mfma_f32_16x16x32_bf16 v[52:55], v[84:87], v[176:179], v[52:55]
	v_mfma_f32_16x16x32_bf16 v[236:239], v[88:91], v[176:179], v[236:239]
	v_mfma_f32_16x16x32_bf16 v[116:119], v[92:95], v[176:179], v[116:119]
	ds_read_b128 v[160:163], v212 offset:53248
	s_add_u32 m0, s1, 24576
	s_nop 0
	global_load_lds_dwordx4 v158, s[86:87]
	s_waitcnt lgkmcnt(4)
	v_mfma_f32_16x16x32_bf16 v[24:27], v[80:83], v[180:183], v[24:27]
	v_mfma_f32_16x16x32_bf16 v[56:59], v[84:87], v[180:183], v[56:59]
	v_mfma_f32_16x16x32_bf16 v[240:243], v[88:91], v[180:183], v[240:243]
	v_mfma_f32_16x16x32_bf16 v[120:123], v[92:95], v[180:183], v[120:123]
	ds_read_b128 v[176:179], v212 offset:55296
	s_add_u32 m0, s1, 28672
	s_nop 0
	global_load_lds_dwordx4 v159, s[86:87]
	s_add_u32 s86, s86, 128
	s_addc_u32 s87, s87, 0
	s_waitcnt lgkmcnt(4)
	v_mfma_f32_16x16x32_bf16 v[28:31], v[80:83], v[188:191], v[28:31]
	v_mfma_f32_16x16x32_bf16 v[60:63], v[84:87], v[188:191], v[60:63]
	v_mfma_f32_16x16x32_bf16 v[248:251], v[88:91], v[188:191], v[248:251]
	v_mfma_f32_16x16x32_bf16 v[124:127], v[92:95], v[188:191], v[124:127]
	s_waitcnt vmcnt(8)
	ds_read_b128 v[180:183], v212 offset:57344
	global_load_dwordx4 v[80:83], v142, s[84:85] offset:0
	s_waitcnt lgkmcnt(4)
	v_mfma_f32_16x16x32_bf16 v[0:3], v[96:99], v[192:195], v[0:3]
	v_mfma_f32_16x16x32_bf16 v[32:35], v[164:167], v[192:195], v[32:35]
	v_mfma_f32_16x16x32_bf16 v[144:147], v[168:171], v[192:195], v[144:147]
	v_mfma_f32_16x16x32_bf16 v[252:255], v[172:175], v[192:195], v[252:255]
	ds_read_b128 v[188:191], v212 offset:59392
	global_load_dwordx4 v[84:87], v150, s[84:85] offset:0
	s_waitcnt lgkmcnt(4)
	v_mfma_f32_16x16x32_bf16 v[4:7], v[96:99], v[196:199], v[4:7]
	v_mfma_f32_16x16x32_bf16 v[36:39], v[164:167], v[196:199], v[36:39]
	v_mfma_f32_16x16x32_bf16 v[184:187], v[168:171], v[196:199], v[184:187]
	v_mfma_f32_16x16x32_bf16 v[100:103], v[172:175], v[196:199], v[100:103]
	ds_read_b128 v[192:195], v212 offset:61440
	global_load_dwordx4 v[88:91], v142, s[92:93] offset:0
	s_waitcnt lgkmcnt(4)
	v_mfma_f32_16x16x32_bf16 v[8:11], v[96:99], v[160:163], v[8:11]
	v_mfma_f32_16x16x32_bf16 v[40:43], v[164:167], v[160:163], v[40:43]
	v_mfma_f32_16x16x32_bf16 v[204:207], v[168:171], v[160:163], v[204:207]
	v_mfma_f32_16x16x32_bf16 v[104:107], v[172:175], v[160:163], v[104:107]
	ds_read_b128 v[196:199], v212 offset:63488
	global_load_dwordx4 v[92:95], v150, s[92:93] offset:0
	s_waitcnt lgkmcnt(4)
	v_mfma_f32_16x16x32_bf16 v[12:15], v[96:99], v[176:179], v[12:15]
	v_mfma_f32_16x16x32_bf16 v[44:47], v[164:167], v[176:179], v[44:47]
	v_mfma_f32_16x16x32_bf16 v[208:211], v[168:171], v[176:179], v[208:211]
	v_mfma_f32_16x16x32_bf16 v[108:111], v[172:175], v[176:179], v[108:111]
	ds_read_b128 v[160:163], v213 offset:49152
	s_waitcnt lgkmcnt(4)
	v_mfma_f32_16x16x32_bf16 v[16:19], v[96:99], v[180:183], v[16:19]
	v_mfma_f32_16x16x32_bf16 v[48:51], v[164:167], v[180:183], v[48:51]
	v_mfma_f32_16x16x32_bf16 v[232:235], v[168:171], v[180:183], v[232:235]
	v_mfma_f32_16x16x32_bf16 v[112:115], v[172:175], v[180:183], v[112:115]
	ds_read_b128 v[176:179], v213 offset:51200
	s_waitcnt lgkmcnt(4)
	v_mfma_f32_16x16x32_bf16 v[20:23], v[96:99], v[188:191], v[20:23]
	v_mfma_f32_16x16x32_bf16 v[52:55], v[164:167], v[188:191], v[52:55]
	v_mfma_f32_16x16x32_bf16 v[236:239], v[168:171], v[188:191], v[236:239]
	v_mfma_f32_16x16x32_bf16 v[116:119], v[172:175], v[188:191], v[116:119]
	ds_read_b128 v[180:183], v213 offset:53248
	s_waitcnt lgkmcnt(4)
	v_mfma_f32_16x16x32_bf16 v[24:27], v[96:99], v[192:195], v[24:27]
	v_mfma_f32_16x16x32_bf16 v[56:59], v[164:167], v[192:195], v[56:59]
	v_mfma_f32_16x16x32_bf16 v[240:243], v[168:171], v[192:195], v[240:243]
	v_mfma_f32_16x16x32_bf16 v[120:123], v[172:175], v[192:195], v[120:123]
	ds_read_b128 v[188:191], v213 offset:55296
	s_waitcnt lgkmcnt(4)
	v_mfma_f32_16x16x32_bf16 v[28:31], v[96:99], v[196:199], v[28:31]
	v_mfma_f32_16x16x32_bf16 v[60:63], v[164:167], v[196:199], v[60:63]
	v_mfma_f32_16x16x32_bf16 v[248:251], v[168:171], v[196:199], v[248:251]
	v_mfma_f32_16x16x32_bf16 v[124:127], v[172:175], v[196:199], v[124:127]
	s_waitcnt vmcnt(16)
	s_barrier
	s_waitcnt vmcnt(8)
	ds_read_b128 v[192:195], v213 offset:57344
	global_load_dwordx4 v[96:99], v142, s[84:85] offset:1024
	s_waitcnt lgkmcnt(4)
	v_mfma_f32_16x16x32_bf16 v[0:3], v[64:67], v[160:163], v[0:3]
	v_mfma_f32_16x16x32_bf16 v[32:35], v[68:71], v[160:163], v[32:35]
	v_mfma_f32_16x16x32_bf16 v[144:147], v[72:75], v[160:163], v[144:147]
	v_mfma_f32_16x16x32_bf16 v[252:255], v[76:79], v[160:163], v[252:255]
	ds_read_b128 v[196:199], v213 offset:59392
	global_load_dwordx4 v[164:167], v150, s[84:85] offset:1024
	s_waitcnt lgkmcnt(4)
	v_mfma_f32_16x16x32_bf16 v[4:7], v[64:67], v[176:179], v[4:7]
	v_mfma_f32_16x16x32_bf16 v[36:39], v[68:71], v[176:179], v[36:39]
	v_mfma_f32_16x16x32_bf16 v[184:187], v[72:75], v[176:179], v[184:187]
	v_mfma_f32_16x16x32_bf16 v[100:103], v[76:79], v[176:179], v[100:103]
	ds_read_b128 v[160:163], v213 offset:61440
	global_load_dwordx4 v[168:171], v142, s[92:93] offset:1024
	s_waitcnt lgkmcnt(4)
	v_mfma_f32_16x16x32_bf16 v[8:11], v[64:67], v[180:183], v[8:11]
	v_mfma_f32_16x16x32_bf16 v[40:43], v[68:71], v[180:183], v[40:43]
	v_mfma_f32_16x16x32_bf16 v[204:207], v[72:75], v[180:183], v[204:207]
	v_mfma_f32_16x16x32_bf16 v[104:107], v[76:79], v[180:183], v[104:107]
	ds_read_b128 v[176:179], v213 offset:63488
	global_load_dwordx4 v[172:175], v150, s[92:93] offset:1024
	s_add_u32 s84, s84, 0x800
	s_addc_u32 s85, s85, 0
	s_add_u32 s92, s92, 0x800
	s_addc_u32 s93, s93, 0
	s_waitcnt lgkmcnt(4)
	v_mfma_f32_16x16x32_bf16 v[12:15], v[64:67], v[188:191], v[12:15]
	v_mfma_f32_16x16x32_bf16 v[44:47], v[68:71], v[188:191], v[44:47]
	v_mfma_f32_16x16x32_bf16 v[208:211], v[72:75], v[188:191], v[208:211]
	v_mfma_f32_16x16x32_bf16 v[108:111], v[76:79], v[188:191], v[108:111]
	ds_read_b128 v[180:183], v212 offset:0
	s_add_u32 m0, s1, 32768
	s_nop 0
	global_load_lds_dwordx4 v151, s[86:87]
	s_waitcnt lgkmcnt(4)
	v_mfma_f32_16x16x32_bf16 v[16:19], v[64:67], v[192:195], v[16:19]
	v_mfma_f32_16x16x32_bf16 v[48:51], v[68:71], v[192:195], v[48:51]
	v_mfma_f32_16x16x32_bf16 v[232:235], v[72:75], v[192:195], v[232:235]
	v_mfma_f32_16x16x32_bf16 v[112:115], v[76:79], v[192:195], v[112:115]
	ds_read_b128 v[188:191], v212 offset:2048
	s_add_u32 m0, s1, 36864
	s_nop 0
	global_load_lds_dwordx4 v156, s[86:87]
	s_waitcnt lgkmcnt(4)
	v_mfma_f32_16x16x32_bf16 v[20:23], v[64:67], v[196:199], v[20:23]
	v_mfma_f32_16x16x32_bf16 v[52:55], v[68:71], v[196:199], v[52:55]
	v_mfma_f32_16x16x32_bf16 v[236:239], v[72:75], v[196:199], v[236:239]
	v_mfma_f32_16x16x32_bf16 v[116:119], v[76:79], v[196:199], v[116:119]
	ds_read_b128 v[192:195], v212 offset:4096
	s_add_u32 m0, s1, 40960
	s_nop 0
	global_load_lds_dwordx4 v158, s[86:87]
	s_waitcnt lgkmcnt(4)
	v_mfma_f32_16x16x32_bf16 v[24:27], v[64:67], v[160:163], v[24:27]
	v_mfma_f32_16x16x32_bf16 v[56:59], v[68:71], v[160:163], v[56:59]
	v_mfma_f32_16x16x32_bf16 v[240:243], v[72:75], v[160:163], v[240:243]
	v_mfma_f32_16x16x32_bf16 v[120:123], v[76:79], v[160:163], v[120:123]
	ds_read_b128 v[196:199], v212 offset:6144
	s_add_u32 m0, s1, 45056
	s_nop 0
	global_load_lds_dwordx4 v159, s[86:87]
	s_add_u32 s86, s86, 128
	s_addc_u32 s87, s87, 0
	s_waitcnt lgkmcnt(4)
	v_mfma_f32_16x16x32_bf16 v[28:31], v[64:67], v[176:179], v[28:31]
	v_mfma_f32_16x16x32_bf16 v[60:63], v[68:71], v[176:179], v[60:63]
	v_mfma_f32_16x16x32_bf16 v[248:251], v[72:75], v[176:179], v[248:251]
	v_mfma_f32_16x16x32_bf16 v[124:127], v[76:79], v[176:179], v[124:127]
	s_waitcnt vmcnt(8)
	ds_read_b128 v[160:163], v212 offset:8192
	global_load_dwordx4 v[64:67], v142, s[84:85] offset:0
	s_waitcnt lgkmcnt(4)
	v_mfma_f32_16x16x32_bf16 v[0:3], v[80:83], v[180:183], v[0:3]
	v_mfma_f32_16x16x32_bf16 v[32:35], v[84:87], v[180:183], v[32:35]
	v_mfma_f32_16x16x32_bf16 v[144:147], v[88:91], v[180:183], v[144:147]
	v_mfma_f32_16x16x32_bf16 v[252:255], v[92:95], v[180:183], v[252:255]
	ds_read_b128 v[176:179], v212 offset:10240
	global_load_dwordx4 v[68:71], v150, s[84:85] offset:0
	s_waitcnt lgkmcnt(4)
	v_mfma_f32_16x16x32_bf16 v[4:7], v[80:83], v[188:191], v[4:7]
	v_mfma_f32_16x16x32_bf16 v[36:39], v[84:87], v[188:191], v[36:39]
	v_mfma_f32_16x16x32_bf16 v[184:187], v[88:91], v[188:191], v[184:187]
	v_mfma_f32_16x16x32_bf16 v[100:103], v[92:95], v[188:191], v[100:103]
	ds_read_b128 v[180:183], v212 offset:12288
	global_load_dwordx4 v[72:75], v142, s[92:93] offset:0
	s_waitcnt lgkmcnt(4)
	v_mfma_f32_16x16x32_bf16 v[8:11], v[80:83], v[192:195], v[8:11]
	v_mfma_f32_16x16x32_bf16 v[40:43], v[84:87], v[192:195], v[40:43]
	v_mfma_f32_16x16x32_bf16 v[204:207], v[88:91], v[192:195], v[204:207]
	v_mfma_f32_16x16x32_bf16 v[104:107], v[92:95], v[192:195], v[104:107]
	ds_read_b128 v[188:191], v212 offset:14336
	global_load_dwordx4 v[76:79], v150, s[92:93] offset:0
	s_waitcnt lgkmcnt(4)
	v_mfma_f32_16x16x32_bf16 v[12:15], v[80:83], v[196:199], v[12:15]
	v_mfma_f32_16x16x32_bf16 v[44:47], v[84:87], v[196:199], v[44:47]
	v_mfma_f32_16x16x32_bf16 v[208:211], v[88:91], v[196:199], v[208:211]
	v_mfma_f32_16x16x32_bf16 v[108:111], v[92:95], v[196:199], v[108:111]
	ds_read_b128 v[192:195], v213 offset:0
	s_waitcnt lgkmcnt(4)
	v_mfma_f32_16x16x32_bf16 v[16:19], v[80:83], v[160:163], v[16:19]
	v_mfma_f32_16x16x32_bf16 v[48:51], v[84:87], v[160:163], v[48:51]
	v_mfma_f32_16x16x32_bf16 v[232:235], v[88:91], v[160:163], v[232:235]
	v_mfma_f32_16x16x32_bf16 v[112:115], v[92:95], v[160:163], v[112:115]
	ds_read_b128 v[196:199], v213 offset:2048
	s_waitcnt lgkmcnt(4)
	v_mfma_f32_16x16x32_bf16 v[20:23], v[80:83], v[176:179], v[20:23]
	v_mfma_f32_16x16x32_bf16 v[52:55], v[84:87], v[176:179], v[52:55]
	v_mfma_f32_16x16x32_bf16 v[236:239], v[88:91], v[176:179], v[236:239]
	v_mfma_f32_16x16x32_bf16 v[116:119], v[92:95], v[176:179], v[116:119]
	ds_read_b128 v[160:163], v213 offset:4096
	s_waitcnt lgkmcnt(4)
	v_mfma_f32_16x16x32_bf16 v[24:27], v[80:83], v[180:183], v[24:27]
	v_mfma_f32_16x16x32_bf16 v[56:59], v[84:87], v[180:183], v[56:59]
	v_mfma_f32_16x16x32_bf16 v[240:243], v[88:91], v[180:183], v[240:243]
	v_mfma_f32_16x16x32_bf16 v[120:123], v[92:95], v[180:183], v[120:123]
	ds_read_b128 v[176:179], v213 offset:6144
	s_waitcnt lgkmcnt(4)
	v_mfma_f32_16x16x32_bf16 v[28:31], v[80:83], v[188:191], v[28:31]
	v_mfma_f32_16x16x32_bf16 v[60:63], v[84:87], v[188:191], v[60:63]
	v_mfma_f32_16x16x32_bf16 v[248:251], v[88:91], v[188:191], v[248:251]
	v_mfma_f32_16x16x32_bf16 v[124:127], v[92:95], v[188:191], v[124:127]
	s_waitcnt vmcnt(16)
	s_barrier
	s_waitcnt vmcnt(8)
	ds_read_b128 v[180:183], v213 offset:8192
	global_load_dwordx4 v[80:83], v142, s[84:85] offset:1024
	s_waitcnt lgkmcnt(4)
	v_mfma_f32_16x16x32_bf16 v[0:3], v[96:99], v[192:195], v[0:3]
	v_mfma_f32_16x16x32_bf16 v[32:35], v[164:167], v[192:195], v[32:35]
	v_mfma_f32_16x16x32_bf16 v[144:147], v[168:171], v[192:195], v[144:147]
	v_mfma_f32_16x16x32_bf16 v[252:255], v[172:175], v[192:195], v[252:255]
	ds_read_b128 v[188:191], v213 offset:10240
	global_load_dwordx4 v[84:87], v150, s[84:85] offset:1024
	s_waitcnt lgkmcnt(4)
	v_mfma_f32_16x16x32_bf16 v[4:7], v[96:99], v[196:199], v[4:7]
	v_mfma_f32_16x16x32_bf16 v[36:39], v[164:167], v[196:199], v[36:39]
	v_mfma_f32_16x16x32_bf16 v[184:187], v[168:171], v[196:199], v[184:187]
	v_mfma_f32_16x16x32_bf16 v[100:103], v[172:175], v[196:199], v[100:103]
	ds_read_b128 v[192:195], v213 offset:12288
	global_load_dwordx4 v[88:91], v142, s[92:93] offset:1024
	s_waitcnt lgkmcnt(4)
	v_mfma_f32_16x16x32_bf16 v[8:11], v[96:99], v[160:163], v[8:11]
	v_mfma_f32_16x16x32_bf16 v[40:43], v[164:167], v[160:163], v[40:43]
	v_mfma_f32_16x16x32_bf16 v[204:207], v[168:171], v[160:163], v[204:207]
	v_mfma_f32_16x16x32_bf16 v[104:107], v[172:175], v[160:163], v[104:107]
	ds_read_b128 v[196:199], v213 offset:14336
	global_load_dwordx4 v[92:95], v150, s[92:93] offset:1024
	s_add_u32 s84, s84, 0x800
	s_addc_u32 s85, s85, 0
	s_add_u32 s92, s92, 0x800
	s_addc_u32 s93, s93, 0
	s_waitcnt lgkmcnt(4)
	v_mfma_f32_16x16x32_bf16 v[12:15], v[96:99], v[176:179], v[12:15]
	v_mfma_f32_16x16x32_bf16 v[44:47], v[164:167], v[176:179], v[44:47]
	v_mfma_f32_16x16x32_bf16 v[208:211], v[168:171], v[176:179], v[208:211]
	v_mfma_f32_16x16x32_bf16 v[108:111], v[172:175], v[176:179], v[108:111]
	ds_read_b128 v[160:163], v212 offset:16384
	s_add_u32 m0, s1, 49152
	s_nop 0
	global_load_lds_dwordx4 v151, s[86:87]
	s_waitcnt lgkmcnt(4)
	v_mfma_f32_16x16x32_bf16 v[16:19], v[96:99], v[180:183], v[16:19]
	v_mfma_f32_16x16x32_bf16 v[48:51], v[164:167], v[180:183], v[48:51]
	v_mfma_f32_16x16x32_bf16 v[232:235], v[168:171], v[180:183], v[232:235]
	v_mfma_f32_16x16x32_bf16 v[112:115], v[172:175], v[180:183], v[112:115]
	ds_read_b128 v[176:179], v212 offset:18432
	s_add_u32 m0, s1, 53248
	s_nop 0
	global_load_lds_dwordx4 v156, s[86:87]
	s_waitcnt lgkmcnt(4)
	v_mfma_f32_16x16x32_bf16 v[20:23], v[96:99], v[188:191], v[20:23]
	v_mfma_f32_16x16x32_bf16 v[52:55], v[164:167], v[188:191], v[52:55]
	v_mfma_f32_16x16x32_bf16 v[236:239], v[168:171], v[188:191], v[236:239]
	v_mfma_f32_16x16x32_bf16 v[116:119], v[172:175], v[188:191], v[116:119]
	ds_read_b128 v[180:183], v212 offset:20480
	s_add_u32 m0, s1, 57344
	s_nop 0
	global_load_lds_dwordx4 v158, s[86:87]
	s_waitcnt lgkmcnt(4)
	v_mfma_f32_16x16x32_bf16 v[24:27], v[96:99], v[192:195], v[24:27]
	v_mfma_f32_16x16x32_bf16 v[56:59], v[164:167], v[192:195], v[56:59]
	v_mfma_f32_16x16x32_bf16 v[240:243], v[168:171], v[192:195], v[240:243]
	v_mfma_f32_16x16x32_bf16 v[120:123], v[172:175], v[192:195], v[120:123]
	ds_read_b128 v[188:191], v212 offset:22528
	s_add_u32 m0, s1, 61440
	s_nop 0
	global_load_lds_dwordx4 v159, s[86:87]
	s_add_u32 s86, s86, 128
	s_addc_u32 s87, s87, 0
	s_waitcnt lgkmcnt(4)
	v_mfma_f32_16x16x32_bf16 v[28:31], v[96:99], v[196:199], v[28:31]
	v_mfma_f32_16x16x32_bf16 v[60:63], v[164:167], v[196:199], v[60:63]
	v_mfma_f32_16x16x32_bf16 v[248:251], v[168:171], v[196:199], v[248:251]
	v_mfma_f32_16x16x32_bf16 v[124:127], v[172:175], v[196:199], v[124:127]
	s_waitcnt vmcnt(8)
	ds_read_b128 v[192:195], v212 offset:24576
	global_load_dwordx4 v[96:99], v142, s[84:85] offset:0
	s_waitcnt lgkmcnt(4)
	v_mfma_f32_16x16x32_bf16 v[0:3], v[64:67], v[160:163], v[0:3]
	v_mfma_f32_16x16x32_bf16 v[32:35], v[68:71], v[160:163], v[32:35]
	v_mfma_f32_16x16x32_bf16 v[144:147], v[72:75], v[160:163], v[144:147]
	v_mfma_f32_16x16x32_bf16 v[252:255], v[76:79], v[160:163], v[252:255]
	ds_read_b128 v[196:199], v212 offset:26624
	global_load_dwordx4 v[164:167], v150, s[84:85] offset:0
	s_waitcnt lgkmcnt(4)
	v_mfma_f32_16x16x32_bf16 v[4:7], v[64:67], v[176:179], v[4:7]
	v_mfma_f32_16x16x32_bf16 v[36:39], v[68:71], v[176:179], v[36:39]
	v_mfma_f32_16x16x32_bf16 v[184:187], v[72:75], v[176:179], v[184:187]
	v_mfma_f32_16x16x32_bf16 v[100:103], v[76:79], v[176:179], v[100:103]
	ds_read_b128 v[160:163], v212 offset:28672
	global_load_dwordx4 v[168:171], v142, s[92:93] offset:0
	s_waitcnt lgkmcnt(4)
	v_mfma_f32_16x16x32_bf16 v[8:11], v[64:67], v[180:183], v[8:11]
	v_mfma_f32_16x16x32_bf16 v[40:43], v[68:71], v[180:183], v[40:43]
	v_mfma_f32_16x16x32_bf16 v[204:207], v[72:75], v[180:183], v[204:207]
	v_mfma_f32_16x16x32_bf16 v[104:107], v[76:79], v[180:183], v[104:107]
	ds_read_b128 v[176:179], v212 offset:30720
	global_load_dwordx4 v[172:175], v150, s[92:93] offset:0
	s_waitcnt lgkmcnt(4)
	v_mfma_f32_16x16x32_bf16 v[12:15], v[64:67], v[188:191], v[12:15]
	v_mfma_f32_16x16x32_bf16 v[44:47], v[68:71], v[188:191], v[44:47]
	v_mfma_f32_16x16x32_bf16 v[208:211], v[72:75], v[188:191], v[208:211]
	v_mfma_f32_16x16x32_bf16 v[108:111], v[76:79], v[188:191], v[108:111]
	ds_read_b128 v[180:183], v213 offset:16384
	s_waitcnt lgkmcnt(4)
	v_mfma_f32_16x16x32_bf16 v[16:19], v[64:67], v[192:195], v[16:19]
	v_mfma_f32_16x16x32_bf16 v[48:51], v[68:71], v[192:195], v[48:51]
	v_mfma_f32_16x16x32_bf16 v[232:235], v[72:75], v[192:195], v[232:235]
	v_mfma_f32_16x16x32_bf16 v[112:115], v[76:79], v[192:195], v[112:115]
	ds_read_b128 v[188:191], v213 offset:18432
	s_waitcnt lgkmcnt(4)
	v_mfma_f32_16x16x32_bf16 v[20:23], v[64:67], v[196:199], v[20:23]
	v_mfma_f32_16x16x32_bf16 v[52:55], v[68:71], v[196:199], v[52:55]
	v_mfma_f32_16x16x32_bf16 v[236:239], v[72:75], v[196:199], v[236:239]
	v_mfma_f32_16x16x32_bf16 v[116:119], v[76:79], v[196:199], v[116:119]
	ds_read_b128 v[192:195], v213 offset:20480
	s_waitcnt lgkmcnt(4)
	v_mfma_f32_16x16x32_bf16 v[24:27], v[64:67], v[160:163], v[24:27]
	v_mfma_f32_16x16x32_bf16 v[56:59], v[68:71], v[160:163], v[56:59]
	v_mfma_f32_16x16x32_bf16 v[240:243], v[72:75], v[160:163], v[240:243]
	v_mfma_f32_16x16x32_bf16 v[120:123], v[76:79], v[160:163], v[120:123]
	ds_read_b128 v[196:199], v213 offset:22528
	s_waitcnt lgkmcnt(4)
	v_mfma_f32_16x16x32_bf16 v[28:31], v[64:67], v[176:179], v[28:31]
	v_mfma_f32_16x16x32_bf16 v[60:63], v[68:71], v[176:179], v[60:63]
	v_mfma_f32_16x16x32_bf16 v[248:251], v[72:75], v[176:179], v[248:251]
	v_mfma_f32_16x16x32_bf16 v[124:127], v[76:79], v[176:179], v[124:127]
	s_waitcnt vmcnt(16)
	s_barrier
	s_waitcnt vmcnt(8)
	ds_read_b128 v[160:163], v213 offset:24576
	global_load_dwordx4 v[64:67], v142, s[84:85] offset:1024
	s_waitcnt lgkmcnt(4)
	v_mfma_f32_16x16x32_bf16 v[0:3], v[80:83], v[180:183], v[0:3]
	v_mfma_f32_16x16x32_bf16 v[32:35], v[84:87], v[180:183], v[32:35]
	v_mfma_f32_16x16x32_bf16 v[144:147], v[88:91], v[180:183], v[144:147]
	v_mfma_f32_16x16x32_bf16 v[252:255], v[92:95], v[180:183], v[252:255]
	ds_read_b128 v[176:179], v213 offset:26624
	global_load_dwordx4 v[68:71], v150, s[84:85] offset:1024
	s_waitcnt lgkmcnt(4)
	v_mfma_f32_16x16x32_bf16 v[4:7], v[80:83], v[188:191], v[4:7]
	v_mfma_f32_16x16x32_bf16 v[36:39], v[84:87], v[188:191], v[36:39]
	v_mfma_f32_16x16x32_bf16 v[184:187], v[88:91], v[188:191], v[184:187]
	v_mfma_f32_16x16x32_bf16 v[100:103], v[92:95], v[188:191], v[100:103]
	ds_read_b128 v[180:183], v213 offset:28672
	global_load_dwordx4 v[72:75], v142, s[92:93] offset:1024
	s_waitcnt lgkmcnt(4)
	v_mfma_f32_16x16x32_bf16 v[8:11], v[80:83], v[192:195], v[8:11]
	v_mfma_f32_16x16x32_bf16 v[40:43], v[84:87], v[192:195], v[40:43]
	v_mfma_f32_16x16x32_bf16 v[204:207], v[88:91], v[192:195], v[204:207]
	v_mfma_f32_16x16x32_bf16 v[104:107], v[92:95], v[192:195], v[104:107]
	ds_read_b128 v[188:191], v213 offset:30720
	global_load_dwordx4 v[76:79], v150, s[92:93] offset:1024
	s_add_u32 s84, s84, 0x800
	s_addc_u32 s85, s85, 0
	s_add_u32 s92, s92, 0x800
	s_addc_u32 s93, s93, 0
	s_waitcnt lgkmcnt(4)
	v_mfma_f32_16x16x32_bf16 v[12:15], v[80:83], v[196:199], v[12:15]
	v_mfma_f32_16x16x32_bf16 v[44:47], v[84:87], v[196:199], v[44:47]
	v_mfma_f32_16x16x32_bf16 v[208:211], v[88:91], v[196:199], v[208:211]
	v_mfma_f32_16x16x32_bf16 v[108:111], v[92:95], v[196:199], v[108:111]
	ds_read_b128 v[192:195], v212 offset:32768
	s_add_u32 m0, s1, 0
	s_nop 0
	global_load_lds_dwordx4 v151, s[86:87]
	s_waitcnt lgkmcnt(4)
	v_mfma_f32_16x16x32_bf16 v[16:19], v[80:83], v[160:163], v[16:19]
	v_mfma_f32_16x16x32_bf16 v[48:51], v[84:87], v[160:163], v[48:51]
	v_mfma_f32_16x16x32_bf16 v[232:235], v[88:91], v[160:163], v[232:235]
	v_mfma_f32_16x16x32_bf16 v[112:115], v[92:95], v[160:163], v[112:115]
	ds_read_b128 v[196:199], v212 offset:34816
	s_add_u32 m0, s1, 4096
	s_nop 0
	global_load_lds_dwordx4 v156, s[86:87]
	s_waitcnt lgkmcnt(4)
	v_mfma_f32_16x16x32_bf16 v[20:23], v[80:83], v[176:179], v[20:23]
	v_mfma_f32_16x16x32_bf16 v[52:55], v[84:87], v[176:179], v[52:55]
	v_mfma_f32_16x16x32_bf16 v[236:239], v[88:91], v[176:179], v[236:239]
	v_mfma_f32_16x16x32_bf16 v[116:119], v[92:95], v[176:179], v[116:119]
	ds_read_b128 v[160:163], v212 offset:36864
	s_add_u32 m0, s1, 8192
	s_nop 0
	global_load_lds_dwordx4 v158, s[86:87]
	s_waitcnt lgkmcnt(4)
	v_mfma_f32_16x16x32_bf16 v[24:27], v[80:83], v[180:183], v[24:27]
	v_mfma_f32_16x16x32_bf16 v[56:59], v[84:87], v[180:183], v[56:59]
	v_mfma_f32_16x16x32_bf16 v[240:243], v[88:91], v[180:183], v[240:243]
	v_mfma_f32_16x16x32_bf16 v[120:123], v[92:95], v[180:183], v[120:123]
	ds_read_b128 v[176:179], v212 offset:38912
	s_add_u32 m0, s1, 12288
	s_nop 0
	global_load_lds_dwordx4 v159, s[86:87]
	s_add_u32 s86, s86, 128
	s_addc_u32 s87, s87, 0
	s_waitcnt lgkmcnt(4)
	v_mfma_f32_16x16x32_bf16 v[28:31], v[80:83], v[188:191], v[28:31]
	v_mfma_f32_16x16x32_bf16 v[60:63], v[84:87], v[188:191], v[60:63]
	v_mfma_f32_16x16x32_bf16 v[248:251], v[88:91], v[188:191], v[248:251]
	v_mfma_f32_16x16x32_bf16 v[124:127], v[92:95], v[188:191], v[124:127]
	s_waitcnt vmcnt(8)
	ds_read_b128 v[180:183], v212 offset:40960
	global_load_dwordx4 v[80:83], v142, s[84:85] offset:0
	s_waitcnt lgkmcnt(4)
	v_mfma_f32_16x16x32_bf16 v[0:3], v[96:99], v[192:195], v[0:3]
	v_mfma_f32_16x16x32_bf16 v[32:35], v[164:167], v[192:195], v[32:35]
	v_mfma_f32_16x16x32_bf16 v[144:147], v[168:171], v[192:195], v[144:147]
	v_mfma_f32_16x16x32_bf16 v[252:255], v[172:175], v[192:195], v[252:255]
	ds_read_b128 v[188:191], v212 offset:43008
	global_load_dwordx4 v[84:87], v150, s[84:85] offset:0
	s_waitcnt lgkmcnt(4)
	v_mfma_f32_16x16x32_bf16 v[4:7], v[96:99], v[196:199], v[4:7]
	v_mfma_f32_16x16x32_bf16 v[36:39], v[164:167], v[196:199], v[36:39]
	v_mfma_f32_16x16x32_bf16 v[184:187], v[168:171], v[196:199], v[184:187]
	v_mfma_f32_16x16x32_bf16 v[100:103], v[172:175], v[196:199], v[100:103]
	ds_read_b128 v[192:195], v212 offset:45056
	global_load_dwordx4 v[88:91], v142, s[92:93] offset:0
	s_waitcnt lgkmcnt(4)
	v_mfma_f32_16x16x32_bf16 v[8:11], v[96:99], v[160:163], v[8:11]
	v_mfma_f32_16x16x32_bf16 v[40:43], v[164:167], v[160:163], v[40:43]
	v_mfma_f32_16x16x32_bf16 v[204:207], v[168:171], v[160:163], v[204:207]
	v_mfma_f32_16x16x32_bf16 v[104:107], v[172:175], v[160:163], v[104:107]
	ds_read_b128 v[196:199], v212 offset:47104
	global_load_dwordx4 v[92:95], v150, s[92:93] offset:0
	s_waitcnt lgkmcnt(4)
	v_mfma_f32_16x16x32_bf16 v[12:15], v[96:99], v[176:179], v[12:15]
	v_mfma_f32_16x16x32_bf16 v[44:47], v[164:167], v[176:179], v[44:47]
	v_mfma_f32_16x16x32_bf16 v[208:211], v[168:171], v[176:179], v[208:211]
	v_mfma_f32_16x16x32_bf16 v[108:111], v[172:175], v[176:179], v[108:111]
	ds_read_b128 v[160:163], v213 offset:32768
	s_waitcnt lgkmcnt(4)
	v_mfma_f32_16x16x32_bf16 v[16:19], v[96:99], v[180:183], v[16:19]
	v_mfma_f32_16x16x32_bf16 v[48:51], v[164:167], v[180:183], v[48:51]
	v_mfma_f32_16x16x32_bf16 v[232:235], v[168:171], v[180:183], v[232:235]
	v_mfma_f32_16x16x32_bf16 v[112:115], v[172:175], v[180:183], v[112:115]
	ds_read_b128 v[176:179], v213 offset:34816
	s_waitcnt lgkmcnt(4)
	v_mfma_f32_16x16x32_bf16 v[20:23], v[96:99], v[188:191], v[20:23]
	v_mfma_f32_16x16x32_bf16 v[52:55], v[164:167], v[188:191], v[52:55]
	v_mfma_f32_16x16x32_bf16 v[236:239], v[168:171], v[188:191], v[236:239]
	v_mfma_f32_16x16x32_bf16 v[116:119], v[172:175], v[188:191], v[116:119]
	ds_read_b128 v[180:183], v213 offset:36864
	s_waitcnt lgkmcnt(4)
	v_mfma_f32_16x16x32_bf16 v[24:27], v[96:99], v[192:195], v[24:27]
	v_mfma_f32_16x16x32_bf16 v[56:59], v[164:167], v[192:195], v[56:59]
	v_mfma_f32_16x16x32_bf16 v[240:243], v[168:171], v[192:195], v[240:243]
	v_mfma_f32_16x16x32_bf16 v[120:123], v[172:175], v[192:195], v[120:123]
	ds_read_b128 v[188:191], v213 offset:38912
	s_waitcnt lgkmcnt(4)
	v_mfma_f32_16x16x32_bf16 v[28:31], v[96:99], v[196:199], v[28:31]
	v_mfma_f32_16x16x32_bf16 v[60:63], v[164:167], v[196:199], v[60:63]
	v_mfma_f32_16x16x32_bf16 v[248:251], v[168:171], v[196:199], v[248:251]
	v_mfma_f32_16x16x32_bf16 v[124:127], v[172:175], v[196:199], v[124:127]
	s_waitcnt vmcnt(16)
	s_barrier
	s_waitcnt vmcnt(8)
	ds_read_b128 v[192:195], v213 offset:40960
	global_load_dwordx4 v[96:99], v142, s[84:85] offset:1024
	s_waitcnt lgkmcnt(4)
	v_mfma_f32_16x16x32_bf16 v[0:3], v[64:67], v[160:163], v[0:3]
	v_mfma_f32_16x16x32_bf16 v[32:35], v[68:71], v[160:163], v[32:35]
	v_mfma_f32_16x16x32_bf16 v[144:147], v[72:75], v[160:163], v[144:147]
	v_mfma_f32_16x16x32_bf16 v[252:255], v[76:79], v[160:163], v[252:255]
	ds_read_b128 v[196:199], v213 offset:43008
	global_load_dwordx4 v[164:167], v150, s[84:85] offset:1024
	s_waitcnt lgkmcnt(4)
	v_mfma_f32_16x16x32_bf16 v[4:7], v[64:67], v[176:179], v[4:7]
	v_mfma_f32_16x16x32_bf16 v[36:39], v[68:71], v[176:179], v[36:39]
	v_mfma_f32_16x16x32_bf16 v[184:187], v[72:75], v[176:179], v[184:187]
	v_mfma_f32_16x16x32_bf16 v[100:103], v[76:79], v[176:179], v[100:103]
	ds_read_b128 v[160:163], v213 offset:45056
	global_load_dwordx4 v[168:171], v142, s[92:93] offset:1024
	s_waitcnt lgkmcnt(4)
	v_mfma_f32_16x16x32_bf16 v[8:11], v[64:67], v[180:183], v[8:11]
	v_mfma_f32_16x16x32_bf16 v[40:43], v[68:71], v[180:183], v[40:43]
	v_mfma_f32_16x16x32_bf16 v[204:207], v[72:75], v[180:183], v[204:207]
	v_mfma_f32_16x16x32_bf16 v[104:107], v[76:79], v[180:183], v[104:107]
	ds_read_b128 v[176:179], v213 offset:47104
	global_load_dwordx4 v[172:175], v150, s[92:93] offset:1024
	s_add_u32 s84, s84, 0x800
	s_addc_u32 s85, s85, 0
	s_add_u32 s92, s92, 0x800
	s_addc_u32 s93, s93, 0
	s_waitcnt lgkmcnt(4)
	v_mfma_f32_16x16x32_bf16 v[12:15], v[64:67], v[188:191], v[12:15]
	v_mfma_f32_16x16x32_bf16 v[44:47], v[68:71], v[188:191], v[44:47]
	v_mfma_f32_16x16x32_bf16 v[208:211], v[72:75], v[188:191], v[208:211]
	v_mfma_f32_16x16x32_bf16 v[108:111], v[76:79], v[188:191], v[108:111]
	ds_read_b128 v[180:183], v212 offset:49152
	s_add_u32 m0, s1, 16384
	s_nop 0
	global_load_lds_dwordx4 v151, s[86:87]
	s_waitcnt lgkmcnt(4)
	v_mfma_f32_16x16x32_bf16 v[16:19], v[64:67], v[192:195], v[16:19]
	v_mfma_f32_16x16x32_bf16 v[48:51], v[68:71], v[192:195], v[48:51]
	v_mfma_f32_16x16x32_bf16 v[232:235], v[72:75], v[192:195], v[232:235]
	v_mfma_f32_16x16x32_bf16 v[112:115], v[76:79], v[192:195], v[112:115]
	ds_read_b128 v[188:191], v212 offset:51200
	s_add_u32 m0, s1, 20480
	s_nop 0
	global_load_lds_dwordx4 v156, s[86:87]
	s_waitcnt lgkmcnt(4)
	v_mfma_f32_16x16x32_bf16 v[20:23], v[64:67], v[196:199], v[20:23]
	v_mfma_f32_16x16x32_bf16 v[52:55], v[68:71], v[196:199], v[52:55]
	v_mfma_f32_16x16x32_bf16 v[236:239], v[72:75], v[196:199], v[236:239]
	v_mfma_f32_16x16x32_bf16 v[116:119], v[76:79], v[196:199], v[116:119]
	ds_read_b128 v[192:195], v212 offset:53248
	s_add_u32 m0, s1, 24576
	s_nop 0
	global_load_lds_dwordx4 v158, s[86:87]
	s_waitcnt lgkmcnt(4)
	v_mfma_f32_16x16x32_bf16 v[24:27], v[64:67], v[160:163], v[24:27]
	v_mfma_f32_16x16x32_bf16 v[56:59], v[68:71], v[160:163], v[56:59]
	v_mfma_f32_16x16x32_bf16 v[240:243], v[72:75], v[160:163], v[240:243]
	v_mfma_f32_16x16x32_bf16 v[120:123], v[76:79], v[160:163], v[120:123]
	ds_read_b128 v[196:199], v212 offset:55296
	s_add_u32 m0, s1, 28672
	s_nop 0
	global_load_lds_dwordx4 v159, s[86:87]
	s_add_u32 s86, s86, 128
	s_addc_u32 s87, s87, 0
	s_waitcnt lgkmcnt(4)
	v_mfma_f32_16x16x32_bf16 v[28:31], v[64:67], v[176:179], v[28:31]
	v_mfma_f32_16x16x32_bf16 v[60:63], v[68:71], v[176:179], v[60:63]
	v_mfma_f32_16x16x32_bf16 v[248:251], v[72:75], v[176:179], v[248:251]
	v_mfma_f32_16x16x32_bf16 v[124:127], v[76:79], v[176:179], v[124:127]
	s_waitcnt vmcnt(8)
	ds_read_b128 v[160:163], v212 offset:57344
	global_load_dwordx4 v[64:67], v142, s[84:85] offset:0
	s_waitcnt lgkmcnt(4)
	v_mfma_f32_16x16x32_bf16 v[0:3], v[80:83], v[180:183], v[0:3]
	v_mfma_f32_16x16x32_bf16 v[32:35], v[84:87], v[180:183], v[32:35]
	v_mfma_f32_16x16x32_bf16 v[144:147], v[88:91], v[180:183], v[144:147]
	v_mfma_f32_16x16x32_bf16 v[252:255], v[92:95], v[180:183], v[252:255]
	ds_read_b128 v[176:179], v212 offset:59392
	global_load_dwordx4 v[68:71], v150, s[84:85] offset:0
	s_waitcnt lgkmcnt(4)
	v_mfma_f32_16x16x32_bf16 v[4:7], v[80:83], v[188:191], v[4:7]
	v_mfma_f32_16x16x32_bf16 v[36:39], v[84:87], v[188:191], v[36:39]
	v_mfma_f32_16x16x32_bf16 v[184:187], v[88:91], v[188:191], v[184:187]
	v_mfma_f32_16x16x32_bf16 v[100:103], v[92:95], v[188:191], v[100:103]
	ds_read_b128 v[180:183], v212 offset:61440
	global_load_dwordx4 v[72:75], v142, s[92:93] offset:0
	s_waitcnt lgkmcnt(4)
	v_mfma_f32_16x16x32_bf16 v[8:11], v[80:83], v[192:195], v[8:11]
	v_mfma_f32_16x16x32_bf16 v[40:43], v[84:87], v[192:195], v[40:43]
	v_mfma_f32_16x16x32_bf16 v[204:207], v[88:91], v[192:195], v[204:207]
	v_mfma_f32_16x16x32_bf16 v[104:107], v[92:95], v[192:195], v[104:107]
	ds_read_b128 v[188:191], v212 offset:63488
	global_load_dwordx4 v[76:79], v150, s[92:93] offset:0
	s_waitcnt lgkmcnt(4)
	v_mfma_f32_16x16x32_bf16 v[12:15], v[80:83], v[196:199], v[12:15]
	v_mfma_f32_16x16x32_bf16 v[44:47], v[84:87], v[196:199], v[44:47]
	v_mfma_f32_16x16x32_bf16 v[208:211], v[88:91], v[196:199], v[208:211]
	v_mfma_f32_16x16x32_bf16 v[108:111], v[92:95], v[196:199], v[108:111]
	ds_read_b128 v[192:195], v213 offset:49152
	s_waitcnt lgkmcnt(4)
	v_mfma_f32_16x16x32_bf16 v[16:19], v[80:83], v[160:163], v[16:19]
	v_mfma_f32_16x16x32_bf16 v[48:51], v[84:87], v[160:163], v[48:51]
	v_mfma_f32_16x16x32_bf16 v[232:235], v[88:91], v[160:163], v[232:235]
	v_mfma_f32_16x16x32_bf16 v[112:115], v[92:95], v[160:163], v[112:115]
	ds_read_b128 v[196:199], v213 offset:51200
	s_waitcnt lgkmcnt(4)
	v_mfma_f32_16x16x32_bf16 v[20:23], v[80:83], v[176:179], v[20:23]
	v_mfma_f32_16x16x32_bf16 v[52:55], v[84:87], v[176:179], v[52:55]
	v_mfma_f32_16x16x32_bf16 v[236:239], v[88:91], v[176:179], v[236:239]
	v_mfma_f32_16x16x32_bf16 v[116:119], v[92:95], v[176:179], v[116:119]
	ds_read_b128 v[160:163], v213 offset:53248
	s_waitcnt lgkmcnt(4)
	v_mfma_f32_16x16x32_bf16 v[24:27], v[80:83], v[180:183], v[24:27]
	v_mfma_f32_16x16x32_bf16 v[56:59], v[84:87], v[180:183], v[56:59]
	v_mfma_f32_16x16x32_bf16 v[240:243], v[88:91], v[180:183], v[240:243]
	v_mfma_f32_16x16x32_bf16 v[120:123], v[92:95], v[180:183], v[120:123]
	ds_read_b128 v[176:179], v213 offset:55296
	s_waitcnt lgkmcnt(4)
	v_mfma_f32_16x16x32_bf16 v[28:31], v[80:83], v[188:191], v[28:31]
	v_mfma_f32_16x16x32_bf16 v[60:63], v[84:87], v[188:191], v[60:63]
	v_mfma_f32_16x16x32_bf16 v[248:251], v[88:91], v[188:191], v[248:251]
	v_mfma_f32_16x16x32_bf16 v[124:127], v[92:95], v[188:191], v[124:127]
	s_waitcnt vmcnt(16)
	s_barrier
	s_waitcnt vmcnt(8)
	ds_read_b128 v[180:183], v213 offset:57344
	global_load_dwordx4 v[80:83], v142, s[84:85] offset:1024
	s_waitcnt lgkmcnt(4)
	v_mfma_f32_16x16x32_bf16 v[0:3], v[96:99], v[192:195], v[0:3]
	v_mfma_f32_16x16x32_bf16 v[32:35], v[164:167], v[192:195], v[32:35]
	v_mfma_f32_16x16x32_bf16 v[144:147], v[168:171], v[192:195], v[144:147]
	v_mfma_f32_16x16x32_bf16 v[252:255], v[172:175], v[192:195], v[252:255]
	ds_read_b128 v[188:191], v213 offset:59392
	global_load_dwordx4 v[84:87], v150, s[84:85] offset:1024
	s_waitcnt lgkmcnt(4)
	v_mfma_f32_16x16x32_bf16 v[4:7], v[96:99], v[196:199], v[4:7]
	v_mfma_f32_16x16x32_bf16 v[36:39], v[164:167], v[196:199], v[36:39]
	v_mfma_f32_16x16x32_bf16 v[184:187], v[168:171], v[196:199], v[184:187]
	v_mfma_f32_16x16x32_bf16 v[100:103], v[172:175], v[196:199], v[100:103]
	ds_read_b128 v[192:195], v213 offset:61440
	global_load_dwordx4 v[88:91], v142, s[92:93] offset:1024
	s_waitcnt lgkmcnt(4)
	v_mfma_f32_16x16x32_bf16 v[8:11], v[96:99], v[160:163], v[8:11]
	v_mfma_f32_16x16x32_bf16 v[40:43], v[164:167], v[160:163], v[40:43]
	v_mfma_f32_16x16x32_bf16 v[204:207], v[168:171], v[160:163], v[204:207]
	v_mfma_f32_16x16x32_bf16 v[104:107], v[172:175], v[160:163], v[104:107]
	ds_read_b128 v[196:199], v213 offset:63488
	global_load_dwordx4 v[92:95], v150, s[92:93] offset:1024
	s_add_u32 s84, s84, 0x800
	s_addc_u32 s85, s85, 0
	s_add_u32 s92, s92, 0x800
	s_addc_u32 s93, s93, 0
	s_waitcnt lgkmcnt(4)
	v_mfma_f32_16x16x32_bf16 v[12:15], v[96:99], v[176:179], v[12:15]
	v_mfma_f32_16x16x32_bf16 v[44:47], v[164:167], v[176:179], v[44:47]
	v_mfma_f32_16x16x32_bf16 v[208:211], v[168:171], v[176:179], v[208:211]
	v_mfma_f32_16x16x32_bf16 v[108:111], v[172:175], v[176:179], v[108:111]
	ds_read_b128 v[160:163], v212 offset:0
	s_add_u32 m0, s1, 32768
	s_nop 0
	global_load_lds_dwordx4 v151, s[86:87]
	s_waitcnt lgkmcnt(4)
	v_mfma_f32_16x16x32_bf16 v[16:19], v[96:99], v[180:183], v[16:19]
	v_mfma_f32_16x16x32_bf16 v[48:51], v[164:167], v[180:183], v[48:51]
	v_mfma_f32_16x16x32_bf16 v[232:235], v[168:171], v[180:183], v[232:235]
	v_mfma_f32_16x16x32_bf16 v[112:115], v[172:175], v[180:183], v[112:115]
	ds_read_b128 v[176:179], v212 offset:2048
	s_add_u32 m0, s1, 36864
	s_nop 0
	global_load_lds_dwordx4 v156, s[86:87]
	s_waitcnt lgkmcnt(4)
	v_mfma_f32_16x16x32_bf16 v[20:23], v[96:99], v[188:191], v[20:23]
	v_mfma_f32_16x16x32_bf16 v[52:55], v[164:167], v[188:191], v[52:55]
	v_mfma_f32_16x16x32_bf16 v[236:239], v[168:171], v[188:191], v[236:239]
	v_mfma_f32_16x16x32_bf16 v[116:119], v[172:175], v[188:191], v[116:119]
	ds_read_b128 v[180:183], v212 offset:4096
	s_add_u32 m0, s1, 40960
	s_nop 0
	global_load_lds_dwordx4 v158, s[86:87]
	s_waitcnt lgkmcnt(4)
	v_mfma_f32_16x16x32_bf16 v[24:27], v[96:99], v[192:195], v[24:27]
	v_mfma_f32_16x16x32_bf16 v[56:59], v[164:167], v[192:195], v[56:59]
	v_mfma_f32_16x16x32_bf16 v[240:243], v[168:171], v[192:195], v[240:243]
	v_mfma_f32_16x16x32_bf16 v[120:123], v[172:175], v[192:195], v[120:123]
	ds_read_b128 v[188:191], v212 offset:6144
	s_add_u32 m0, s1, 45056
	s_nop 0
	global_load_lds_dwordx4 v159, s[86:87]
	s_add_u32 s86, s86, 128
	s_addc_u32 s87, s87, 0
	s_waitcnt lgkmcnt(4)
	v_mfma_f32_16x16x32_bf16 v[28:31], v[96:99], v[196:199], v[28:31]
	v_mfma_f32_16x16x32_bf16 v[60:63], v[164:167], v[196:199], v[60:63]
	v_mfma_f32_16x16x32_bf16 v[248:251], v[168:171], v[196:199], v[248:251]
	v_mfma_f32_16x16x32_bf16 v[124:127], v[172:175], v[196:199], v[124:127]
	s_waitcnt vmcnt(8)
	ds_read_b128 v[192:195], v212 offset:8192
	global_load_dwordx4 v[96:99], v142, s[84:85] offset:0
	s_waitcnt lgkmcnt(4)
	v_mfma_f32_16x16x32_bf16 v[0:3], v[64:67], v[160:163], v[0:3]
	v_mfma_f32_16x16x32_bf16 v[32:35], v[68:71], v[160:163], v[32:35]
	v_mfma_f32_16x16x32_bf16 v[144:147], v[72:75], v[160:163], v[144:147]
	v_mfma_f32_16x16x32_bf16 v[252:255], v[76:79], v[160:163], v[252:255]
	ds_read_b128 v[196:199], v212 offset:10240
	global_load_dwordx4 v[164:167], v150, s[84:85] offset:0
	s_waitcnt lgkmcnt(4)
	v_mfma_f32_16x16x32_bf16 v[4:7], v[64:67], v[176:179], v[4:7]
	v_mfma_f32_16x16x32_bf16 v[36:39], v[68:71], v[176:179], v[36:39]
	v_mfma_f32_16x16x32_bf16 v[184:187], v[72:75], v[176:179], v[184:187]
	v_mfma_f32_16x16x32_bf16 v[100:103], v[76:79], v[176:179], v[100:103]
	ds_read_b128 v[160:163], v212 offset:12288
	global_load_dwordx4 v[168:171], v142, s[92:93] offset:0
	s_waitcnt lgkmcnt(4)
	v_mfma_f32_16x16x32_bf16 v[8:11], v[64:67], v[180:183], v[8:11]
	v_mfma_f32_16x16x32_bf16 v[40:43], v[68:71], v[180:183], v[40:43]
	v_mfma_f32_16x16x32_bf16 v[204:207], v[72:75], v[180:183], v[204:207]
	v_mfma_f32_16x16x32_bf16 v[104:107], v[76:79], v[180:183], v[104:107]
	ds_read_b128 v[176:179], v212 offset:14336
	global_load_dwordx4 v[172:175], v150, s[92:93] offset:0
	s_waitcnt lgkmcnt(4)
	v_mfma_f32_16x16x32_bf16 v[12:15], v[64:67], v[188:191], v[12:15]
	v_mfma_f32_16x16x32_bf16 v[44:47], v[68:71], v[188:191], v[44:47]
	v_mfma_f32_16x16x32_bf16 v[208:211], v[72:75], v[188:191], v[208:211]
	v_mfma_f32_16x16x32_bf16 v[108:111], v[76:79], v[188:191], v[108:111]
	ds_read_b128 v[180:183], v213 offset:0
	s_waitcnt lgkmcnt(4)
	v_mfma_f32_16x16x32_bf16 v[16:19], v[64:67], v[192:195], v[16:19]
	v_mfma_f32_16x16x32_bf16 v[48:51], v[68:71], v[192:195], v[48:51]
	v_mfma_f32_16x16x32_bf16 v[232:235], v[72:75], v[192:195], v[232:235]
	v_mfma_f32_16x16x32_bf16 v[112:115], v[76:79], v[192:195], v[112:115]
	ds_read_b128 v[188:191], v213 offset:2048
	s_waitcnt lgkmcnt(4)
	v_mfma_f32_16x16x32_bf16 v[20:23], v[64:67], v[196:199], v[20:23]
	v_mfma_f32_16x16x32_bf16 v[52:55], v[68:71], v[196:199], v[52:55]
	v_mfma_f32_16x16x32_bf16 v[236:239], v[72:75], v[196:199], v[236:239]
	v_mfma_f32_16x16x32_bf16 v[116:119], v[76:79], v[196:199], v[116:119]
	ds_read_b128 v[192:195], v213 offset:4096
	s_waitcnt lgkmcnt(4)
	v_mfma_f32_16x16x32_bf16 v[24:27], v[64:67], v[160:163], v[24:27]
	v_mfma_f32_16x16x32_bf16 v[56:59], v[68:71], v[160:163], v[56:59]
	v_mfma_f32_16x16x32_bf16 v[240:243], v[72:75], v[160:163], v[240:243]
	v_mfma_f32_16x16x32_bf16 v[120:123], v[76:79], v[160:163], v[120:123]
	ds_read_b128 v[196:199], v213 offset:6144
	s_waitcnt lgkmcnt(4)
	v_mfma_f32_16x16x32_bf16 v[28:31], v[64:67], v[176:179], v[28:31]
	v_mfma_f32_16x16x32_bf16 v[60:63], v[68:71], v[176:179], v[60:63]
	v_mfma_f32_16x16x32_bf16 v[248:251], v[72:75], v[176:179], v[248:251]
	v_mfma_f32_16x16x32_bf16 v[124:127], v[76:79], v[176:179], v[124:127]
	s_waitcnt vmcnt(16)
	s_barrier
	s_waitcnt vmcnt(8)
	ds_read_b128 v[160:163], v213 offset:8192
	global_load_dwordx4 v[64:67], v142, s[84:85] offset:1024
	s_waitcnt lgkmcnt(4)
	v_mfma_f32_16x16x32_bf16 v[0:3], v[80:83], v[180:183], v[0:3]
	v_mfma_f32_16x16x32_bf16 v[32:35], v[84:87], v[180:183], v[32:35]
	v_mfma_f32_16x16x32_bf16 v[144:147], v[88:91], v[180:183], v[144:147]
	v_mfma_f32_16x16x32_bf16 v[252:255], v[92:95], v[180:183], v[252:255]
	ds_read_b128 v[176:179], v213 offset:10240
	global_load_dwordx4 v[68:71], v150, s[84:85] offset:1024
	s_waitcnt lgkmcnt(4)
	v_mfma_f32_16x16x32_bf16 v[4:7], v[80:83], v[188:191], v[4:7]
	v_mfma_f32_16x16x32_bf16 v[36:39], v[84:87], v[188:191], v[36:39]
	v_mfma_f32_16x16x32_bf16 v[184:187], v[88:91], v[188:191], v[184:187]
	v_mfma_f32_16x16x32_bf16 v[100:103], v[92:95], v[188:191], v[100:103]
	ds_read_b128 v[180:183], v213 offset:12288
	global_load_dwordx4 v[72:75], v142, s[92:93] offset:1024
	s_waitcnt lgkmcnt(4)
	v_mfma_f32_16x16x32_bf16 v[8:11], v[80:83], v[192:195], v[8:11]
	v_mfma_f32_16x16x32_bf16 v[40:43], v[84:87], v[192:195], v[40:43]
	v_mfma_f32_16x16x32_bf16 v[204:207], v[88:91], v[192:195], v[204:207]
	v_mfma_f32_16x16x32_bf16 v[104:107], v[92:95], v[192:195], v[104:107]
	ds_read_b128 v[188:191], v213 offset:14336
	global_load_dwordx4 v[76:79], v150, s[92:93] offset:1024
	s_add_u32 s84, s84, 0x800
	s_addc_u32 s85, s85, 0
	s_add_u32 s92, s92, 0x800
	s_addc_u32 s93, s93, 0
	s_waitcnt lgkmcnt(4)
	v_mfma_f32_16x16x32_bf16 v[12:15], v[80:83], v[196:199], v[12:15]
	v_mfma_f32_16x16x32_bf16 v[44:47], v[84:87], v[196:199], v[44:47]
	v_mfma_f32_16x16x32_bf16 v[208:211], v[88:91], v[196:199], v[208:211]
	v_mfma_f32_16x16x32_bf16 v[108:111], v[92:95], v[196:199], v[108:111]
	ds_read_b128 v[192:195], v212 offset:16384
	s_add_u32 m0, s1, 49152
	s_nop 0
	global_load_lds_dwordx4 v151, s[86:87]
	s_waitcnt lgkmcnt(4)
	v_mfma_f32_16x16x32_bf16 v[16:19], v[80:83], v[160:163], v[16:19]
	v_mfma_f32_16x16x32_bf16 v[48:51], v[84:87], v[160:163], v[48:51]
	v_mfma_f32_16x16x32_bf16 v[232:235], v[88:91], v[160:163], v[232:235]
	v_mfma_f32_16x16x32_bf16 v[112:115], v[92:95], v[160:163], v[112:115]
	ds_read_b128 v[196:199], v212 offset:18432
	s_add_u32 m0, s1, 53248
	s_nop 0
	global_load_lds_dwordx4 v156, s[86:87]
	s_waitcnt lgkmcnt(4)
	v_mfma_f32_16x16x32_bf16 v[20:23], v[80:83], v[176:179], v[20:23]
	v_mfma_f32_16x16x32_bf16 v[52:55], v[84:87], v[176:179], v[52:55]
	v_mfma_f32_16x16x32_bf16 v[236:239], v[88:91], v[176:179], v[236:239]
	v_mfma_f32_16x16x32_bf16 v[116:119], v[92:95], v[176:179], v[116:119]
	ds_read_b128 v[160:163], v212 offset:20480
	s_add_u32 m0, s1, 57344
	s_nop 0
	global_load_lds_dwordx4 v158, s[86:87]
	s_waitcnt lgkmcnt(4)
	v_mfma_f32_16x16x32_bf16 v[24:27], v[80:83], v[180:183], v[24:27]
	v_mfma_f32_16x16x32_bf16 v[56:59], v[84:87], v[180:183], v[56:59]
	v_mfma_f32_16x16x32_bf16 v[240:243], v[88:91], v[180:183], v[240:243]
	v_mfma_f32_16x16x32_bf16 v[120:123], v[92:95], v[180:183], v[120:123]
	ds_read_b128 v[176:179], v212 offset:22528
	s_add_u32 m0, s1, 61440
	s_nop 0
	global_load_lds_dwordx4 v159, s[86:87]
	s_add_u32 s86, s86, 128
	s_addc_u32 s87, s87, 0
	s_waitcnt lgkmcnt(4)
	v_mfma_f32_16x16x32_bf16 v[28:31], v[80:83], v[188:191], v[28:31]
	v_mfma_f32_16x16x32_bf16 v[60:63], v[84:87], v[188:191], v[60:63]
	v_mfma_f32_16x16x32_bf16 v[248:251], v[88:91], v[188:191], v[248:251]
	v_mfma_f32_16x16x32_bf16 v[124:127], v[92:95], v[188:191], v[124:127]
	s_waitcnt vmcnt(8)
	ds_read_b128 v[180:183], v212 offset:24576
	global_load_dwordx4 v[80:83], v142, s[84:85] offset:0
	s_waitcnt lgkmcnt(4)
	v_mfma_f32_16x16x32_bf16 v[0:3], v[96:99], v[192:195], v[0:3]
	v_mfma_f32_16x16x32_bf16 v[32:35], v[164:167], v[192:195], v[32:35]
	v_mfma_f32_16x16x32_bf16 v[144:147], v[168:171], v[192:195], v[144:147]
	v_mfma_f32_16x16x32_bf16 v[252:255], v[172:175], v[192:195], v[252:255]
	ds_read_b128 v[188:191], v212 offset:26624
	global_load_dwordx4 v[84:87], v150, s[84:85] offset:0
	s_waitcnt lgkmcnt(4)
	v_mfma_f32_16x16x32_bf16 v[4:7], v[96:99], v[196:199], v[4:7]
	v_mfma_f32_16x16x32_bf16 v[36:39], v[164:167], v[196:199], v[36:39]
	v_mfma_f32_16x16x32_bf16 v[184:187], v[168:171], v[196:199], v[184:187]
	v_mfma_f32_16x16x32_bf16 v[100:103], v[172:175], v[196:199], v[100:103]
	ds_read_b128 v[192:195], v212 offset:28672
	global_load_dwordx4 v[88:91], v142, s[92:93] offset:0
	s_waitcnt lgkmcnt(4)
	v_mfma_f32_16x16x32_bf16 v[8:11], v[96:99], v[160:163], v[8:11]
	v_mfma_f32_16x16x32_bf16 v[40:43], v[164:167], v[160:163], v[40:43]
	v_mfma_f32_16x16x32_bf16 v[204:207], v[168:171], v[160:163], v[204:207]
	v_mfma_f32_16x16x32_bf16 v[104:107], v[172:175], v[160:163], v[104:107]
	ds_read_b128 v[196:199], v212 offset:30720
	global_load_dwordx4 v[92:95], v150, s[92:93] offset:0
	s_waitcnt lgkmcnt(4)
	v_mfma_f32_16x16x32_bf16 v[12:15], v[96:99], v[176:179], v[12:15]
	v_mfma_f32_16x16x32_bf16 v[44:47], v[164:167], v[176:179], v[44:47]
	v_mfma_f32_16x16x32_bf16 v[208:211], v[168:171], v[176:179], v[208:211]
	v_mfma_f32_16x16x32_bf16 v[108:111], v[172:175], v[176:179], v[108:111]
	ds_read_b128 v[160:163], v213 offset:16384
	s_waitcnt lgkmcnt(4)
	v_mfma_f32_16x16x32_bf16 v[16:19], v[96:99], v[180:183], v[16:19]
	v_mfma_f32_16x16x32_bf16 v[48:51], v[164:167], v[180:183], v[48:51]
	v_mfma_f32_16x16x32_bf16 v[232:235], v[168:171], v[180:183], v[232:235]
	v_mfma_f32_16x16x32_bf16 v[112:115], v[172:175], v[180:183], v[112:115]
	ds_read_b128 v[176:179], v213 offset:18432
	s_waitcnt lgkmcnt(4)
	v_mfma_f32_16x16x32_bf16 v[20:23], v[96:99], v[188:191], v[20:23]
	v_mfma_f32_16x16x32_bf16 v[52:55], v[164:167], v[188:191], v[52:55]
	v_mfma_f32_16x16x32_bf16 v[236:239], v[168:171], v[188:191], v[236:239]
	v_mfma_f32_16x16x32_bf16 v[116:119], v[172:175], v[188:191], v[116:119]
	ds_read_b128 v[180:183], v213 offset:20480
	s_waitcnt lgkmcnt(4)
	v_mfma_f32_16x16x32_bf16 v[24:27], v[96:99], v[192:195], v[24:27]
	v_mfma_f32_16x16x32_bf16 v[56:59], v[164:167], v[192:195], v[56:59]
	v_mfma_f32_16x16x32_bf16 v[240:243], v[168:171], v[192:195], v[240:243]
	v_mfma_f32_16x16x32_bf16 v[120:123], v[172:175], v[192:195], v[120:123]
	ds_read_b128 v[188:191], v213 offset:22528
	s_waitcnt lgkmcnt(4)
	v_mfma_f32_16x16x32_bf16 v[28:31], v[96:99], v[196:199], v[28:31]
	v_mfma_f32_16x16x32_bf16 v[60:63], v[164:167], v[196:199], v[60:63]
	v_mfma_f32_16x16x32_bf16 v[248:251], v[168:171], v[196:199], v[248:251]
	v_mfma_f32_16x16x32_bf16 v[124:127], v[172:175], v[196:199], v[124:127]
	s_waitcnt vmcnt(16)
	s_barrier
	s_waitcnt vmcnt(8)
	ds_read_b128 v[192:195], v213 offset:24576
	global_load_dwordx4 v[96:99], v142, s[84:85] offset:1024
	s_waitcnt lgkmcnt(4)
	v_mfma_f32_16x16x32_bf16 v[0:3], v[64:67], v[160:163], v[0:3]
	v_mfma_f32_16x16x32_bf16 v[32:35], v[68:71], v[160:163], v[32:35]
	v_mfma_f32_16x16x32_bf16 v[144:147], v[72:75], v[160:163], v[144:147]
	v_mfma_f32_16x16x32_bf16 v[252:255], v[76:79], v[160:163], v[252:255]
	ds_read_b128 v[196:199], v213 offset:26624
	global_load_dwordx4 v[164:167], v150, s[84:85] offset:1024
	s_waitcnt lgkmcnt(4)
	v_mfma_f32_16x16x32_bf16 v[4:7], v[64:67], v[176:179], v[4:7]
	v_mfma_f32_16x16x32_bf16 v[36:39], v[68:71], v[176:179], v[36:39]
	v_mfma_f32_16x16x32_bf16 v[184:187], v[72:75], v[176:179], v[184:187]
	v_mfma_f32_16x16x32_bf16 v[100:103], v[76:79], v[176:179], v[100:103]
	ds_read_b128 v[160:163], v213 offset:28672
	global_load_dwordx4 v[168:171], v142, s[92:93] offset:1024
	s_waitcnt lgkmcnt(4)
	v_mfma_f32_16x16x32_bf16 v[8:11], v[64:67], v[180:183], v[8:11]
	v_mfma_f32_16x16x32_bf16 v[40:43], v[68:71], v[180:183], v[40:43]
	v_mfma_f32_16x16x32_bf16 v[204:207], v[72:75], v[180:183], v[204:207]
	v_mfma_f32_16x16x32_bf16 v[104:107], v[76:79], v[180:183], v[104:107]
	ds_read_b128 v[176:179], v213 offset:30720
	global_load_dwordx4 v[172:175], v150, s[92:93] offset:1024
	s_add_u32 s84, s84, 0x800
	s_addc_u32 s85, s85, 0
	s_add_u32 s92, s92, 0x800
	s_addc_u32 s93, s93, 0
	s_waitcnt lgkmcnt(4)
	v_mfma_f32_16x16x32_bf16 v[12:15], v[64:67], v[188:191], v[12:15]
	v_mfma_f32_16x16x32_bf16 v[44:47], v[68:71], v[188:191], v[44:47]
	v_mfma_f32_16x16x32_bf16 v[208:211], v[72:75], v[188:191], v[208:211]
	v_mfma_f32_16x16x32_bf16 v[108:111], v[76:79], v[188:191], v[108:111]
	ds_read_b128 v[180:183], v212 offset:32768
	s_waitcnt lgkmcnt(4)
	v_mfma_f32_16x16x32_bf16 v[16:19], v[64:67], v[192:195], v[16:19]
	v_mfma_f32_16x16x32_bf16 v[48:51], v[68:71], v[192:195], v[48:51]
	v_mfma_f32_16x16x32_bf16 v[232:235], v[72:75], v[192:195], v[232:235]
	v_mfma_f32_16x16x32_bf16 v[112:115], v[76:79], v[192:195], v[112:115]
	ds_read_b128 v[188:191], v212 offset:34816
	s_waitcnt lgkmcnt(4)
	v_mfma_f32_16x16x32_bf16 v[20:23], v[64:67], v[196:199], v[20:23]
	v_mfma_f32_16x16x32_bf16 v[52:55], v[68:71], v[196:199], v[52:55]
	v_mfma_f32_16x16x32_bf16 v[236:239], v[72:75], v[196:199], v[236:239]
	v_mfma_f32_16x16x32_bf16 v[116:119], v[76:79], v[196:199], v[116:119]
	ds_read_b128 v[192:195], v212 offset:36864
	s_waitcnt lgkmcnt(4)
	v_mfma_f32_16x16x32_bf16 v[24:27], v[64:67], v[160:163], v[24:27]
	v_mfma_f32_16x16x32_bf16 v[56:59], v[68:71], v[160:163], v[56:59]
	v_mfma_f32_16x16x32_bf16 v[240:243], v[72:75], v[160:163], v[240:243]
	v_mfma_f32_16x16x32_bf16 v[120:123], v[76:79], v[160:163], v[120:123]
	ds_read_b128 v[196:199], v212 offset:38912
	s_waitcnt lgkmcnt(4)
	v_mfma_f32_16x16x32_bf16 v[28:31], v[64:67], v[176:179], v[28:31]
	v_mfma_f32_16x16x32_bf16 v[60:63], v[68:71], v[176:179], v[60:63]
	v_mfma_f32_16x16x32_bf16 v[248:251], v[72:75], v[176:179], v[248:251]
	v_mfma_f32_16x16x32_bf16 v[124:127], v[76:79], v[176:179], v[124:127]
	s_waitcnt vmcnt(4)
	ds_read_b128 v[160:163], v212 offset:40960
	global_load_dwordx4 v[64:67], v142, s[84:85] offset:0
	s_waitcnt lgkmcnt(4)
	v_mfma_f32_16x16x32_bf16 v[0:3], v[80:83], v[180:183], v[0:3]
	v_mfma_f32_16x16x32_bf16 v[32:35], v[84:87], v[180:183], v[32:35]
	v_mfma_f32_16x16x32_bf16 v[144:147], v[88:91], v[180:183], v[144:147]
	v_mfma_f32_16x16x32_bf16 v[252:255], v[92:95], v[180:183], v[252:255]
	ds_read_b128 v[176:179], v212 offset:43008
	global_load_dwordx4 v[68:71], v150, s[84:85] offset:0
	s_waitcnt lgkmcnt(4)
	v_mfma_f32_16x16x32_bf16 v[4:7], v[80:83], v[188:191], v[4:7]
	v_mfma_f32_16x16x32_bf16 v[36:39], v[84:87], v[188:191], v[36:39]
	v_mfma_f32_16x16x32_bf16 v[184:187], v[88:91], v[188:191], v[184:187]
	v_mfma_f32_16x16x32_bf16 v[100:103], v[92:95], v[188:191], v[100:103]
	ds_read_b128 v[180:183], v212 offset:45056
	global_load_dwordx4 v[72:75], v142, s[92:93] offset:0
	s_waitcnt lgkmcnt(4)
	v_mfma_f32_16x16x32_bf16 v[8:11], v[80:83], v[192:195], v[8:11]
	v_mfma_f32_16x16x32_bf16 v[40:43], v[84:87], v[192:195], v[40:43]
	v_mfma_f32_16x16x32_bf16 v[204:207], v[88:91], v[192:195], v[204:207]
	v_mfma_f32_16x16x32_bf16 v[104:107], v[92:95], v[192:195], v[104:107]
	ds_read_b128 v[188:191], v212 offset:47104
	global_load_dwordx4 v[76:79], v150, s[92:93] offset:0
	s_waitcnt lgkmcnt(4)
	v_mfma_f32_16x16x32_bf16 v[12:15], v[80:83], v[196:199], v[12:15]
	v_mfma_f32_16x16x32_bf16 v[44:47], v[84:87], v[196:199], v[44:47]
	v_mfma_f32_16x16x32_bf16 v[208:211], v[88:91], v[196:199], v[208:211]
	v_mfma_f32_16x16x32_bf16 v[108:111], v[92:95], v[196:199], v[108:111]
	ds_read_b128 v[192:195], v213 offset:32768
	s_waitcnt lgkmcnt(4)
	v_mfma_f32_16x16x32_bf16 v[16:19], v[80:83], v[160:163], v[16:19]
	v_mfma_f32_16x16x32_bf16 v[48:51], v[84:87], v[160:163], v[48:51]
	v_mfma_f32_16x16x32_bf16 v[232:235], v[88:91], v[160:163], v[232:235]
	v_mfma_f32_16x16x32_bf16 v[112:115], v[92:95], v[160:163], v[112:115]
	ds_read_b128 v[196:199], v213 offset:34816
	s_waitcnt lgkmcnt(4)
	v_mfma_f32_16x16x32_bf16 v[20:23], v[80:83], v[176:179], v[20:23]
	v_mfma_f32_16x16x32_bf16 v[52:55], v[84:87], v[176:179], v[52:55]
	v_mfma_f32_16x16x32_bf16 v[236:239], v[88:91], v[176:179], v[236:239]
	v_mfma_f32_16x16x32_bf16 v[116:119], v[92:95], v[176:179], v[116:119]
	ds_read_b128 v[160:163], v213 offset:36864
	s_waitcnt lgkmcnt(4)
	v_mfma_f32_16x16x32_bf16 v[24:27], v[80:83], v[180:183], v[24:27]
	v_mfma_f32_16x16x32_bf16 v[56:59], v[84:87], v[180:183], v[56:59]
	v_mfma_f32_16x16x32_bf16 v[240:243], v[88:91], v[180:183], v[240:243]
	v_mfma_f32_16x16x32_bf16 v[120:123], v[92:95], v[180:183], v[120:123]
	ds_read_b128 v[176:179], v213 offset:38912
	s_waitcnt lgkmcnt(4)
	v_mfma_f32_16x16x32_bf16 v[28:31], v[80:83], v[188:191], v[28:31]
	v_mfma_f32_16x16x32_bf16 v[60:63], v[84:87], v[188:191], v[60:63]
	v_mfma_f32_16x16x32_bf16 v[248:251], v[88:91], v[188:191], v[248:251]
	v_mfma_f32_16x16x32_bf16 v[124:127], v[92:95], v[188:191], v[124:127]
	s_waitcnt vmcnt(12)
	s_barrier
	s_waitcnt vmcnt(4)
	ds_read_b128 v[180:183], v213 offset:40960
	global_load_dwordx4 v[80:83], v142, s[84:85] offset:1024
	s_waitcnt lgkmcnt(4)
	v_mfma_f32_16x16x32_bf16 v[0:3], v[96:99], v[192:195], v[0:3]
	v_mfma_f32_16x16x32_bf16 v[32:35], v[164:167], v[192:195], v[32:35]
	v_mfma_f32_16x16x32_bf16 v[144:147], v[168:171], v[192:195], v[144:147]
	v_mfma_f32_16x16x32_bf16 v[252:255], v[172:175], v[192:195], v[252:255]
	ds_read_b128 v[188:191], v213 offset:43008
	global_load_dwordx4 v[84:87], v150, s[84:85] offset:1024
	s_waitcnt lgkmcnt(4)
	v_mfma_f32_16x16x32_bf16 v[4:7], v[96:99], v[196:199], v[4:7]
	v_mfma_f32_16x16x32_bf16 v[36:39], v[164:167], v[196:199], v[36:39]
	v_mfma_f32_16x16x32_bf16 v[184:187], v[168:171], v[196:199], v[184:187]
	v_mfma_f32_16x16x32_bf16 v[100:103], v[172:175], v[196:199], v[100:103]
	ds_read_b128 v[192:195], v213 offset:45056
	global_load_dwordx4 v[88:91], v142, s[92:93] offset:1024
	s_waitcnt lgkmcnt(4)
	v_mfma_f32_16x16x32_bf16 v[8:11], v[96:99], v[160:163], v[8:11]
	v_mfma_f32_16x16x32_bf16 v[40:43], v[164:167], v[160:163], v[40:43]
	v_mfma_f32_16x16x32_bf16 v[204:207], v[168:171], v[160:163], v[204:207]
	v_mfma_f32_16x16x32_bf16 v[104:107], v[172:175], v[160:163], v[104:107]
	ds_read_b128 v[196:199], v213 offset:47104
	global_load_dwordx4 v[92:95], v150, s[92:93] offset:1024
	s_add_u32 s84, s84, 0x800
	s_addc_u32 s85, s85, 0
	s_add_u32 s92, s92, 0x800
	s_addc_u32 s93, s93, 0
	s_waitcnt lgkmcnt(4)
	v_mfma_f32_16x16x32_bf16 v[12:15], v[96:99], v[176:179], v[12:15]
	v_mfma_f32_16x16x32_bf16 v[44:47], v[164:167], v[176:179], v[44:47]
	v_mfma_f32_16x16x32_bf16 v[208:211], v[168:171], v[176:179], v[208:211]
	v_mfma_f32_16x16x32_bf16 v[108:111], v[172:175], v[176:179], v[108:111]
	ds_read_b128 v[160:163], v212 offset:49152
	s_waitcnt lgkmcnt(4)
	v_mfma_f32_16x16x32_bf16 v[16:19], v[96:99], v[180:183], v[16:19]
	v_mfma_f32_16x16x32_bf16 v[48:51], v[164:167], v[180:183], v[48:51]
	v_mfma_f32_16x16x32_bf16 v[232:235], v[168:171], v[180:183], v[232:235]
	v_mfma_f32_16x16x32_bf16 v[112:115], v[172:175], v[180:183], v[112:115]
	ds_read_b128 v[176:179], v212 offset:51200
	s_waitcnt lgkmcnt(4)
	v_mfma_f32_16x16x32_bf16 v[20:23], v[96:99], v[188:191], v[20:23]
	v_mfma_f32_16x16x32_bf16 v[52:55], v[164:167], v[188:191], v[52:55]
	v_mfma_f32_16x16x32_bf16 v[236:239], v[168:171], v[188:191], v[236:239]
	v_mfma_f32_16x16x32_bf16 v[116:119], v[172:175], v[188:191], v[116:119]
	ds_read_b128 v[180:183], v212 offset:53248
	s_waitcnt lgkmcnt(4)
	v_mfma_f32_16x16x32_bf16 v[24:27], v[96:99], v[192:195], v[24:27]
	v_mfma_f32_16x16x32_bf16 v[56:59], v[164:167], v[192:195], v[56:59]
	v_mfma_f32_16x16x32_bf16 v[240:243], v[168:171], v[192:195], v[240:243]
	v_mfma_f32_16x16x32_bf16 v[120:123], v[172:175], v[192:195], v[120:123]
	ds_read_b128 v[188:191], v212 offset:55296
	s_waitcnt lgkmcnt(4)
	v_mfma_f32_16x16x32_bf16 v[28:31], v[96:99], v[196:199], v[28:31]
	v_mfma_f32_16x16x32_bf16 v[60:63], v[164:167], v[196:199], v[60:63]
	v_mfma_f32_16x16x32_bf16 v[248:251], v[168:171], v[196:199], v[248:251]
	v_mfma_f32_16x16x32_bf16 v[124:127], v[172:175], v[196:199], v[124:127]
	s_waitcnt vmcnt(4)
	ds_read_b128 v[192:195], v212 offset:57344
	s_waitcnt lgkmcnt(4)
	v_mfma_f32_16x16x32_bf16 v[0:3], v[64:67], v[160:163], v[0:3]
	v_mfma_f32_16x16x32_bf16 v[32:35], v[68:71], v[160:163], v[32:35]
	v_mfma_f32_16x16x32_bf16 v[144:147], v[72:75], v[160:163], v[144:147]
	v_mfma_f32_16x16x32_bf16 v[252:255], v[76:79], v[160:163], v[252:255]
	ds_read_b128 v[196:199], v212 offset:59392
	s_waitcnt lgkmcnt(4)
	v_mfma_f32_16x16x32_bf16 v[4:7], v[64:67], v[176:179], v[4:7]
	v_mfma_f32_16x16x32_bf16 v[36:39], v[68:71], v[176:179], v[36:39]
	v_mfma_f32_16x16x32_bf16 v[184:187], v[72:75], v[176:179], v[184:187]
	v_mfma_f32_16x16x32_bf16 v[100:103], v[76:79], v[176:179], v[100:103]
	ds_read_b128 v[160:163], v212 offset:61440
	s_waitcnt lgkmcnt(4)
	v_mfma_f32_16x16x32_bf16 v[8:11], v[64:67], v[180:183], v[8:11]
	v_mfma_f32_16x16x32_bf16 v[40:43], v[68:71], v[180:183], v[40:43]
	v_mfma_f32_16x16x32_bf16 v[204:207], v[72:75], v[180:183], v[204:207]
	v_mfma_f32_16x16x32_bf16 v[104:107], v[76:79], v[180:183], v[104:107]
	ds_read_b128 v[176:179], v212 offset:63488
	s_waitcnt lgkmcnt(4)
	v_mfma_f32_16x16x32_bf16 v[12:15], v[64:67], v[188:191], v[12:15]
	v_mfma_f32_16x16x32_bf16 v[44:47], v[68:71], v[188:191], v[44:47]
	v_mfma_f32_16x16x32_bf16 v[208:211], v[72:75], v[188:191], v[208:211]
	v_mfma_f32_16x16x32_bf16 v[108:111], v[76:79], v[188:191], v[108:111]
	ds_read_b128 v[180:183], v213 offset:49152
	s_waitcnt lgkmcnt(4)
	v_mfma_f32_16x16x32_bf16 v[16:19], v[64:67], v[192:195], v[16:19]
	v_mfma_f32_16x16x32_bf16 v[48:51], v[68:71], v[192:195], v[48:51]
	v_mfma_f32_16x16x32_bf16 v[232:235], v[72:75], v[192:195], v[232:235]
	v_mfma_f32_16x16x32_bf16 v[112:115], v[76:79], v[192:195], v[112:115]
	ds_read_b128 v[188:191], v213 offset:51200
	s_waitcnt lgkmcnt(4)
	v_mfma_f32_16x16x32_bf16 v[20:23], v[64:67], v[196:199], v[20:23]
	v_mfma_f32_16x16x32_bf16 v[52:55], v[68:71], v[196:199], v[52:55]
	v_mfma_f32_16x16x32_bf16 v[236:239], v[72:75], v[196:199], v[236:239]
	v_mfma_f32_16x16x32_bf16 v[116:119], v[76:79], v[196:199], v[116:119]
	ds_read_b128 v[192:195], v213 offset:53248
	s_waitcnt lgkmcnt(4)
	v_mfma_f32_16x16x32_bf16 v[24:27], v[64:67], v[160:163], v[24:27]
	v_mfma_f32_16x16x32_bf16 v[56:59], v[68:71], v[160:163], v[56:59]
	v_mfma_f32_16x16x32_bf16 v[240:243], v[72:75], v[160:163], v[240:243]
	v_mfma_f32_16x16x32_bf16 v[120:123], v[76:79], v[160:163], v[120:123]
	ds_read_b128 v[196:199], v213 offset:55296
	s_waitcnt lgkmcnt(4)
	v_mfma_f32_16x16x32_bf16 v[28:31], v[64:67], v[176:179], v[28:31]
	v_mfma_f32_16x16x32_bf16 v[60:63], v[68:71], v[176:179], v[60:63]
	v_mfma_f32_16x16x32_bf16 v[248:251], v[72:75], v[176:179], v[248:251]
	v_mfma_f32_16x16x32_bf16 v[124:127], v[76:79], v[176:179], v[124:127]
	s_waitcnt vmcnt(0)
	ds_read_b128 v[160:163], v213 offset:57344
	s_waitcnt lgkmcnt(4)
	v_mfma_f32_16x16x32_bf16 v[0:3], v[80:83], v[180:183], v[0:3]
	v_mfma_f32_16x16x32_bf16 v[32:35], v[84:87], v[180:183], v[32:35]
	v_mfma_f32_16x16x32_bf16 v[144:147], v[88:91], v[180:183], v[144:147]
	v_mfma_f32_16x16x32_bf16 v[252:255], v[92:95], v[180:183], v[252:255]
	ds_read_b128 v[176:179], v213 offset:59392
	s_waitcnt lgkmcnt(4)
	v_mfma_f32_16x16x32_bf16 v[4:7], v[80:83], v[188:191], v[4:7]
	v_mfma_f32_16x16x32_bf16 v[36:39], v[84:87], v[188:191], v[36:39]
	v_mfma_f32_16x16x32_bf16 v[184:187], v[88:91], v[188:191], v[184:187]
	v_mfma_f32_16x16x32_bf16 v[100:103], v[92:95], v[188:191], v[100:103]
	ds_read_b128 v[180:183], v213 offset:61440
	s_waitcnt lgkmcnt(4)
	v_mfma_f32_16x16x32_bf16 v[8:11], v[80:83], v[192:195], v[8:11]
	v_mfma_f32_16x16x32_bf16 v[40:43], v[84:87], v[192:195], v[40:43]
	v_mfma_f32_16x16x32_bf16 v[204:207], v[88:91], v[192:195], v[204:207]
	v_mfma_f32_16x16x32_bf16 v[104:107], v[92:95], v[192:195], v[104:107]
	ds_read_b128 v[188:191], v213 offset:63488
	s_waitcnt lgkmcnt(4)
	v_mfma_f32_16x16x32_bf16 v[12:15], v[80:83], v[196:199], v[12:15]
	v_mfma_f32_16x16x32_bf16 v[44:47], v[84:87], v[196:199], v[44:47]
	v_mfma_f32_16x16x32_bf16 v[208:211], v[88:91], v[196:199], v[208:211]
	v_mfma_f32_16x16x32_bf16 v[108:111], v[92:95], v[196:199], v[108:111]
	s_waitcnt lgkmcnt(3)
	v_mfma_f32_16x16x32_bf16 v[16:19], v[80:83], v[160:163], v[16:19]
	v_mfma_f32_16x16x32_bf16 v[48:51], v[84:87], v[160:163], v[48:51]
	v_mfma_f32_16x16x32_bf16 v[232:235], v[88:91], v[160:163], v[232:235]
	v_mfma_f32_16x16x32_bf16 v[112:115], v[92:95], v[160:163], v[112:115]
	s_waitcnt lgkmcnt(2)
	v_mfma_f32_16x16x32_bf16 v[20:23], v[80:83], v[176:179], v[20:23]
	v_mfma_f32_16x16x32_bf16 v[52:55], v[84:87], v[176:179], v[52:55]
	v_mfma_f32_16x16x32_bf16 v[236:239], v[88:91], v[176:179], v[236:239]
	v_mfma_f32_16x16x32_bf16 v[116:119], v[92:95], v[176:179], v[116:119]
	s_waitcnt lgkmcnt(1)
	v_mfma_f32_16x16x32_bf16 v[24:27], v[80:83], v[180:183], v[24:27]
	v_mfma_f32_16x16x32_bf16 v[56:59], v[84:87], v[180:183], v[56:59]
	v_mfma_f32_16x16x32_bf16 v[240:243], v[88:91], v[180:183], v[240:243]
	v_mfma_f32_16x16x32_bf16 v[120:123], v[92:95], v[180:183], v[120:123]
	s_waitcnt lgkmcnt(0)
	v_mfma_f32_16x16x32_bf16 v[28:31], v[80:83], v[188:191], v[28:31]
	v_mfma_f32_16x16x32_bf16 v[60:63], v[84:87], v[188:191], v[60:63]
	v_mfma_f32_16x16x32_bf16 v[248:251], v[88:91], v[188:191], v[248:251]
	v_mfma_f32_16x16x32_bf16 v[124:127], v[92:95], v[188:191], v[124:127]
	s_nop 7
	s_nop 7
	s_waitcnt vmcnt(0) lgkmcnt(0)
	s_setprio 0
	s_barrier
	v_mov_b32_e32 v150, v100
	v_mov_b32_e32 v151, v101
	v_mov_b32_e32 v156, v102
	v_mov_b32_e32 v158, v103
	v_mov_b32_e32 v159, v104
	v_mov_b32_e32 v160, v105
	v_mov_b32_e32 v183, v106
	v_mov_b32_e32 v188, v107
	v_mov_b32_e32 v189, v108
	v_mov_b32_e32 v212, v109
	v_mov_b32_e32 v213, v110
	v_mov_b32_e32 v214, v111
	v_mov_b32_e32 v216, v112
	v_mov_b32_e32 v218, v113
	v_mov_b32_e32 v220, v114
	v_mov_b32_e32 v222, v115
	v_mov_b32_e32 v224, v116
	v_mov_b32_e32 v226, v117
	v_mov_b32_e32 v228, v118
	v_mov_b32_e32 v230, v119
	v_mov_b32_e32 v231, v120
	v_mov_b32_e32 v244, v121
	v_mov_b32_e32 v245, v122
	ds_write_b32 v140, v123 offset:40960
	ds_write_b32 v140, v124 offset:41984
	ds_write_b32 v140, v125 offset:43008
	ds_write_b32 v140, v126 offset:44032
	ds_write_b32 v140, v127 offset:45056
	v_lshlrev_b32_e32 v64, 13, v135
	v_lshl_add_u32 v65, v134, 3, v138
	v_lshl_or_b32 v66, v134, 11, v64
	v_lshlrev_b32_e32 v68, 5, v138
	v_or3_b32 v161, v64, v137, v68
	v_lshl_or_b32 v162, v65, 2, v66
	v_add_u32_e32 v68, 0x60, v65
	v_add_u32_e32 v65, 0x70, v65
	v_and_b32_e32 v68, 0x7f, v68
	v_and_b32_e32 v65, 0x7f, v65
	v_lshl_or_b32 v163, v68, 2, v66
	v_lshl_or_b32 v164, v65, 2, v66
	v_add_u32_e32 v66, 8, v133
	v_and_b32_e32 v66, 0x78, v66
	v_lshlrev_b32_e32 v65, 9, v136
	v_lshlrev_b32_e32 v66, 2, v66
	v_or3_b32 v166, v64, v65, v66
	v_add_u32_e32 v66, 16, v133
	v_and_b32_e32 v66, 0x78, v66
	v_lshlrev_b32_e32 v65, 9, v132
	v_lshlrev_b32_e32 v66, 2, v66
	v_or3_b32 v168, v64, v65, v66
	v_add_u32_e32 v66, 24, v133
	v_and_b32_e32 v66, 0x78, v66
	v_lshlrev_b32_e32 v67, 5, v135
	v_lshlrev_b32_e32 v65, 9, v130
	v_lshlrev_b32_e32 v66, 2, v66
	v_or3_b32 v170, v64, v65, v66
	v_or_b32_e32 v64, 16, v67
	v_add_u32_e32 v68, 0x100, v131
	v_add_u32_e32 v69, 0x200, v131
	v_add_u32_e32 v70, 0x300, v131
	v_add_u32_e32 v71, 0x500, v131
	v_add_u32_e32 v72, 0x600, v131
	v_add_u32_e32 v73, 0x700, v131
	v_or_b32_e32 v172, v64, v134
	v_or_b32_e32 v173, v136, v64
	v_or_b32_e32 v174, v132, v64
	v_or_b32_e32 v175, v130, v64
	v_and_b32_e32 v64, 24, v153
	s_movk_i32 s90, 0x3c0
	v_lshrrev_b32_e32 v176, 4, v68
	v_lshrrev_b32_e32 v177, 4, v69
	v_lshrrev_b32_e32 v178, 4, v70
	v_lshrrev_b32_e32 v180, 4, v71
	v_lshrrev_b32_e32 v181, 4, v72
	v_lshrrev_b32_e32 v182, 4, v73
	v_or_b32_e32 v165, v134, v67
	v_or_b32_e32 v167, v136, v67
	v_or_b32_e32 v169, v132, v67
	v_or_b32_e32 v171, v130, v67
	v_and_or_b32 v64, v131, s90, v64
	v_mul_u32_u24_e32 v65, 0x110, v138
	v_lshlrev_b32_e32 v66, 4, v138
	v_mul_u32_u24_e32 v67, 0x110, v128
	v_mul_u32_u24_e32 v68, 0x110, v176
	v_mul_u32_u24_e32 v69, 0x110, v177
	v_mul_u32_u24_e32 v70, 0x110, v178
	v_mul_u32_u24_e32 v71, 0x110, v180
	v_mul_u32_u24_e32 v72, 0x110, v181
	v_mul_u32_u24_e32 v73, 0x110, v182
	v_or_b32_e32 v179, 64, v128
	v_lshlrev_b32_e32 v190, 2, v138
	v_add_u32_e32 v191, v64, v65
	v_add_u32_e32 v192, v66, v67
	v_add_u32_e32 v193, v66, v68
	v_add_u32_e32 v194, v66, v69
	v_add_u32_e32 v195, v66, v70
	v_add_u32_e32 v196, v66, v71
	v_add_u32_e32 v197, v66, v72
	v_add_u32_e32 v198, v66, v73
	v_mbcnt_hi_u32_b32 v199, -1, v155
	s_waitcnt lgkmcnt(0)
	s_mov_b64 s[6:7], -1
	s_cmp_lt_i32 s77, 5
	s_branch .Lmy_ip0_epi

.LBB0_430:
	s_lshr_b32 s90, s64, 3
	s_lshl_b32 s90, s90, 4
	s_and_b32 s91, s64, 7
	s_or_b32 s90, s90, s91
	s_lshl_b32 s91, s89, 3
	s_add_i32 s90, s90, s91
	s_ashr_i32 s1, s90, 31
	s_lshr_b32 s1, s1, 23
	s_add_i32 s1, s90, s1
	s_ashr_i32 s1, s1, 9
	s_and_b32 s0, s90, 7
	s_lshl_b32 s1, s1, 3
	s_or_b32 s38, s1, s0
	s_mul_hi_i32 s66, s38, 0x2aaaaaab
	s_lshr_b32 s0, s66, 31
	s_add_i32 s66, s66, s0
	s_lshl_b32 s0, s66, 3
	s_bfe_u32 s1, s90, 0x30003
	s_or_b32 s0, s0, s1
	s_mul_i32 s1, s66, 6
	s_sub_i32 s65, s38, s1
	s_lshl_b32 s1, s65, 3
	s_bfe_u32 s33, s90, 0x30006
	s_or_b32 s4, s1, s33
	s_ashr_i32 s1, s0, 31
	s_ashr_i32 s5, s4, 31
	s_lshl_b64 s[54:55], s[4:5], 18
	s_lshl_b64 s[56:57], s[0:1], 18
	s_cmp_lg_u32 s89, 0
	s_cbranch_scc1 .Lmy_ip1_pass2
	s_barrier
	s_setprio 2
	s_add_u32 s84, s50, 0x3a00000
	s_addc_u32 s85, s51, 0
	s_add_u32 s84, s84, s56
	s_addc_u32 s85, s85, s57
	s_add_u32 s92, s84, 0x40000
	s_addc_u32 s93, s85, 0
	s_add_u32 s86, s50, s54
	s_addc_u32 s87, s51, s55
	s_lshl_b64 s[54:55], s[0:1], 17
	v_readfirstlane_b32 s88, v129
	v_and_b32_e32 v200, 15, v131
	v_bfe_u32 v201, v131, 4, 2
	v_and_b32_e32 v202, 63, v131
	v_lshlrev_b32_e32 v202, 4, v202
	v_lshrrev_b32_e32 v203, 6, v131
	v_lshl_add_u32 v66, v203, 16, v202
	v_add_u32_e32 v67, 0x8000, v66
	v_bfe_u32 v202, v131, 1, 3
	v_xor_b32_e32 v202, v201, v202
	v_lshlrev_b32_e32 v202, 4, v202
	v_lshl_or_b32 v75, v200, 7, v202
	v_xor_b32_e32 v212, 64, v75
	v_bfe_u32 v200, v131, 4, 3
	v_and_b32_e32 v201, 7, v131
	v_xor_b32_e32 v200, v200, v201
	v_lshlrev_b32_e32 v200, 4, v200
	v_lshrrev_b32_e32 v201, 3, v131
	v_lshl_or_b32 v68, v201, 11, v200
	v_add_u32_e32 v69, 65536, v68
	v_add_u32_e32 v71, 131072, v68
	v_add_u32_e32 v74, 196608, v68
	s_add_u32 m0, s88, 0
	v_mov_b32_e32 v32, 0
	v_mov_b32_e32 v33, 0
	global_load_lds_dwordx4 v68, s[86:87]
	v_mov_b32_e32 v34, 0
	v_mov_b32_e32 v35, 0
	v_mov_b32_e32 v36, 0
	s_add_u32 m0, s88, 4096
	v_mov_b32_e32 v37, 0
	v_mov_b32_e32 v38, 0
	global_load_lds_dwordx4 v69, s[86:87]
	v_mov_b32_e32 v39, 0
	v_mov_b32_e32 v40, 0
	v_mov_b32_e32 v41, 0
	s_add_u32 m0, s88, 8192
	v_mov_b32_e32 v42, 0
	v_mov_b32_e32 v43, 0
	global_load_lds_dwordx4 v71, s[86:87]
	v_mov_b32_e32 v44, 0
	v_mov_b32_e32 v45, 0
	v_mov_b32_e32 v46, 0
	s_add_u32 m0, s88, 12288
	v_mov_b32_e32 v47, 0
	v_mov_b32_e32 v48, 0
	global_load_lds_dwordx4 v74, s[86:87]
	s_add_u32 s86, s86, 128
	s_addc_u32 s87, s87, 0
	v_mov_b32_e32 v49, 0
	v_mov_b32_e32 v50, 0
	v_mov_b32_e32 v51, 0
	global_load_dwordx4 v[76:79], v66, s[84:85] offset:0
	v_mov_b32_e32 v52, 0
	v_mov_b32_e32 v53, 0
	v_mov_b32_e32 v54, 0
	global_load_dwordx4 v[80:83], v67, s[84:85] offset:0
	v_mov_b32_e32 v55, 0
	v_mov_b32_e32 v56, 0
	v_mov_b32_e32 v57, 0
	global_load_dwordx4 v[84:87], v66, s[92:93] offset:0
	v_mov_b32_e32 v58, 0
	v_mov_b32_e32 v59, 0
	v_mov_b32_e32 v60, 0
	global_load_dwordx4 v[88:91], v67, s[92:93] offset:0
	v_mov_b32_e32 v61, 0
	v_mov_b32_e32 v62, 0
	v_mov_b32_e32 v63, 0
	global_load_dwordx4 v[140:143], v66, s[84:85] offset:1024
	v_mov_b32_e32 v4, 0
	v_mov_b32_e32 v5, 0
	v_mov_b32_e32 v6, 0
	global_load_dwordx4 v[144:147], v67, s[84:85] offset:1024
	v_mov_b32_e32 v7, 0
	v_mov_b32_e32 v12, 0
	v_mov_b32_e32 v13, 0
	global_load_dwordx4 v[148:151], v66, s[92:93] offset:1024
	v_mov_b32_e32 v14, 0
	v_mov_b32_e32 v15, 0
	v_mov_b32_e32 v16, 0
	global_load_dwordx4 v[204:207], v67, s[92:93] offset:1024
	s_add_u32 s84, s84, 0x800
	s_addc_u32 s85, s85, 0
	s_add_u32 s92, s92, 0x800
	s_addc_u32 s93, s93, 0
	v_mov_b32_e32 v17, 0
	v_mov_b32_e32 v18, 0
	v_mov_b32_e32 v19, 0
	s_add_u32 m0, s88, 16384
	v_mov_b32_e32 v20, 0
	v_mov_b32_e32 v21, 0
	global_load_lds_dwordx4 v68, s[86:87]
	v_mov_b32_e32 v22, 0
	v_mov_b32_e32 v23, 0
	v_mov_b32_e32 v0, 0
	s_add_u32 m0, s88, 20480
	v_mov_b32_e32 v1, 0
	v_mov_b32_e32 v2, 0
	global_load_lds_dwordx4 v69, s[86:87]
	v_mov_b32_e32 v3, 0
	v_mov_b32_e32 v8, 0
	v_mov_b32_e32 v9, 0
	s_add_u32 m0, s88, 24576
	v_mov_b32_e32 v10, 0
	v_mov_b32_e32 v11, 0
	global_load_lds_dwordx4 v71, s[86:87]
	v_mov_b32_e32 v24, 0
	v_mov_b32_e32 v25, 0
	v_mov_b32_e32 v26, 0
	s_add_u32 m0, s88, 28672
	v_mov_b32_e32 v27, 0
	v_mov_b32_e32 v28, 0
	global_load_lds_dwordx4 v74, s[86:87]
	s_add_u32 s86, s86, 128
	s_addc_u32 s87, s87, 0
	v_mov_b32_e32 v29, 0
	v_mov_b32_e32 v30, 0
	v_mov_b32_e32 v31, 0
	s_add_u32 m0, s88, 32768
	v_mov_b32_e32 v188, 0
	v_mov_b32_e32 v189, 0
	global_load_lds_dwordx4 v68, s[86:87]
	v_mov_b32_e32 v190, 0
	v_mov_b32_e32 v191, 0
	v_mov_b32_e32 v208, 0
	s_add_u32 m0, s88, 36864
	v_mov_b32_e32 v209, 0
	v_mov_b32_e32 v210, 0
	global_load_lds_dwordx4 v69, s[86:87]
	v_mov_b32_e32 v211, 0
	v_mov_b32_e32 v232, 0
	v_mov_b32_e32 v233, 0
	s_add_u32 m0, s88, 40960
	v_mov_b32_e32 v234, 0
	v_mov_b32_e32 v235, 0
	global_load_lds_dwordx4 v71, s[86:87]
	v_mov_b32_e32 v236, 0
	v_mov_b32_e32 v237, 0
	v_mov_b32_e32 v238, 0
	s_add_u32 m0, s88, 45056
	v_mov_b32_e32 v239, 0
	v_mov_b32_e32 v240, 0
	global_load_lds_dwordx4 v74, s[86:87]
	s_add_u32 s86, s86, 128
	s_addc_u32 s87, s87, 0
	v_mov_b32_e32 v241, 0
	v_mov_b32_e32 v242, 0
	v_mov_b32_e32 v243, 0
	v_mov_b32_e32 v248, 0
	v_mov_b32_e32 v249, 0
	v_mov_b32_e32 v250, 0
	v_mov_b32_e32 v251, 0
	v_mov_b32_e32 v252, 0
	v_mov_b32_e32 v253, 0
	v_mov_b32_e32 v254, 0
	v_mov_b32_e32 v255, 0
	v_mov_b32_e32 v92, 0
	v_mov_b32_e32 v93, 0
	v_mov_b32_e32 v94, 0
	v_mov_b32_e32 v95, 0
	v_mov_b32_e32 v96, 0
	v_mov_b32_e32 v97, 0
	v_mov_b32_e32 v98, 0
	v_mov_b32_e32 v99, 0
	v_mov_b32_e32 v100, 0
	v_mov_b32_e32 v101, 0
	v_mov_b32_e32 v102, 0
	v_mov_b32_e32 v103, 0
	v_mov_b32_e32 v104, 0
	v_mov_b32_e32 v105, 0
	v_mov_b32_e32 v106, 0
	v_mov_b32_e32 v107, 0
	v_mov_b32_e32 v108, 0
	v_mov_b32_e32 v109, 0
	v_mov_b32_e32 v110, 0
	v_mov_b32_e32 v111, 0
	v_mov_b32_e32 v112, 0
	v_mov_b32_e32 v113, 0
	v_mov_b32_e32 v114, 0
	v_mov_b32_e32 v115, 0
	v_mov_b32_e32 v116, 0
	v_mov_b32_e32 v117, 0
	v_mov_b32_e32 v118, 0
	v_mov_b32_e32 v119, 0
	v_mov_b32_e32 v120, 0
	v_mov_b32_e32 v121, 0
	v_mov_b32_e32 v122, 0
	v_mov_b32_e32 v123, 0
	v_mov_b32_e32 v124, 0
	v_mov_b32_e32 v125, 0
	v_mov_b32_e32 v126, 0
	v_mov_b32_e32 v127, 0
	s_waitcnt vmcnt(12)
	s_barrier
	ds_read_b128 v[176:179], v75 offset:0
	ds_read_b128 v[180:183], v75 offset:2048
	ds_read_b128 v[184:187], v75 offset:4096
	ds_read_b128 v[192:195], v75 offset:6144
	ds_read_b128 v[196:199], v75 offset:8192
	global_load_dwordx4 v[160:163], v66, s[84:85] offset:0
	s_waitcnt lgkmcnt(4)
	v_mfma_f32_16x16x32_bf16 v[32:35], v[76:79], v[176:179], v[32:35]
	v_mfma_f32_16x16x32_bf16 v[4:7], v[80:83], v[176:179], v[4:7]
	v_mfma_f32_16x16x32_bf16 v[188:191], v[84:87], v[176:179], v[188:191]
	v_mfma_f32_16x16x32_bf16 v[96:99], v[88:91], v[176:179], v[96:99]
	ds_read_b128 v[200:203], v75 offset:10240
	global_load_dwordx4 v[164:167], v67, s[84:85] offset:0
	s_waitcnt lgkmcnt(4)
	v_mfma_f32_16x16x32_bf16 v[36:39], v[76:79], v[180:183], v[36:39]
	v_mfma_f32_16x16x32_bf16 v[12:15], v[80:83], v[180:183], v[12:15]
	v_mfma_f32_16x16x32_bf16 v[208:211], v[84:87], v[180:183], v[208:211]
	v_mfma_f32_16x16x32_bf16 v[100:103], v[88:91], v[180:183], v[100:103]
	ds_read_b128 v[176:179], v75 offset:12288
	global_load_dwordx4 v[168:171], v66, s[92:93] offset:0
	s_waitcnt lgkmcnt(4)
	v_mfma_f32_16x16x32_bf16 v[40:43], v[76:79], v[184:187], v[40:43]
	v_mfma_f32_16x16x32_bf16 v[16:19], v[80:83], v[184:187], v[16:19]
	v_mfma_f32_16x16x32_bf16 v[232:235], v[84:87], v[184:187], v[232:235]
	v_mfma_f32_16x16x32_bf16 v[104:107], v[88:91], v[184:187], v[104:107]
	ds_read_b128 v[180:183], v75 offset:14336
	global_load_dwordx4 v[172:175], v67, s[92:93] offset:0
	s_waitcnt lgkmcnt(4)
	v_mfma_f32_16x16x32_bf16 v[44:47], v[76:79], v[192:195], v[44:47]
	v_mfma_f32_16x16x32_bf16 v[20:23], v[80:83], v[192:195], v[20:23]
	v_mfma_f32_16x16x32_bf16 v[236:239], v[84:87], v[192:195], v[236:239]
	v_mfma_f32_16x16x32_bf16 v[108:111], v[88:91], v[192:195], v[108:111]
	ds_read_b128 v[184:187], v212 offset:0
	s_waitcnt lgkmcnt(4)
	v_mfma_f32_16x16x32_bf16 v[48:51], v[76:79], v[196:199], v[48:51]
	v_mfma_f32_16x16x32_bf16 v[0:3], v[80:83], v[196:199], v[0:3]
	v_mfma_f32_16x16x32_bf16 v[240:243], v[84:87], v[196:199], v[240:243]
	v_mfma_f32_16x16x32_bf16 v[112:115], v[88:91], v[196:199], v[112:115]
	ds_read_b128 v[192:195], v212 offset:2048
	s_waitcnt lgkmcnt(4)
	v_mfma_f32_16x16x32_bf16 v[52:55], v[76:79], v[200:203], v[52:55]
	v_mfma_f32_16x16x32_bf16 v[8:11], v[80:83], v[200:203], v[8:11]
	v_mfma_f32_16x16x32_bf16 v[248:251], v[84:87], v[200:203], v[248:251]
	v_mfma_f32_16x16x32_bf16 v[116:119], v[88:91], v[200:203], v[116:119]
	ds_read_b128 v[196:199], v212 offset:4096
	s_waitcnt lgkmcnt(4)
	v_mfma_f32_16x16x32_bf16 v[56:59], v[76:79], v[176:179], v[56:59]
	v_mfma_f32_16x16x32_bf16 v[24:27], v[80:83], v[176:179], v[24:27]
	v_mfma_f32_16x16x32_bf16 v[252:255], v[84:87], v[176:179], v[252:255]
	v_mfma_f32_16x16x32_bf16 v[120:123], v[88:91], v[176:179], v[120:123]
	ds_read_b128 v[200:203], v212 offset:6144
	s_waitcnt lgkmcnt(4)
	v_mfma_f32_16x16x32_bf16 v[60:63], v[76:79], v[180:183], v[60:63]
	v_mfma_f32_16x16x32_bf16 v[28:31], v[80:83], v[180:183], v[28:31]
	v_mfma_f32_16x16x32_bf16 v[92:95], v[84:87], v[180:183], v[92:95]
	v_mfma_f32_16x16x32_bf16 v[124:127], v[88:91], v[180:183], v[124:127]
	s_waitcnt vmcnt(8)
	s_barrier
	s_waitcnt vmcnt(12)
	ds_read_b128 v[176:179], v212 offset:8192
	global_load_dwordx4 v[76:79], v66, s[84:85] offset:1024
	s_waitcnt lgkmcnt(4)
	v_mfma_f32_16x16x32_bf16 v[32:35], v[140:143], v[184:187], v[32:35]
	v_mfma_f32_16x16x32_bf16 v[4:7], v[144:147], v[184:187], v[4:7]
	v_mfma_f32_16x16x32_bf16 v[188:191], v[148:151], v[184:187], v[188:191]
	v_mfma_f32_16x16x32_bf16 v[96:99], v[204:207], v[184:187], v[96:99]
	ds_read_b128 v[180:183], v212 offset:10240
	global_load_dwordx4 v[80:83], v67, s[84:85] offset:1024
	s_waitcnt lgkmcnt(4)
	v_mfma_f32_16x16x32_bf16 v[36:39], v[140:143], v[192:195], v[36:39]
	v_mfma_f32_16x16x32_bf16 v[12:15], v[144:147], v[192:195], v[12:15]
	v_mfma_f32_16x16x32_bf16 v[208:211], v[148:151], v[192:195], v[208:211]
	v_mfma_f32_16x16x32_bf16 v[100:103], v[204:207], v[192:195], v[100:103]
	ds_read_b128 v[184:187], v212 offset:12288
	global_load_dwordx4 v[84:87], v66, s[92:93] offset:1024
	s_waitcnt lgkmcnt(4)
	v_mfma_f32_16x16x32_bf16 v[40:43], v[140:143], v[196:199], v[40:43]
	v_mfma_f32_16x16x32_bf16 v[16:19], v[144:147], v[196:199], v[16:19]
	v_mfma_f32_16x16x32_bf16 v[232:235], v[148:151], v[196:199], v[232:235]
	v_mfma_f32_16x16x32_bf16 v[104:107], v[204:207], v[196:199], v[104:107]
	ds_read_b128 v[192:195], v212 offset:14336
	global_load_dwordx4 v[88:91], v67, s[92:93] offset:1024
	s_add_u32 s84, s84, 0x800
	s_addc_u32 s85, s85, 0
	s_add_u32 s92, s92, 0x800
	s_addc_u32 s93, s93, 0
	s_waitcnt lgkmcnt(4)
	v_mfma_f32_16x16x32_bf16 v[44:47], v[140:143], v[200:203], v[44:47]
	v_mfma_f32_16x16x32_bf16 v[20:23], v[144:147], v[200:203], v[20:23]
	v_mfma_f32_16x16x32_bf16 v[236:239], v[148:151], v[200:203], v[236:239]
	v_mfma_f32_16x16x32_bf16 v[108:111], v[204:207], v[200:203], v[108:111]
	ds_read_b128 v[196:199], v75 offset:16384
	s_add_u32 m0, s88, 49152
	s_nop 0
	global_load_lds_dwordx4 v68, s[86:87]
	s_waitcnt lgkmcnt(4)
	v_mfma_f32_16x16x32_bf16 v[48:51], v[140:143], v[176:179], v[48:51]
	v_mfma_f32_16x16x32_bf16 v[0:3], v[144:147], v[176:179], v[0:3]
	v_mfma_f32_16x16x32_bf16 v[240:243], v[148:151], v[176:179], v[240:243]
	v_mfma_f32_16x16x32_bf16 v[112:115], v[204:207], v[176:179], v[112:115]
	ds_read_b128 v[200:203], v75 offset:18432
	s_add_u32 m0, s88, 53248
	s_nop 0
	global_load_lds_dwordx4 v69, s[86:87]
	s_waitcnt lgkmcnt(4)
	v_mfma_f32_16x16x32_bf16 v[52:55], v[140:143], v[180:183], v[52:55]
	v_mfma_f32_16x16x32_bf16 v[8:11], v[144:147], v[180:183], v[8:11]
	v_mfma_f32_16x16x32_bf16 v[248:251], v[148:151], v[180:183], v[248:251]
	v_mfma_f32_16x16x32_bf16 v[116:119], v[204:207], v[180:183], v[116:119]
	ds_read_b128 v[176:179], v75 offset:20480
	s_add_u32 m0, s88, 57344
	s_nop 0
	global_load_lds_dwordx4 v71, s[86:87]
	s_waitcnt lgkmcnt(4)
	v_mfma_f32_16x16x32_bf16 v[56:59], v[140:143], v[184:187], v[56:59]
	v_mfma_f32_16x16x32_bf16 v[24:27], v[144:147], v[184:187], v[24:27]
	v_mfma_f32_16x16x32_bf16 v[252:255], v[148:151], v[184:187], v[252:255]
	v_mfma_f32_16x16x32_bf16 v[120:123], v[204:207], v[184:187], v[120:123]
	ds_read_b128 v[180:183], v75 offset:22528
	s_add_u32 m0, s88, 61440
	s_nop 0
	global_load_lds_dwordx4 v74, s[86:87]
	s_add_u32 s86, s86, 128
	s_addc_u32 s87, s87, 0
	s_waitcnt lgkmcnt(4)
	v_mfma_f32_16x16x32_bf16 v[60:63], v[140:143], v[192:195], v[60:63]
	v_mfma_f32_16x16x32_bf16 v[28:31], v[144:147], v[192:195], v[28:31]
	v_mfma_f32_16x16x32_bf16 v[92:95], v[148:151], v[192:195], v[92:95]
	v_mfma_f32_16x16x32_bf16 v[124:127], v[204:207], v[192:195], v[124:127]
	s_waitcnt vmcnt(8)
	ds_read_b128 v[184:187], v75 offset:24576
	global_load_dwordx4 v[140:143], v66, s[84:85] offset:0
	s_waitcnt lgkmcnt(4)
	v_mfma_f32_16x16x32_bf16 v[32:35], v[160:163], v[196:199], v[32:35]
	v_mfma_f32_16x16x32_bf16 v[4:7], v[164:167], v[196:199], v[4:7]
	v_mfma_f32_16x16x32_bf16 v[188:191], v[168:171], v[196:199], v[188:191]
	v_mfma_f32_16x16x32_bf16 v[96:99], v[172:175], v[196:199], v[96:99]
	ds_read_b128 v[192:195], v75 offset:26624
	global_load_dwordx4 v[144:147], v67, s[84:85] offset:0
	s_waitcnt lgkmcnt(4)
	v_mfma_f32_16x16x32_bf16 v[36:39], v[160:163], v[200:203], v[36:39]
	v_mfma_f32_16x16x32_bf16 v[12:15], v[164:167], v[200:203], v[12:15]
	v_mfma_f32_16x16x32_bf16 v[208:211], v[168:171], v[200:203], v[208:211]
	v_mfma_f32_16x16x32_bf16 v[100:103], v[172:175], v[200:203], v[100:103]
	ds_read_b128 v[196:199], v75 offset:28672
	global_load_dwordx4 v[148:151], v66, s[92:93] offset:0
	s_waitcnt lgkmcnt(4)
	v_mfma_f32_16x16x32_bf16 v[40:43], v[160:163], v[176:179], v[40:43]
	v_mfma_f32_16x16x32_bf16 v[16:19], v[164:167], v[176:179], v[16:19]
	v_mfma_f32_16x16x32_bf16 v[232:235], v[168:171], v[176:179], v[232:235]
	v_mfma_f32_16x16x32_bf16 v[104:107], v[172:175], v[176:179], v[104:107]
	ds_read_b128 v[200:203], v75 offset:30720
	global_load_dwordx4 v[204:207], v67, s[92:93] offset:0
	s_waitcnt lgkmcnt(4)
	v_mfma_f32_16x16x32_bf16 v[44:47], v[160:163], v[180:183], v[44:47]
	v_mfma_f32_16x16x32_bf16 v[20:23], v[164:167], v[180:183], v[20:23]
	v_mfma_f32_16x16x32_bf16 v[236:239], v[168:171], v[180:183], v[236:239]
	v_mfma_f32_16x16x32_bf16 v[108:111], v[172:175], v[180:183], v[108:111]
	ds_read_b128 v[176:179], v212 offset:16384
	s_waitcnt lgkmcnt(4)
	v_mfma_f32_16x16x32_bf16 v[48:51], v[160:163], v[184:187], v[48:51]
	v_mfma_f32_16x16x32_bf16 v[0:3], v[164:167], v[184:187], v[0:3]
	v_mfma_f32_16x16x32_bf16 v[240:243], v[168:171], v[184:187], v[240:243]
	v_mfma_f32_16x16x32_bf16 v[112:115], v[172:175], v[184:187], v[112:115]
	ds_read_b128 v[180:183], v212 offset:18432
	s_waitcnt lgkmcnt(4)
	v_mfma_f32_16x16x32_bf16 v[52:55], v[160:163], v[192:195], v[52:55]
	v_mfma_f32_16x16x32_bf16 v[8:11], v[164:167], v[192:195], v[8:11]
	v_mfma_f32_16x16x32_bf16 v[248:251], v[168:171], v[192:195], v[248:251]
	v_mfma_f32_16x16x32_bf16 v[116:119], v[172:175], v[192:195], v[116:119]
	ds_read_b128 v[184:187], v212 offset:20480
	s_waitcnt lgkmcnt(4)
	v_mfma_f32_16x16x32_bf16 v[56:59], v[160:163], v[196:199], v[56:59]
	v_mfma_f32_16x16x32_bf16 v[24:27], v[164:167], v[196:199], v[24:27]
	v_mfma_f32_16x16x32_bf16 v[252:255], v[168:171], v[196:199], v[252:255]
	v_mfma_f32_16x16x32_bf16 v[120:123], v[172:175], v[196:199], v[120:123]
	ds_read_b128 v[192:195], v212 offset:22528
	s_waitcnt lgkmcnt(4)
	v_mfma_f32_16x16x32_bf16 v[60:63], v[160:163], v[200:203], v[60:63]
	v_mfma_f32_16x16x32_bf16 v[28:31], v[164:167], v[200:203], v[28:31]
	v_mfma_f32_16x16x32_bf16 v[92:95], v[168:171], v[200:203], v[92:95]
	v_mfma_f32_16x16x32_bf16 v[124:127], v[172:175], v[200:203], v[124:127]
	s_waitcnt vmcnt(16)
	s_barrier
	s_waitcnt vmcnt(8)
	ds_read_b128 v[196:199], v212 offset:24576
	global_load_dwordx4 v[160:163], v66, s[84:85] offset:1024
	s_waitcnt lgkmcnt(4)
	v_mfma_f32_16x16x32_bf16 v[32:35], v[76:79], v[176:179], v[32:35]
	v_mfma_f32_16x16x32_bf16 v[4:7], v[80:83], v[176:179], v[4:7]
	v_mfma_f32_16x16x32_bf16 v[188:191], v[84:87], v[176:179], v[188:191]
	v_mfma_f32_16x16x32_bf16 v[96:99], v[88:91], v[176:179], v[96:99]
	ds_read_b128 v[200:203], v212 offset:26624
	global_load_dwordx4 v[164:167], v67, s[84:85] offset:1024
	s_waitcnt lgkmcnt(4)
	v_mfma_f32_16x16x32_bf16 v[36:39], v[76:79], v[180:183], v[36:39]
	v_mfma_f32_16x16x32_bf16 v[12:15], v[80:83], v[180:183], v[12:15]
	v_mfma_f32_16x16x32_bf16 v[208:211], v[84:87], v[180:183], v[208:211]
	v_mfma_f32_16x16x32_bf16 v[100:103], v[88:91], v[180:183], v[100:103]
	ds_read_b128 v[176:179], v212 offset:28672
	global_load_dwordx4 v[168:171], v66, s[92:93] offset:1024
	s_waitcnt lgkmcnt(4)
	v_mfma_f32_16x16x32_bf16 v[40:43], v[76:79], v[184:187], v[40:43]
	v_mfma_f32_16x16x32_bf16 v[16:19], v[80:83], v[184:187], v[16:19]
	v_mfma_f32_16x16x32_bf16 v[232:235], v[84:87], v[184:187], v[232:235]
	v_mfma_f32_16x16x32_bf16 v[104:107], v[88:91], v[184:187], v[104:107]
	ds_read_b128 v[180:183], v212 offset:30720
	global_load_dwordx4 v[172:175], v67, s[92:93] offset:1024
	s_add_u32 s84, s84, 0x800
	s_addc_u32 s85, s85, 0
	s_add_u32 s92, s92, 0x800
	s_addc_u32 s93, s93, 0
	s_waitcnt lgkmcnt(4)
	v_mfma_f32_16x16x32_bf16 v[44:47], v[76:79], v[192:195], v[44:47]
	v_mfma_f32_16x16x32_bf16 v[20:23], v[80:83], v[192:195], v[20:23]
	v_mfma_f32_16x16x32_bf16 v[236:239], v[84:87], v[192:195], v[236:239]
	v_mfma_f32_16x16x32_bf16 v[108:111], v[88:91], v[192:195], v[108:111]
	ds_read_b128 v[184:187], v75 offset:32768
	s_add_u32 m0, s88, 0
	s_nop 0
	global_load_lds_dwordx4 v68, s[86:87]
	s_waitcnt lgkmcnt(4)
	v_mfma_f32_16x16x32_bf16 v[48:51], v[76:79], v[196:199], v[48:51]
	v_mfma_f32_16x16x32_bf16 v[0:3], v[80:83], v[196:199], v[0:3]
	v_mfma_f32_16x16x32_bf16 v[240:243], v[84:87], v[196:199], v[240:243]
	v_mfma_f32_16x16x32_bf16 v[112:115], v[88:91], v[196:199], v[112:115]
	ds_read_b128 v[192:195], v75 offset:34816
	s_add_u32 m0, s88, 4096
	s_nop 0
	global_load_lds_dwordx4 v69, s[86:87]
	s_waitcnt lgkmcnt(4)
	v_mfma_f32_16x16x32_bf16 v[52:55], v[76:79], v[200:203], v[52:55]
	v_mfma_f32_16x16x32_bf16 v[8:11], v[80:83], v[200:203], v[8:11]
	v_mfma_f32_16x16x32_bf16 v[248:251], v[84:87], v[200:203], v[248:251]
	v_mfma_f32_16x16x32_bf16 v[116:119], v[88:91], v[200:203], v[116:119]
	ds_read_b128 v[196:199], v75 offset:36864
	s_add_u32 m0, s88, 8192
	s_nop 0
	global_load_lds_dwordx4 v71, s[86:87]
	s_waitcnt lgkmcnt(4)
	v_mfma_f32_16x16x32_bf16 v[56:59], v[76:79], v[176:179], v[56:59]
	v_mfma_f32_16x16x32_bf16 v[24:27], v[80:83], v[176:179], v[24:27]
	v_mfma_f32_16x16x32_bf16 v[252:255], v[84:87], v[176:179], v[252:255]
	v_mfma_f32_16x16x32_bf16 v[120:123], v[88:91], v[176:179], v[120:123]
	ds_read_b128 v[200:203], v75 offset:38912
	s_add_u32 m0, s88, 12288
	s_nop 0
	global_load_lds_dwordx4 v74, s[86:87]
	s_add_u32 s86, s86, 128
	s_addc_u32 s87, s87, 0
	s_waitcnt lgkmcnt(4)
	v_mfma_f32_16x16x32_bf16 v[60:63], v[76:79], v[180:183], v[60:63]
	v_mfma_f32_16x16x32_bf16 v[28:31], v[80:83], v[180:183], v[28:31]
	v_mfma_f32_16x16x32_bf16 v[92:95], v[84:87], v[180:183], v[92:95]
	v_mfma_f32_16x16x32_bf16 v[124:127], v[88:91], v[180:183], v[124:127]
	s_waitcnt vmcnt(8)
	ds_read_b128 v[176:179], v75 offset:40960
	global_load_dwordx4 v[76:79], v66, s[84:85] offset:0
	s_waitcnt lgkmcnt(4)
	v_mfma_f32_16x16x32_bf16 v[32:35], v[140:143], v[184:187], v[32:35]
	v_mfma_f32_16x16x32_bf16 v[4:7], v[144:147], v[184:187], v[4:7]
	v_mfma_f32_16x16x32_bf16 v[188:191], v[148:151], v[184:187], v[188:191]
	v_mfma_f32_16x16x32_bf16 v[96:99], v[204:207], v[184:187], v[96:99]
	ds_read_b128 v[180:183], v75 offset:43008
	global_load_dwordx4 v[80:83], v67, s[84:85] offset:0
	s_waitcnt lgkmcnt(4)
	v_mfma_f32_16x16x32_bf16 v[36:39], v[140:143], v[192:195], v[36:39]
	v_mfma_f32_16x16x32_bf16 v[12:15], v[144:147], v[192:195], v[12:15]
	v_mfma_f32_16x16x32_bf16 v[208:211], v[148:151], v[192:195], v[208:211]
	v_mfma_f32_16x16x32_bf16 v[100:103], v[204:207], v[192:195], v[100:103]
	ds_read_b128 v[184:187], v75 offset:45056
	global_load_dwordx4 v[84:87], v66, s[92:93] offset:0
	s_waitcnt lgkmcnt(4)
	v_mfma_f32_16x16x32_bf16 v[40:43], v[140:143], v[196:199], v[40:43]
	v_mfma_f32_16x16x32_bf16 v[16:19], v[144:147], v[196:199], v[16:19]
	v_mfma_f32_16x16x32_bf16 v[232:235], v[148:151], v[196:199], v[232:235]
	v_mfma_f32_16x16x32_bf16 v[104:107], v[204:207], v[196:199], v[104:107]
	ds_read_b128 v[192:195], v75 offset:47104
	global_load_dwordx4 v[88:91], v67, s[92:93] offset:0
	s_waitcnt lgkmcnt(4)
	v_mfma_f32_16x16x32_bf16 v[44:47], v[140:143], v[200:203], v[44:47]
	v_mfma_f32_16x16x32_bf16 v[20:23], v[144:147], v[200:203], v[20:23]
	v_mfma_f32_16x16x32_bf16 v[236:239], v[148:151], v[200:203], v[236:239]
	v_mfma_f32_16x16x32_bf16 v[108:111], v[204:207], v[200:203], v[108:111]
	ds_read_b128 v[196:199], v212 offset:32768
	s_waitcnt lgkmcnt(4)
	v_mfma_f32_16x16x32_bf16 v[48:51], v[140:143], v[176:179], v[48:51]
	v_mfma_f32_16x16x32_bf16 v[0:3], v[144:147], v[176:179], v[0:3]
	v_mfma_f32_16x16x32_bf16 v[240:243], v[148:151], v[176:179], v[240:243]
	v_mfma_f32_16x16x32_bf16 v[112:115], v[204:207], v[176:179], v[112:115]
	ds_read_b128 v[200:203], v212 offset:34816
	s_waitcnt lgkmcnt(4)
	v_mfma_f32_16x16x32_bf16 v[52:55], v[140:143], v[180:183], v[52:55]
	v_mfma_f32_16x16x32_bf16 v[8:11], v[144:147], v[180:183], v[8:11]
	v_mfma_f32_16x16x32_bf16 v[248:251], v[148:151], v[180:183], v[248:251]
	v_mfma_f32_16x16x32_bf16 v[116:119], v[204:207], v[180:183], v[116:119]
	ds_read_b128 v[176:179], v212 offset:36864
	s_waitcnt lgkmcnt(4)
	v_mfma_f32_16x16x32_bf16 v[56:59], v[140:143], v[184:187], v[56:59]
	v_mfma_f32_16x16x32_bf16 v[24:27], v[144:147], v[184:187], v[24:27]
	v_mfma_f32_16x16x32_bf16 v[252:255], v[148:151], v[184:187], v[252:255]
	v_mfma_f32_16x16x32_bf16 v[120:123], v[204:207], v[184:187], v[120:123]
	ds_read_b128 v[180:183], v212 offset:38912
	s_waitcnt lgkmcnt(4)
	v_mfma_f32_16x16x32_bf16 v[60:63], v[140:143], v[192:195], v[60:63]
	v_mfma_f32_16x16x32_bf16 v[28:31], v[144:147], v[192:195], v[28:31]
	v_mfma_f32_16x16x32_bf16 v[92:95], v[148:151], v[192:195], v[92:95]
	v_mfma_f32_16x16x32_bf16 v[124:127], v[204:207], v[192:195], v[124:127]
	s_waitcnt vmcnt(16)
	s_barrier
	s_waitcnt vmcnt(8)
	ds_read_b128 v[184:187], v212 offset:40960
	global_load_dwordx4 v[140:143], v66, s[84:85] offset:1024
	s_waitcnt lgkmcnt(4)
	v_mfma_f32_16x16x32_bf16 v[32:35], v[160:163], v[196:199], v[32:35]
	v_mfma_f32_16x16x32_bf16 v[4:7], v[164:167], v[196:199], v[4:7]
	v_mfma_f32_16x16x32_bf16 v[188:191], v[168:171], v[196:199], v[188:191]
	v_mfma_f32_16x16x32_bf16 v[96:99], v[172:175], v[196:199], v[96:99]
	ds_read_b128 v[192:195], v212 offset:43008
	global_load_dwordx4 v[144:147], v67, s[84:85] offset:1024
	s_waitcnt lgkmcnt(4)
	v_mfma_f32_16x16x32_bf16 v[36:39], v[160:163], v[200:203], v[36:39]
	v_mfma_f32_16x16x32_bf16 v[12:15], v[164:167], v[200:203], v[12:15]
	v_mfma_f32_16x16x32_bf16 v[208:211], v[168:171], v[200:203], v[208:211]
	v_mfma_f32_16x16x32_bf16 v[100:103], v[172:175], v[200:203], v[100:103]
	ds_read_b128 v[196:199], v212 offset:45056
	global_load_dwordx4 v[148:151], v66, s[92:93] offset:1024
	s_waitcnt lgkmcnt(4)
	v_mfma_f32_16x16x32_bf16 v[40:43], v[160:163], v[176:179], v[40:43]
	v_mfma_f32_16x16x32_bf16 v[16:19], v[164:167], v[176:179], v[16:19]
	v_mfma_f32_16x16x32_bf16 v[232:235], v[168:171], v[176:179], v[232:235]
	v_mfma_f32_16x16x32_bf16 v[104:107], v[172:175], v[176:179], v[104:107]
	ds_read_b128 v[200:203], v212 offset:47104
	global_load_dwordx4 v[204:207], v67, s[92:93] offset:1024
	s_add_u32 s84, s84, 0x800
	s_addc_u32 s85, s85, 0
	s_add_u32 s92, s92, 0x800
	s_addc_u32 s93, s93, 0
	s_waitcnt lgkmcnt(4)
	v_mfma_f32_16x16x32_bf16 v[44:47], v[160:163], v[180:183], v[44:47]
	v_mfma_f32_16x16x32_bf16 v[20:23], v[164:167], v[180:183], v[20:23]
	v_mfma_f32_16x16x32_bf16 v[236:239], v[168:171], v[180:183], v[236:239]
	v_mfma_f32_16x16x32_bf16 v[108:111], v[172:175], v[180:183], v[108:111]
	ds_read_b128 v[176:179], v75 offset:49152
	s_add_u32 m0, s88, 16384
	s_nop 0
	global_load_lds_dwordx4 v68, s[86:87]
	s_waitcnt lgkmcnt(4)
	v_mfma_f32_16x16x32_bf16 v[48:51], v[160:163], v[184:187], v[48:51]
	v_mfma_f32_16x16x32_bf16 v[0:3], v[164:167], v[184:187], v[0:3]
	v_mfma_f32_16x16x32_bf16 v[240:243], v[168:171], v[184:187], v[240:243]
	v_mfma_f32_16x16x32_bf16 v[112:115], v[172:175], v[184:187], v[112:115]
	ds_read_b128 v[180:183], v75 offset:51200
	s_add_u32 m0, s88, 20480
	s_nop 0
	global_load_lds_dwordx4 v69, s[86:87]
	s_waitcnt lgkmcnt(4)
	v_mfma_f32_16x16x32_bf16 v[52:55], v[160:163], v[192:195], v[52:55]
	v_mfma_f32_16x16x32_bf16 v[8:11], v[164:167], v[192:195], v[8:11]
	v_mfma_f32_16x16x32_bf16 v[248:251], v[168:171], v[192:195], v[248:251]
	v_mfma_f32_16x16x32_bf16 v[116:119], v[172:175], v[192:195], v[116:119]
	ds_read_b128 v[184:187], v75 offset:53248
	s_add_u32 m0, s88, 24576
	s_nop 0
	global_load_lds_dwordx4 v71, s[86:87]
	s_waitcnt lgkmcnt(4)
	v_mfma_f32_16x16x32_bf16 v[56:59], v[160:163], v[196:199], v[56:59]
	v_mfma_f32_16x16x32_bf16 v[24:27], v[164:167], v[196:199], v[24:27]
	v_mfma_f32_16x16x32_bf16 v[252:255], v[168:171], v[196:199], v[252:255]
	v_mfma_f32_16x16x32_bf16 v[120:123], v[172:175], v[196:199], v[120:123]
	ds_read_b128 v[192:195], v75 offset:55296
	s_add_u32 m0, s88, 28672
	s_nop 0
	global_load_lds_dwordx4 v74, s[86:87]
	s_add_u32 s86, s86, 128
	s_addc_u32 s87, s87, 0
	s_waitcnt lgkmcnt(4)
	v_mfma_f32_16x16x32_bf16 v[60:63], v[160:163], v[200:203], v[60:63]
	v_mfma_f32_16x16x32_bf16 v[28:31], v[164:167], v[200:203], v[28:31]
	v_mfma_f32_16x16x32_bf16 v[92:95], v[168:171], v[200:203], v[92:95]
	v_mfma_f32_16x16x32_bf16 v[124:127], v[172:175], v[200:203], v[124:127]
	s_waitcnt vmcnt(8)
	ds_read_b128 v[196:199], v75 offset:57344
	global_load_dwordx4 v[160:163], v66, s[84:85] offset:0
	s_waitcnt lgkmcnt(4)
	v_mfma_f32_16x16x32_bf16 v[32:35], v[76:79], v[176:179], v[32:35]
	v_mfma_f32_16x16x32_bf16 v[4:7], v[80:83], v[176:179], v[4:7]
	v_mfma_f32_16x16x32_bf16 v[188:191], v[84:87], v[176:179], v[188:191]
	v_mfma_f32_16x16x32_bf16 v[96:99], v[88:91], v[176:179], v[96:99]
	ds_read_b128 v[200:203], v75 offset:59392
	global_load_dwordx4 v[164:167], v67, s[84:85] offset:0
	s_waitcnt lgkmcnt(4)
	v_mfma_f32_16x16x32_bf16 v[36:39], v[76:79], v[180:183], v[36:39]
	v_mfma_f32_16x16x32_bf16 v[12:15], v[80:83], v[180:183], v[12:15]
	v_mfma_f32_16x16x32_bf16 v[208:211], v[84:87], v[180:183], v[208:211]
	v_mfma_f32_16x16x32_bf16 v[100:103], v[88:91], v[180:183], v[100:103]
	ds_read_b128 v[176:179], v75 offset:61440
	global_load_dwordx4 v[168:171], v66, s[92:93] offset:0
	s_waitcnt lgkmcnt(4)
	v_mfma_f32_16x16x32_bf16 v[40:43], v[76:79], v[184:187], v[40:43]
	v_mfma_f32_16x16x32_bf16 v[16:19], v[80:83], v[184:187], v[16:19]
	v_mfma_f32_16x16x32_bf16 v[232:235], v[84:87], v[184:187], v[232:235]
	v_mfma_f32_16x16x32_bf16 v[104:107], v[88:91], v[184:187], v[104:107]
	ds_read_b128 v[180:183], v75 offset:63488
	global_load_dwordx4 v[172:175], v67, s[92:93] offset:0
	s_waitcnt lgkmcnt(4)
	v_mfma_f32_16x16x32_bf16 v[44:47], v[76:79], v[192:195], v[44:47]
	v_mfma_f32_16x16x32_bf16 v[20:23], v[80:83], v[192:195], v[20:23]
	v_mfma_f32_16x16x32_bf16 v[236:239], v[84:87], v[192:195], v[236:239]
	v_mfma_f32_16x16x32_bf16 v[108:111], v[88:91], v[192:195], v[108:111]
	ds_read_b128 v[184:187], v212 offset:49152
	s_waitcnt lgkmcnt(4)
	v_mfma_f32_16x16x32_bf16 v[48:51], v[76:79], v[196:199], v[48:51]
	v_mfma_f32_16x16x32_bf16 v[0:3], v[80:83], v[196:199], v[0:3]
	v_mfma_f32_16x16x32_bf16 v[240:243], v[84:87], v[196:199], v[240:243]
	v_mfma_f32_16x16x32_bf16 v[112:115], v[88:91], v[196:199], v[112:115]
	ds_read_b128 v[192:195], v212 offset:51200
	s_waitcnt lgkmcnt(4)
	v_mfma_f32_16x16x32_bf16 v[52:55], v[76:79], v[200:203], v[52:55]
	v_mfma_f32_16x16x32_bf16 v[8:11], v[80:83], v[200:203], v[8:11]
	v_mfma_f32_16x16x32_bf16 v[248:251], v[84:87], v[200:203], v[248:251]
	v_mfma_f32_16x16x32_bf16 v[116:119], v[88:91], v[200:203], v[116:119]
	ds_read_b128 v[196:199], v212 offset:53248
	s_waitcnt lgkmcnt(4)
	v_mfma_f32_16x16x32_bf16 v[56:59], v[76:79], v[176:179], v[56:59]
	v_mfma_f32_16x16x32_bf16 v[24:27], v[80:83], v[176:179], v[24:27]
	v_mfma_f32_16x16x32_bf16 v[252:255], v[84:87], v[176:179], v[252:255]
	v_mfma_f32_16x16x32_bf16 v[120:123], v[88:91], v[176:179], v[120:123]
	ds_read_b128 v[200:203], v212 offset:55296
	s_waitcnt lgkmcnt(4)
	v_mfma_f32_16x16x32_bf16 v[60:63], v[76:79], v[180:183], v[60:63]
	v_mfma_f32_16x16x32_bf16 v[28:31], v[80:83], v[180:183], v[28:31]
	v_mfma_f32_16x16x32_bf16 v[92:95], v[84:87], v[180:183], v[92:95]
	v_mfma_f32_16x16x32_bf16 v[124:127], v[88:91], v[180:183], v[124:127]
	s_waitcnt vmcnt(16)
	s_barrier
	s_waitcnt vmcnt(8)
	ds_read_b128 v[176:179], v212 offset:57344
	global_load_dwordx4 v[76:79], v66, s[84:85] offset:1024
	s_waitcnt lgkmcnt(4)
	v_mfma_f32_16x16x32_bf16 v[32:35], v[140:143], v[184:187], v[32:35]
	v_mfma_f32_16x16x32_bf16 v[4:7], v[144:147], v[184:187], v[4:7]
	v_mfma_f32_16x16x32_bf16 v[188:191], v[148:151], v[184:187], v[188:191]
	v_mfma_f32_16x16x32_bf16 v[96:99], v[204:207], v[184:187], v[96:99]
	ds_read_b128 v[180:183], v212 offset:59392
	global_load_dwordx4 v[80:83], v67, s[84:85] offset:1024
	s_waitcnt lgkmcnt(4)
	v_mfma_f32_16x16x32_bf16 v[36:39], v[140:143], v[192:195], v[36:39]
	v_mfma_f32_16x16x32_bf16 v[12:15], v[144:147], v[192:195], v[12:15]
	v_mfma_f32_16x16x32_bf16 v[208:211], v[148:151], v[192:195], v[208:211]
	v_mfma_f32_16x16x32_bf16 v[100:103], v[204:207], v[192:195], v[100:103]
	ds_read_b128 v[184:187], v212 offset:61440
	global_load_dwordx4 v[84:87], v66, s[92:93] offset:1024
	s_waitcnt lgkmcnt(4)
	v_mfma_f32_16x16x32_bf16 v[40:43], v[140:143], v[196:199], v[40:43]
	v_mfma_f32_16x16x32_bf16 v[16:19], v[144:147], v[196:199], v[16:19]
	v_mfma_f32_16x16x32_bf16 v[232:235], v[148:151], v[196:199], v[232:235]
	v_mfma_f32_16x16x32_bf16 v[104:107], v[204:207], v[196:199], v[104:107]
	ds_read_b128 v[192:195], v212 offset:63488
	global_load_dwordx4 v[88:91], v67, s[92:93] offset:1024
	s_add_u32 s84, s84, 0x800
	s_addc_u32 s85, s85, 0
	s_add_u32 s92, s92, 0x800
	s_addc_u32 s93, s93, 0
	s_waitcnt lgkmcnt(4)
	v_mfma_f32_16x16x32_bf16 v[44:47], v[140:143], v[200:203], v[44:47]
	v_mfma_f32_16x16x32_bf16 v[20:23], v[144:147], v[200:203], v[20:23]
	v_mfma_f32_16x16x32_bf16 v[236:239], v[148:151], v[200:203], v[236:239]
	v_mfma_f32_16x16x32_bf16 v[108:111], v[204:207], v[200:203], v[108:111]
	ds_read_b128 v[196:199], v75 offset:0
	s_add_u32 m0, s88, 32768
	s_nop 0
	global_load_lds_dwordx4 v68, s[86:87]
	s_waitcnt lgkmcnt(4)
	v_mfma_f32_16x16x32_bf16 v[48:51], v[140:143], v[176:179], v[48:51]
	v_mfma_f32_16x16x32_bf16 v[0:3], v[144:147], v[176:179], v[0:3]
	v_mfma_f32_16x16x32_bf16 v[240:243], v[148:151], v[176:179], v[240:243]
	v_mfma_f32_16x16x32_bf16 v[112:115], v[204:207], v[176:179], v[112:115]
	ds_read_b128 v[200:203], v75 offset:2048
	s_add_u32 m0, s88, 36864
	s_nop 0
	global_load_lds_dwordx4 v69, s[86:87]
	s_waitcnt lgkmcnt(4)
	v_mfma_f32_16x16x32_bf16 v[52:55], v[140:143], v[180:183], v[52:55]
	v_mfma_f32_16x16x32_bf16 v[8:11], v[144:147], v[180:183], v[8:11]
	v_mfma_f32_16x16x32_bf16 v[248:251], v[148:151], v[180:183], v[248:251]
	v_mfma_f32_16x16x32_bf16 v[116:119], v[204:207], v[180:183], v[116:119]
	ds_read_b128 v[176:179], v75 offset:4096
	s_add_u32 m0, s88, 40960
	s_nop 0
	global_load_lds_dwordx4 v71, s[86:87]
	s_waitcnt lgkmcnt(4)
	v_mfma_f32_16x16x32_bf16 v[56:59], v[140:143], v[184:187], v[56:59]
	v_mfma_f32_16x16x32_bf16 v[24:27], v[144:147], v[184:187], v[24:27]
	v_mfma_f32_16x16x32_bf16 v[252:255], v[148:151], v[184:187], v[252:255]
	v_mfma_f32_16x16x32_bf16 v[120:123], v[204:207], v[184:187], v[120:123]
	ds_read_b128 v[180:183], v75 offset:6144
	s_add_u32 m0, s88, 45056
	s_nop 0
	global_load_lds_dwordx4 v74, s[86:87]
	s_add_u32 s86, s86, 128
	s_addc_u32 s87, s87, 0
	s_waitcnt lgkmcnt(4)
	v_mfma_f32_16x16x32_bf16 v[60:63], v[140:143], v[192:195], v[60:63]
	v_mfma_f32_16x16x32_bf16 v[28:31], v[144:147], v[192:195], v[28:31]
	v_mfma_f32_16x16x32_bf16 v[92:95], v[148:151], v[192:195], v[92:95]
	v_mfma_f32_16x16x32_bf16 v[124:127], v[204:207], v[192:195], v[124:127]
	s_waitcnt vmcnt(8)
	ds_read_b128 v[184:187], v75 offset:8192
	global_load_dwordx4 v[140:143], v66, s[84:85] offset:0
	s_waitcnt lgkmcnt(4)
	v_mfma_f32_16x16x32_bf16 v[32:35], v[160:163], v[196:199], v[32:35]
	v_mfma_f32_16x16x32_bf16 v[4:7], v[164:167], v[196:199], v[4:7]
	v_mfma_f32_16x16x32_bf16 v[188:191], v[168:171], v[196:199], v[188:191]
	v_mfma_f32_16x16x32_bf16 v[96:99], v[172:175], v[196:199], v[96:99]
	ds_read_b128 v[192:195], v75 offset:10240
	global_load_dwordx4 v[144:147], v67, s[84:85] offset:0
	s_waitcnt lgkmcnt(4)
	v_mfma_f32_16x16x32_bf16 v[36:39], v[160:163], v[200:203], v[36:39]
	v_mfma_f32_16x16x32_bf16 v[12:15], v[164:167], v[200:203], v[12:15]
	v_mfma_f32_16x16x32_bf16 v[208:211], v[168:171], v[200:203], v[208:211]
	v_mfma_f32_16x16x32_bf16 v[100:103], v[172:175], v[200:203], v[100:103]
	ds_read_b128 v[196:199], v75 offset:12288
	global_load_dwordx4 v[148:151], v66, s[92:93] offset:0
	s_waitcnt lgkmcnt(4)
	v_mfma_f32_16x16x32_bf16 v[40:43], v[160:163], v[176:179], v[40:43]
	v_mfma_f32_16x16x32_bf16 v[16:19], v[164:167], v[176:179], v[16:19]
	v_mfma_f32_16x16x32_bf16 v[232:235], v[168:171], v[176:179], v[232:235]
	v_mfma_f32_16x16x32_bf16 v[104:107], v[172:175], v[176:179], v[104:107]
	ds_read_b128 v[200:203], v75 offset:14336
	global_load_dwordx4 v[204:207], v67, s[92:93] offset:0
	s_waitcnt lgkmcnt(4)
	v_mfma_f32_16x16x32_bf16 v[44:47], v[160:163], v[180:183], v[44:47]
	v_mfma_f32_16x16x32_bf16 v[20:23], v[164:167], v[180:183], v[20:23]
	v_mfma_f32_16x16x32_bf16 v[236:239], v[168:171], v[180:183], v[236:239]
	v_mfma_f32_16x16x32_bf16 v[108:111], v[172:175], v[180:183], v[108:111]
	ds_read_b128 v[176:179], v212 offset:0
	s_waitcnt lgkmcnt(4)
	v_mfma_f32_16x16x32_bf16 v[48:51], v[160:163], v[184:187], v[48:51]
	v_mfma_f32_16x16x32_bf16 v[0:3], v[164:167], v[184:187], v[0:3]
	v_mfma_f32_16x16x32_bf16 v[240:243], v[168:171], v[184:187], v[240:243]
	v_mfma_f32_16x16x32_bf16 v[112:115], v[172:175], v[184:187], v[112:115]
	ds_read_b128 v[180:183], v212 offset:2048
	s_waitcnt lgkmcnt(4)
	v_mfma_f32_16x16x32_bf16 v[52:55], v[160:163], v[192:195], v[52:55]
	v_mfma_f32_16x16x32_bf16 v[8:11], v[164:167], v[192:195], v[8:11]
	v_mfma_f32_16x16x32_bf16 v[248:251], v[168:171], v[192:195], v[248:251]
	v_mfma_f32_16x16x32_bf16 v[116:119], v[172:175], v[192:195], v[116:119]
	ds_read_b128 v[184:187], v212 offset:4096
	s_waitcnt lgkmcnt(4)
	v_mfma_f32_16x16x32_bf16 v[56:59], v[160:163], v[196:199], v[56:59]
	v_mfma_f32_16x16x32_bf16 v[24:27], v[164:167], v[196:199], v[24:27]
	v_mfma_f32_16x16x32_bf16 v[252:255], v[168:171], v[196:199], v[252:255]
	v_mfma_f32_16x16x32_bf16 v[120:123], v[172:175], v[196:199], v[120:123]
	ds_read_b128 v[192:195], v212 offset:6144
	s_waitcnt lgkmcnt(4)
	v_mfma_f32_16x16x32_bf16 v[60:63], v[160:163], v[200:203], v[60:63]
	v_mfma_f32_16x16x32_bf16 v[28:31], v[164:167], v[200:203], v[28:31]
	v_mfma_f32_16x16x32_bf16 v[92:95], v[168:171], v[200:203], v[92:95]
	v_mfma_f32_16x16x32_bf16 v[124:127], v[172:175], v[200:203], v[124:127]
	s_waitcnt vmcnt(16)
	s_barrier
	s_waitcnt vmcnt(8)
	ds_read_b128 v[196:199], v212 offset:8192
	global_load_dwordx4 v[160:163], v66, s[84:85] offset:1024
	s_waitcnt lgkmcnt(4)
	v_mfma_f32_16x16x32_bf16 v[32:35], v[76:79], v[176:179], v[32:35]
	v_mfma_f32_16x16x32_bf16 v[4:7], v[80:83], v[176:179], v[4:7]
	v_mfma_f32_16x16x32_bf16 v[188:191], v[84:87], v[176:179], v[188:191]
	v_mfma_f32_16x16x32_bf16 v[96:99], v[88:91], v[176:179], v[96:99]
	ds_read_b128 v[200:203], v212 offset:10240
	global_load_dwordx4 v[164:167], v67, s[84:85] offset:1024
	s_waitcnt lgkmcnt(4)
	v_mfma_f32_16x16x32_bf16 v[36:39], v[76:79], v[180:183], v[36:39]
	v_mfma_f32_16x16x32_bf16 v[12:15], v[80:83], v[180:183], v[12:15]
	v_mfma_f32_16x16x32_bf16 v[208:211], v[84:87], v[180:183], v[208:211]
	v_mfma_f32_16x16x32_bf16 v[100:103], v[88:91], v[180:183], v[100:103]
	ds_read_b128 v[176:179], v212 offset:12288
	global_load_dwordx4 v[168:171], v66, s[92:93] offset:1024
	s_waitcnt lgkmcnt(4)
	v_mfma_f32_16x16x32_bf16 v[40:43], v[76:79], v[184:187], v[40:43]
	v_mfma_f32_16x16x32_bf16 v[16:19], v[80:83], v[184:187], v[16:19]
	v_mfma_f32_16x16x32_bf16 v[232:235], v[84:87], v[184:187], v[232:235]
	v_mfma_f32_16x16x32_bf16 v[104:107], v[88:91], v[184:187], v[104:107]
	ds_read_b128 v[180:183], v212 offset:14336
	global_load_dwordx4 v[172:175], v67, s[92:93] offset:1024
	s_add_u32 s84, s84, 0x800
	s_addc_u32 s85, s85, 0
	s_add_u32 s92, s92, 0x800
	s_addc_u32 s93, s93, 0
	s_waitcnt lgkmcnt(4)
	v_mfma_f32_16x16x32_bf16 v[44:47], v[76:79], v[192:195], v[44:47]
	v_mfma_f32_16x16x32_bf16 v[20:23], v[80:83], v[192:195], v[20:23]
	v_mfma_f32_16x16x32_bf16 v[236:239], v[84:87], v[192:195], v[236:239]
	v_mfma_f32_16x16x32_bf16 v[108:111], v[88:91], v[192:195], v[108:111]
	ds_read_b128 v[184:187], v75 offset:16384
	s_add_u32 m0, s88, 49152
	s_nop 0
	global_load_lds_dwordx4 v68, s[86:87]
	s_waitcnt lgkmcnt(4)
	v_mfma_f32_16x16x32_bf16 v[48:51], v[76:79], v[196:199], v[48:51]
	v_mfma_f32_16x16x32_bf16 v[0:3], v[80:83], v[196:199], v[0:3]
	v_mfma_f32_16x16x32_bf16 v[240:243], v[84:87], v[196:199], v[240:243]
	v_mfma_f32_16x16x32_bf16 v[112:115], v[88:91], v[196:199], v[112:115]
	ds_read_b128 v[192:195], v75 offset:18432
	s_add_u32 m0, s88, 53248
	s_nop 0
	global_load_lds_dwordx4 v69, s[86:87]
	s_waitcnt lgkmcnt(4)
	v_mfma_f32_16x16x32_bf16 v[52:55], v[76:79], v[200:203], v[52:55]
	v_mfma_f32_16x16x32_bf16 v[8:11], v[80:83], v[200:203], v[8:11]
	v_mfma_f32_16x16x32_bf16 v[248:251], v[84:87], v[200:203], v[248:251]
	v_mfma_f32_16x16x32_bf16 v[116:119], v[88:91], v[200:203], v[116:119]
	ds_read_b128 v[196:199], v75 offset:20480
	s_add_u32 m0, s88, 57344
	s_nop 0
	global_load_lds_dwordx4 v71, s[86:87]
	s_waitcnt lgkmcnt(4)
	v_mfma_f32_16x16x32_bf16 v[56:59], v[76:79], v[176:179], v[56:59]
	v_mfma_f32_16x16x32_bf16 v[24:27], v[80:83], v[176:179], v[24:27]
	v_mfma_f32_16x16x32_bf16 v[252:255], v[84:87], v[176:179], v[252:255]
	v_mfma_f32_16x16x32_bf16 v[120:123], v[88:91], v[176:179], v[120:123]
	ds_read_b128 v[200:203], v75 offset:22528
	s_add_u32 m0, s88, 61440
	s_nop 0
	global_load_lds_dwordx4 v74, s[86:87]
	s_add_u32 s86, s86, 128
	s_addc_u32 s87, s87, 0
	s_waitcnt lgkmcnt(4)
	v_mfma_f32_16x16x32_bf16 v[60:63], v[76:79], v[180:183], v[60:63]
	v_mfma_f32_16x16x32_bf16 v[28:31], v[80:83], v[180:183], v[28:31]
	v_mfma_f32_16x16x32_bf16 v[92:95], v[84:87], v[180:183], v[92:95]
	v_mfma_f32_16x16x32_bf16 v[124:127], v[88:91], v[180:183], v[124:127]
	s_waitcnt vmcnt(8)
	ds_read_b128 v[176:179], v75 offset:24576
	global_load_dwordx4 v[76:79], v66, s[84:85] offset:0
	s_waitcnt lgkmcnt(4)
	v_mfma_f32_16x16x32_bf16 v[32:35], v[140:143], v[184:187], v[32:35]
	v_mfma_f32_16x16x32_bf16 v[4:7], v[144:147], v[184:187], v[4:7]
	v_mfma_f32_16x16x32_bf16 v[188:191], v[148:151], v[184:187], v[188:191]
	v_mfma_f32_16x16x32_bf16 v[96:99], v[204:207], v[184:187], v[96:99]
	ds_read_b128 v[180:183], v75 offset:26624
	global_load_dwordx4 v[80:83], v67, s[84:85] offset:0
	s_waitcnt lgkmcnt(4)
	v_mfma_f32_16x16x32_bf16 v[36:39], v[140:143], v[192:195], v[36:39]
	v_mfma_f32_16x16x32_bf16 v[12:15], v[144:147], v[192:195], v[12:15]
	v_mfma_f32_16x16x32_bf16 v[208:211], v[148:151], v[192:195], v[208:211]
	v_mfma_f32_16x16x32_bf16 v[100:103], v[204:207], v[192:195], v[100:103]
	ds_read_b128 v[184:187], v75 offset:28672
	global_load_dwordx4 v[84:87], v66, s[92:93] offset:0
	s_waitcnt lgkmcnt(4)
	v_mfma_f32_16x16x32_bf16 v[40:43], v[140:143], v[196:199], v[40:43]
	v_mfma_f32_16x16x32_bf16 v[16:19], v[144:147], v[196:199], v[16:19]
	v_mfma_f32_16x16x32_bf16 v[232:235], v[148:151], v[196:199], v[232:235]
	v_mfma_f32_16x16x32_bf16 v[104:107], v[204:207], v[196:199], v[104:107]
	ds_read_b128 v[192:195], v75 offset:30720
	global_load_dwordx4 v[88:91], v67, s[92:93] offset:0
	s_waitcnt lgkmcnt(4)
	v_mfma_f32_16x16x32_bf16 v[44:47], v[140:143], v[200:203], v[44:47]
	v_mfma_f32_16x16x32_bf16 v[20:23], v[144:147], v[200:203], v[20:23]
	v_mfma_f32_16x16x32_bf16 v[236:239], v[148:151], v[200:203], v[236:239]
	v_mfma_f32_16x16x32_bf16 v[108:111], v[204:207], v[200:203], v[108:111]
	ds_read_b128 v[196:199], v212 offset:16384
	s_waitcnt lgkmcnt(4)
	v_mfma_f32_16x16x32_bf16 v[48:51], v[140:143], v[176:179], v[48:51]
	v_mfma_f32_16x16x32_bf16 v[0:3], v[144:147], v[176:179], v[0:3]
	v_mfma_f32_16x16x32_bf16 v[240:243], v[148:151], v[176:179], v[240:243]
	v_mfma_f32_16x16x32_bf16 v[112:115], v[204:207], v[176:179], v[112:115]
	ds_read_b128 v[200:203], v212 offset:18432
	s_waitcnt lgkmcnt(4)
	v_mfma_f32_16x16x32_bf16 v[52:55], v[140:143], v[180:183], v[52:55]
	v_mfma_f32_16x16x32_bf16 v[8:11], v[144:147], v[180:183], v[8:11]
	v_mfma_f32_16x16x32_bf16 v[248:251], v[148:151], v[180:183], v[248:251]
	v_mfma_f32_16x16x32_bf16 v[116:119], v[204:207], v[180:183], v[116:119]
	ds_read_b128 v[176:179], v212 offset:20480
	s_waitcnt lgkmcnt(4)
	v_mfma_f32_16x16x32_bf16 v[56:59], v[140:143], v[184:187], v[56:59]
	v_mfma_f32_16x16x32_bf16 v[24:27], v[144:147], v[184:187], v[24:27]
	v_mfma_f32_16x16x32_bf16 v[252:255], v[148:151], v[184:187], v[252:255]
	v_mfma_f32_16x16x32_bf16 v[120:123], v[204:207], v[184:187], v[120:123]
	ds_read_b128 v[180:183], v212 offset:22528
	s_waitcnt lgkmcnt(4)
	v_mfma_f32_16x16x32_bf16 v[60:63], v[140:143], v[192:195], v[60:63]
	v_mfma_f32_16x16x32_bf16 v[28:31], v[144:147], v[192:195], v[28:31]
	v_mfma_f32_16x16x32_bf16 v[92:95], v[148:151], v[192:195], v[92:95]
	v_mfma_f32_16x16x32_bf16 v[124:127], v[204:207], v[192:195], v[124:127]
	s_waitcnt vmcnt(16)
	s_barrier
	s_waitcnt vmcnt(8)
	ds_read_b128 v[184:187], v212 offset:24576
	global_load_dwordx4 v[140:143], v66, s[84:85] offset:1024
	s_waitcnt lgkmcnt(4)
	v_mfma_f32_16x16x32_bf16 v[32:35], v[160:163], v[196:199], v[32:35]
	v_mfma_f32_16x16x32_bf16 v[4:7], v[164:167], v[196:199], v[4:7]
	v_mfma_f32_16x16x32_bf16 v[188:191], v[168:171], v[196:199], v[188:191]
	v_mfma_f32_16x16x32_bf16 v[96:99], v[172:175], v[196:199], v[96:99]
	ds_read_b128 v[192:195], v212 offset:26624
	global_load_dwordx4 v[144:147], v67, s[84:85] offset:1024
	s_waitcnt lgkmcnt(4)
	v_mfma_f32_16x16x32_bf16 v[36:39], v[160:163], v[200:203], v[36:39]
	v_mfma_f32_16x16x32_bf16 v[12:15], v[164:167], v[200:203], v[12:15]
	v_mfma_f32_16x16x32_bf16 v[208:211], v[168:171], v[200:203], v[208:211]
	v_mfma_f32_16x16x32_bf16 v[100:103], v[172:175], v[200:203], v[100:103]
	ds_read_b128 v[196:199], v212 offset:28672
	global_load_dwordx4 v[148:151], v66, s[92:93] offset:1024
	s_waitcnt lgkmcnt(4)
	v_mfma_f32_16x16x32_bf16 v[40:43], v[160:163], v[176:179], v[40:43]
	v_mfma_f32_16x16x32_bf16 v[16:19], v[164:167], v[176:179], v[16:19]
	v_mfma_f32_16x16x32_bf16 v[232:235], v[168:171], v[176:179], v[232:235]
	v_mfma_f32_16x16x32_bf16 v[104:107], v[172:175], v[176:179], v[104:107]
	ds_read_b128 v[200:203], v212 offset:30720
	global_load_dwordx4 v[204:207], v67, s[92:93] offset:1024
	s_add_u32 s84, s84, 0x800
	s_addc_u32 s85, s85, 0
	s_add_u32 s92, s92, 0x800
	s_addc_u32 s93, s93, 0
	s_waitcnt lgkmcnt(4)
	v_mfma_f32_16x16x32_bf16 v[44:47], v[160:163], v[180:183], v[44:47]
	v_mfma_f32_16x16x32_bf16 v[20:23], v[164:167], v[180:183], v[20:23]
	v_mfma_f32_16x16x32_bf16 v[236:239], v[168:171], v[180:183], v[236:239]
	v_mfma_f32_16x16x32_bf16 v[108:111], v[172:175], v[180:183], v[108:111]
	ds_read_b128 v[176:179], v75 offset:32768
	s_add_u32 m0, s88, 0
	s_nop 0
	global_load_lds_dwordx4 v68, s[86:87]
	s_waitcnt lgkmcnt(4)
	v_mfma_f32_16x16x32_bf16 v[48:51], v[160:163], v[184:187], v[48:51]
	v_mfma_f32_16x16x32_bf16 v[0:3], v[164:167], v[184:187], v[0:3]
	v_mfma_f32_16x16x32_bf16 v[240:243], v[168:171], v[184:187], v[240:243]
	v_mfma_f32_16x16x32_bf16 v[112:115], v[172:175], v[184:187], v[112:115]
	ds_read_b128 v[180:183], v75 offset:34816
	s_add_u32 m0, s88, 4096
	s_nop 0
	global_load_lds_dwordx4 v69, s[86:87]
	s_waitcnt lgkmcnt(4)
	v_mfma_f32_16x16x32_bf16 v[52:55], v[160:163], v[192:195], v[52:55]
	v_mfma_f32_16x16x32_bf16 v[8:11], v[164:167], v[192:195], v[8:11]
	v_mfma_f32_16x16x32_bf16 v[248:251], v[168:171], v[192:195], v[248:251]
	v_mfma_f32_16x16x32_bf16 v[116:119], v[172:175], v[192:195], v[116:119]
	ds_read_b128 v[184:187], v75 offset:36864
	s_add_u32 m0, s88, 8192
	s_nop 0
	global_load_lds_dwordx4 v71, s[86:87]
	s_waitcnt lgkmcnt(4)
	v_mfma_f32_16x16x32_bf16 v[56:59], v[160:163], v[196:199], v[56:59]
	v_mfma_f32_16x16x32_bf16 v[24:27], v[164:167], v[196:199], v[24:27]
	v_mfma_f32_16x16x32_bf16 v[252:255], v[168:171], v[196:199], v[252:255]
	v_mfma_f32_16x16x32_bf16 v[120:123], v[172:175], v[196:199], v[120:123]
	ds_read_b128 v[192:195], v75 offset:38912
	s_add_u32 m0, s88, 12288
	s_nop 0
	global_load_lds_dwordx4 v74, s[86:87]
	s_add_u32 s86, s86, 128
	s_addc_u32 s87, s87, 0
	s_waitcnt lgkmcnt(4)
	v_mfma_f32_16x16x32_bf16 v[60:63], v[160:163], v[200:203], v[60:63]
	v_mfma_f32_16x16x32_bf16 v[28:31], v[164:167], v[200:203], v[28:31]
	v_mfma_f32_16x16x32_bf16 v[92:95], v[168:171], v[200:203], v[92:95]
	v_mfma_f32_16x16x32_bf16 v[124:127], v[172:175], v[200:203], v[124:127]
	s_waitcnt vmcnt(8)
	ds_read_b128 v[196:199], v75 offset:40960
	global_load_dwordx4 v[160:163], v66, s[84:85] offset:0
	s_waitcnt lgkmcnt(4)
	v_mfma_f32_16x16x32_bf16 v[32:35], v[76:79], v[176:179], v[32:35]
	v_mfma_f32_16x16x32_bf16 v[4:7], v[80:83], v[176:179], v[4:7]
	v_mfma_f32_16x16x32_bf16 v[188:191], v[84:87], v[176:179], v[188:191]
	v_mfma_f32_16x16x32_bf16 v[96:99], v[88:91], v[176:179], v[96:99]
	ds_read_b128 v[200:203], v75 offset:43008
	global_load_dwordx4 v[164:167], v67, s[84:85] offset:0
	s_waitcnt lgkmcnt(4)
	v_mfma_f32_16x16x32_bf16 v[36:39], v[76:79], v[180:183], v[36:39]
	v_mfma_f32_16x16x32_bf16 v[12:15], v[80:83], v[180:183], v[12:15]
	v_mfma_f32_16x16x32_bf16 v[208:211], v[84:87], v[180:183], v[208:211]
	v_mfma_f32_16x16x32_bf16 v[100:103], v[88:91], v[180:183], v[100:103]
	ds_read_b128 v[176:179], v75 offset:45056
	global_load_dwordx4 v[168:171], v66, s[92:93] offset:0
	s_waitcnt lgkmcnt(4)
	v_mfma_f32_16x16x32_bf16 v[40:43], v[76:79], v[184:187], v[40:43]
	v_mfma_f32_16x16x32_bf16 v[16:19], v[80:83], v[184:187], v[16:19]
	v_mfma_f32_16x16x32_bf16 v[232:235], v[84:87], v[184:187], v[232:235]
	v_mfma_f32_16x16x32_bf16 v[104:107], v[88:91], v[184:187], v[104:107]
	ds_read_b128 v[180:183], v75 offset:47104
	global_load_dwordx4 v[172:175], v67, s[92:93] offset:0
	s_waitcnt lgkmcnt(4)
	v_mfma_f32_16x16x32_bf16 v[44:47], v[76:79], v[192:195], v[44:47]
	v_mfma_f32_16x16x32_bf16 v[20:23], v[80:83], v[192:195], v[20:23]
	v_mfma_f32_16x16x32_bf16 v[236:239], v[84:87], v[192:195], v[236:239]
	v_mfma_f32_16x16x32_bf16 v[108:111], v[88:91], v[192:195], v[108:111]
	ds_read_b128 v[184:187], v212 offset:32768
	s_waitcnt lgkmcnt(4)
	v_mfma_f32_16x16x32_bf16 v[48:51], v[76:79], v[196:199], v[48:51]
	v_mfma_f32_16x16x32_bf16 v[0:3], v[80:83], v[196:199], v[0:3]
	v_mfma_f32_16x16x32_bf16 v[240:243], v[84:87], v[196:199], v[240:243]
	v_mfma_f32_16x16x32_bf16 v[112:115], v[88:91], v[196:199], v[112:115]
	ds_read_b128 v[192:195], v212 offset:34816
	s_waitcnt lgkmcnt(4)
	v_mfma_f32_16x16x32_bf16 v[52:55], v[76:79], v[200:203], v[52:55]
	v_mfma_f32_16x16x32_bf16 v[8:11], v[80:83], v[200:203], v[8:11]
	v_mfma_f32_16x16x32_bf16 v[248:251], v[84:87], v[200:203], v[248:251]
	v_mfma_f32_16x16x32_bf16 v[116:119], v[88:91], v[200:203], v[116:119]
	ds_read_b128 v[196:199], v212 offset:36864
	s_waitcnt lgkmcnt(4)
	v_mfma_f32_16x16x32_bf16 v[56:59], v[76:79], v[176:179], v[56:59]
	v_mfma_f32_16x16x32_bf16 v[24:27], v[80:83], v[176:179], v[24:27]
	v_mfma_f32_16x16x32_bf16 v[252:255], v[84:87], v[176:179], v[252:255]
	v_mfma_f32_16x16x32_bf16 v[120:123], v[88:91], v[176:179], v[120:123]
	ds_read_b128 v[200:203], v212 offset:38912
	s_waitcnt lgkmcnt(4)
	v_mfma_f32_16x16x32_bf16 v[60:63], v[76:79], v[180:183], v[60:63]
	v_mfma_f32_16x16x32_bf16 v[28:31], v[80:83], v[180:183], v[28:31]
	v_mfma_f32_16x16x32_bf16 v[92:95], v[84:87], v[180:183], v[92:95]
	v_mfma_f32_16x16x32_bf16 v[124:127], v[88:91], v[180:183], v[124:127]
	s_waitcnt vmcnt(16)
	s_barrier
	s_waitcnt vmcnt(8)
	ds_read_b128 v[176:179], v212 offset:40960
	global_load_dwordx4 v[76:79], v66, s[84:85] offset:1024
	s_waitcnt lgkmcnt(4)
	v_mfma_f32_16x16x32_bf16 v[32:35], v[140:143], v[184:187], v[32:35]
	v_mfma_f32_16x16x32_bf16 v[4:7], v[144:147], v[184:187], v[4:7]
	v_mfma_f32_16x16x32_bf16 v[188:191], v[148:151], v[184:187], v[188:191]
	v_mfma_f32_16x16x32_bf16 v[96:99], v[204:207], v[184:187], v[96:99]
	ds_read_b128 v[180:183], v212 offset:43008
	global_load_dwordx4 v[80:83], v67, s[84:85] offset:1024
	s_waitcnt lgkmcnt(4)
	v_mfma_f32_16x16x32_bf16 v[36:39], v[140:143], v[192:195], v[36:39]
	v_mfma_f32_16x16x32_bf16 v[12:15], v[144:147], v[192:195], v[12:15]
	v_mfma_f32_16x16x32_bf16 v[208:211], v[148:151], v[192:195], v[208:211]
	v_mfma_f32_16x16x32_bf16 v[100:103], v[204:207], v[192:195], v[100:103]
	ds_read_b128 v[184:187], v212 offset:45056
	global_load_dwordx4 v[84:87], v66, s[92:93] offset:1024
	s_waitcnt lgkmcnt(4)
	v_mfma_f32_16x16x32_bf16 v[40:43], v[140:143], v[196:199], v[40:43]
	v_mfma_f32_16x16x32_bf16 v[16:19], v[144:147], v[196:199], v[16:19]
	v_mfma_f32_16x16x32_bf16 v[232:235], v[148:151], v[196:199], v[232:235]
	v_mfma_f32_16x16x32_bf16 v[104:107], v[204:207], v[196:199], v[104:107]
	ds_read_b128 v[192:195], v212 offset:47104
	global_load_dwordx4 v[88:91], v67, s[92:93] offset:1024
	s_add_u32 s84, s84, 0x800
	s_addc_u32 s85, s85, 0
	s_add_u32 s92, s92, 0x800
	s_addc_u32 s93, s93, 0
	s_waitcnt lgkmcnt(4)
	v_mfma_f32_16x16x32_bf16 v[44:47], v[140:143], v[200:203], v[44:47]
	v_mfma_f32_16x16x32_bf16 v[20:23], v[144:147], v[200:203], v[20:23]
	v_mfma_f32_16x16x32_bf16 v[236:239], v[148:151], v[200:203], v[236:239]
	v_mfma_f32_16x16x32_bf16 v[108:111], v[204:207], v[200:203], v[108:111]
	ds_read_b128 v[196:199], v75 offset:49152
	s_add_u32 m0, s88, 16384
	s_nop 0
	global_load_lds_dwordx4 v68, s[86:87]
	s_waitcnt lgkmcnt(4)
	v_mfma_f32_16x16x32_bf16 v[48:51], v[140:143], v[176:179], v[48:51]
	v_mfma_f32_16x16x32_bf16 v[0:3], v[144:147], v[176:179], v[0:3]
	v_mfma_f32_16x16x32_bf16 v[240:243], v[148:151], v[176:179], v[240:243]
	v_mfma_f32_16x16x32_bf16 v[112:115], v[204:207], v[176:179], v[112:115]
	ds_read_b128 v[200:203], v75 offset:51200
	s_add_u32 m0, s88, 20480
	s_nop 0
	global_load_lds_dwordx4 v69, s[86:87]
	s_waitcnt lgkmcnt(4)
	v_mfma_f32_16x16x32_bf16 v[52:55], v[140:143], v[180:183], v[52:55]
	v_mfma_f32_16x16x32_bf16 v[8:11], v[144:147], v[180:183], v[8:11]
	v_mfma_f32_16x16x32_bf16 v[248:251], v[148:151], v[180:183], v[248:251]
	v_mfma_f32_16x16x32_bf16 v[116:119], v[204:207], v[180:183], v[116:119]
	ds_read_b128 v[176:179], v75 offset:53248
	s_add_u32 m0, s88, 24576
	s_nop 0
	global_load_lds_dwordx4 v71, s[86:87]
	s_waitcnt lgkmcnt(4)
	v_mfma_f32_16x16x32_bf16 v[56:59], v[140:143], v[184:187], v[56:59]
	v_mfma_f32_16x16x32_bf16 v[24:27], v[144:147], v[184:187], v[24:27]
	v_mfma_f32_16x16x32_bf16 v[252:255], v[148:151], v[184:187], v[252:255]
	v_mfma_f32_16x16x32_bf16 v[120:123], v[204:207], v[184:187], v[120:123]
	ds_read_b128 v[180:183], v75 offset:55296
	s_add_u32 m0, s88, 28672
	s_nop 0
	global_load_lds_dwordx4 v74, s[86:87]
	s_add_u32 s86, s86, 128
	s_addc_u32 s87, s87, 0
	s_waitcnt lgkmcnt(4)
	v_mfma_f32_16x16x32_bf16 v[60:63], v[140:143], v[192:195], v[60:63]
	v_mfma_f32_16x16x32_bf16 v[28:31], v[144:147], v[192:195], v[28:31]
	v_mfma_f32_16x16x32_bf16 v[92:95], v[148:151], v[192:195], v[92:95]
	v_mfma_f32_16x16x32_bf16 v[124:127], v[204:207], v[192:195], v[124:127]
	s_waitcnt vmcnt(8)
	ds_read_b128 v[184:187], v75 offset:57344
	global_load_dwordx4 v[140:143], v66, s[84:85] offset:0
	s_waitcnt lgkmcnt(4)
	v_mfma_f32_16x16x32_bf16 v[32:35], v[160:163], v[196:199], v[32:35]
	v_mfma_f32_16x16x32_bf16 v[4:7], v[164:167], v[196:199], v[4:7]
	v_mfma_f32_16x16x32_bf16 v[188:191], v[168:171], v[196:199], v[188:191]
	v_mfma_f32_16x16x32_bf16 v[96:99], v[172:175], v[196:199], v[96:99]
	ds_read_b128 v[192:195], v75 offset:59392
	global_load_dwordx4 v[144:147], v67, s[84:85] offset:0
	s_waitcnt lgkmcnt(4)
	v_mfma_f32_16x16x32_bf16 v[36:39], v[160:163], v[200:203], v[36:39]
	v_mfma_f32_16x16x32_bf16 v[12:15], v[164:167], v[200:203], v[12:15]
	v_mfma_f32_16x16x32_bf16 v[208:211], v[168:171], v[200:203], v[208:211]
	v_mfma_f32_16x16x32_bf16 v[100:103], v[172:175], v[200:203], v[100:103]
	ds_read_b128 v[196:199], v75 offset:61440
	global_load_dwordx4 v[148:151], v66, s[92:93] offset:0
	s_waitcnt lgkmcnt(4)
	v_mfma_f32_16x16x32_bf16 v[40:43], v[160:163], v[176:179], v[40:43]
	v_mfma_f32_16x16x32_bf16 v[16:19], v[164:167], v[176:179], v[16:19]
	v_mfma_f32_16x16x32_bf16 v[232:235], v[168:171], v[176:179], v[232:235]
	v_mfma_f32_16x16x32_bf16 v[104:107], v[172:175], v[176:179], v[104:107]
	ds_read_b128 v[200:203], v75 offset:63488
	global_load_dwordx4 v[204:207], v67, s[92:93] offset:0
	s_waitcnt lgkmcnt(4)
	v_mfma_f32_16x16x32_bf16 v[44:47], v[160:163], v[180:183], v[44:47]
	v_mfma_f32_16x16x32_bf16 v[20:23], v[164:167], v[180:183], v[20:23]
	v_mfma_f32_16x16x32_bf16 v[236:239], v[168:171], v[180:183], v[236:239]
	v_mfma_f32_16x16x32_bf16 v[108:111], v[172:175], v[180:183], v[108:111]
	ds_read_b128 v[176:179], v212 offset:49152
	s_waitcnt lgkmcnt(4)
	v_mfma_f32_16x16x32_bf16 v[48:51], v[160:163], v[184:187], v[48:51]
	v_mfma_f32_16x16x32_bf16 v[0:3], v[164:167], v[184:187], v[0:3]
	v_mfma_f32_16x16x32_bf16 v[240:243], v[168:171], v[184:187], v[240:243]
	v_mfma_f32_16x16x32_bf16 v[112:115], v[172:175], v[184:187], v[112:115]
	ds_read_b128 v[180:183], v212 offset:51200
	s_waitcnt lgkmcnt(4)
	v_mfma_f32_16x16x32_bf16 v[52:55], v[160:163], v[192:195], v[52:55]
	v_mfma_f32_16x16x32_bf16 v[8:11], v[164:167], v[192:195], v[8:11]
	v_mfma_f32_16x16x32_bf16 v[248:251], v[168:171], v[192:195], v[248:251]
	v_mfma_f32_16x16x32_bf16 v[116:119], v[172:175], v[192:195], v[116:119]
	ds_read_b128 v[184:187], v212 offset:53248
	s_waitcnt lgkmcnt(4)
	v_mfma_f32_16x16x32_bf16 v[56:59], v[160:163], v[196:199], v[56:59]
	v_mfma_f32_16x16x32_bf16 v[24:27], v[164:167], v[196:199], v[24:27]
	v_mfma_f32_16x16x32_bf16 v[252:255], v[168:171], v[196:199], v[252:255]
	v_mfma_f32_16x16x32_bf16 v[120:123], v[172:175], v[196:199], v[120:123]
	ds_read_b128 v[192:195], v212 offset:55296
	s_waitcnt lgkmcnt(4)
	v_mfma_f32_16x16x32_bf16 v[60:63], v[160:163], v[200:203], v[60:63]
	v_mfma_f32_16x16x32_bf16 v[28:31], v[164:167], v[200:203], v[28:31]
	v_mfma_f32_16x16x32_bf16 v[92:95], v[168:171], v[200:203], v[92:95]
	v_mfma_f32_16x16x32_bf16 v[124:127], v[172:175], v[200:203], v[124:127]
	s_waitcnt vmcnt(16)
	s_barrier
	s_waitcnt vmcnt(8)
	ds_read_b128 v[196:199], v212 offset:57344
	global_load_dwordx4 v[160:163], v66, s[84:85] offset:1024
	s_waitcnt lgkmcnt(4)
	v_mfma_f32_16x16x32_bf16 v[32:35], v[76:79], v[176:179], v[32:35]
	v_mfma_f32_16x16x32_bf16 v[4:7], v[80:83], v[176:179], v[4:7]
	v_mfma_f32_16x16x32_bf16 v[188:191], v[84:87], v[176:179], v[188:191]
	v_mfma_f32_16x16x32_bf16 v[96:99], v[88:91], v[176:179], v[96:99]
	ds_read_b128 v[200:203], v212 offset:59392
	global_load_dwordx4 v[164:167], v67, s[84:85] offset:1024
	s_waitcnt lgkmcnt(4)
	v_mfma_f32_16x16x32_bf16 v[36:39], v[76:79], v[180:183], v[36:39]
	v_mfma_f32_16x16x32_bf16 v[12:15], v[80:83], v[180:183], v[12:15]
	v_mfma_f32_16x16x32_bf16 v[208:211], v[84:87], v[180:183], v[208:211]
	v_mfma_f32_16x16x32_bf16 v[100:103], v[88:91], v[180:183], v[100:103]
	ds_read_b128 v[176:179], v212 offset:61440
	global_load_dwordx4 v[168:171], v66, s[92:93] offset:1024
	s_waitcnt lgkmcnt(4)
	v_mfma_f32_16x16x32_bf16 v[40:43], v[76:79], v[184:187], v[40:43]
	v_mfma_f32_16x16x32_bf16 v[16:19], v[80:83], v[184:187], v[16:19]
	v_mfma_f32_16x16x32_bf16 v[232:235], v[84:87], v[184:187], v[232:235]
	v_mfma_f32_16x16x32_bf16 v[104:107], v[88:91], v[184:187], v[104:107]
	ds_read_b128 v[180:183], v212 offset:63488
	global_load_dwordx4 v[172:175], v67, s[92:93] offset:1024
	s_add_u32 s84, s84, 0x800
	s_addc_u32 s85, s85, 0
	s_add_u32 s92, s92, 0x800
	s_addc_u32 s93, s93, 0
	s_waitcnt lgkmcnt(4)
	v_mfma_f32_16x16x32_bf16 v[44:47], v[76:79], v[192:195], v[44:47]
	v_mfma_f32_16x16x32_bf16 v[20:23], v[80:83], v[192:195], v[20:23]
	v_mfma_f32_16x16x32_bf16 v[236:239], v[84:87], v[192:195], v[236:239]
	v_mfma_f32_16x16x32_bf16 v[108:111], v[88:91], v[192:195], v[108:111]
	ds_read_b128 v[184:187], v75 offset:0
	s_add_u32 m0, s88, 32768
	s_nop 0
	global_load_lds_dwordx4 v68, s[86:87]
	s_waitcnt lgkmcnt(4)
	v_mfma_f32_16x16x32_bf16 v[48:51], v[76:79], v[196:199], v[48:51]
	v_mfma_f32_16x16x32_bf16 v[0:3], v[80:83], v[196:199], v[0:3]
	v_mfma_f32_16x16x32_bf16 v[240:243], v[84:87], v[196:199], v[240:243]
	v_mfma_f32_16x16x32_bf16 v[112:115], v[88:91], v[196:199], v[112:115]
	ds_read_b128 v[192:195], v75 offset:2048
	s_add_u32 m0, s88, 36864
	s_nop 0
	global_load_lds_dwordx4 v69, s[86:87]
	s_waitcnt lgkmcnt(4)
	v_mfma_f32_16x16x32_bf16 v[52:55], v[76:79], v[200:203], v[52:55]
	v_mfma_f32_16x16x32_bf16 v[8:11], v[80:83], v[200:203], v[8:11]
	v_mfma_f32_16x16x32_bf16 v[248:251], v[84:87], v[200:203], v[248:251]
	v_mfma_f32_16x16x32_bf16 v[116:119], v[88:91], v[200:203], v[116:119]
	ds_read_b128 v[196:199], v75 offset:4096
	s_add_u32 m0, s88, 40960
	s_nop 0
	global_load_lds_dwordx4 v71, s[86:87]
	s_waitcnt lgkmcnt(4)
	v_mfma_f32_16x16x32_bf16 v[56:59], v[76:79], v[176:179], v[56:59]
	v_mfma_f32_16x16x32_bf16 v[24:27], v[80:83], v[176:179], v[24:27]
	v_mfma_f32_16x16x32_bf16 v[252:255], v[84:87], v[176:179], v[252:255]
	v_mfma_f32_16x16x32_bf16 v[120:123], v[88:91], v[176:179], v[120:123]
	ds_read_b128 v[200:203], v75 offset:6144
	s_add_u32 m0, s88, 45056
	s_nop 0
	global_load_lds_dwordx4 v74, s[86:87]
	s_add_u32 s86, s86, 128
	s_addc_u32 s87, s87, 0
	s_waitcnt lgkmcnt(4)
	v_mfma_f32_16x16x32_bf16 v[60:63], v[76:79], v[180:183], v[60:63]
	v_mfma_f32_16x16x32_bf16 v[28:31], v[80:83], v[180:183], v[28:31]
	v_mfma_f32_16x16x32_bf16 v[92:95], v[84:87], v[180:183], v[92:95]
	v_mfma_f32_16x16x32_bf16 v[124:127], v[88:91], v[180:183], v[124:127]
	s_waitcnt vmcnt(8)
	ds_read_b128 v[176:179], v75 offset:8192
	global_load_dwordx4 v[76:79], v66, s[84:85] offset:0
	s_waitcnt lgkmcnt(4)
	v_mfma_f32_16x16x32_bf16 v[32:35], v[140:143], v[184:187], v[32:35]
	v_mfma_f32_16x16x32_bf16 v[4:7], v[144:147], v[184:187], v[4:7]
	v_mfma_f32_16x16x32_bf16 v[188:191], v[148:151], v[184:187], v[188:191]
	v_mfma_f32_16x16x32_bf16 v[96:99], v[204:207], v[184:187], v[96:99]
	ds_read_b128 v[180:183], v75 offset:10240
	global_load_dwordx4 v[80:83], v67, s[84:85] offset:0
	s_waitcnt lgkmcnt(4)
	v_mfma_f32_16x16x32_bf16 v[36:39], v[140:143], v[192:195], v[36:39]
	v_mfma_f32_16x16x32_bf16 v[12:15], v[144:147], v[192:195], v[12:15]
	v_mfma_f32_16x16x32_bf16 v[208:211], v[148:151], v[192:195], v[208:211]
	v_mfma_f32_16x16x32_bf16 v[100:103], v[204:207], v[192:195], v[100:103]
	ds_read_b128 v[184:187], v75 offset:12288
	global_load_dwordx4 v[84:87], v66, s[92:93] offset:0
	s_waitcnt lgkmcnt(4)
	v_mfma_f32_16x16x32_bf16 v[40:43], v[140:143], v[196:199], v[40:43]
	v_mfma_f32_16x16x32_bf16 v[16:19], v[144:147], v[196:199], v[16:19]
	v_mfma_f32_16x16x32_bf16 v[232:235], v[148:151], v[196:199], v[232:235]
	v_mfma_f32_16x16x32_bf16 v[104:107], v[204:207], v[196:199], v[104:107]
	ds_read_b128 v[192:195], v75 offset:14336
	global_load_dwordx4 v[88:91], v67, s[92:93] offset:0
	s_waitcnt lgkmcnt(4)
	v_mfma_f32_16x16x32_bf16 v[44:47], v[140:143], v[200:203], v[44:47]
	v_mfma_f32_16x16x32_bf16 v[20:23], v[144:147], v[200:203], v[20:23]
	v_mfma_f32_16x16x32_bf16 v[236:239], v[148:151], v[200:203], v[236:239]
	v_mfma_f32_16x16x32_bf16 v[108:111], v[204:207], v[200:203], v[108:111]
	ds_read_b128 v[196:199], v212 offset:0
	s_waitcnt lgkmcnt(4)
	v_mfma_f32_16x16x32_bf16 v[48:51], v[140:143], v[176:179], v[48:51]
	v_mfma_f32_16x16x32_bf16 v[0:3], v[144:147], v[176:179], v[0:3]
	v_mfma_f32_16x16x32_bf16 v[240:243], v[148:151], v[176:179], v[240:243]
	v_mfma_f32_16x16x32_bf16 v[112:115], v[204:207], v[176:179], v[112:115]
	ds_read_b128 v[200:203], v212 offset:2048
	s_waitcnt lgkmcnt(4)
	v_mfma_f32_16x16x32_bf16 v[52:55], v[140:143], v[180:183], v[52:55]
	v_mfma_f32_16x16x32_bf16 v[8:11], v[144:147], v[180:183], v[8:11]
	v_mfma_f32_16x16x32_bf16 v[248:251], v[148:151], v[180:183], v[248:251]
	v_mfma_f32_16x16x32_bf16 v[116:119], v[204:207], v[180:183], v[116:119]
	ds_read_b128 v[176:179], v212 offset:4096
	s_waitcnt lgkmcnt(4)
	v_mfma_f32_16x16x32_bf16 v[56:59], v[140:143], v[184:187], v[56:59]
	v_mfma_f32_16x16x32_bf16 v[24:27], v[144:147], v[184:187], v[24:27]
	v_mfma_f32_16x16x32_bf16 v[252:255], v[148:151], v[184:187], v[252:255]
	v_mfma_f32_16x16x32_bf16 v[120:123], v[204:207], v[184:187], v[120:123]
	ds_read_b128 v[180:183], v212 offset:6144
	s_waitcnt lgkmcnt(4)
	v_mfma_f32_16x16x32_bf16 v[60:63], v[140:143], v[192:195], v[60:63]
	v_mfma_f32_16x16x32_bf16 v[28:31], v[144:147], v[192:195], v[28:31]
	v_mfma_f32_16x16x32_bf16 v[92:95], v[148:151], v[192:195], v[92:95]
	v_mfma_f32_16x16x32_bf16 v[124:127], v[204:207], v[192:195], v[124:127]
	s_waitcnt vmcnt(16)
	s_barrier
	s_waitcnt vmcnt(8)
	ds_read_b128 v[184:187], v212 offset:8192
	global_load_dwordx4 v[140:143], v66, s[84:85] offset:1024
	s_waitcnt lgkmcnt(4)
	v_mfma_f32_16x16x32_bf16 v[32:35], v[160:163], v[196:199], v[32:35]
	v_mfma_f32_16x16x32_bf16 v[4:7], v[164:167], v[196:199], v[4:7]
	v_mfma_f32_16x16x32_bf16 v[188:191], v[168:171], v[196:199], v[188:191]
	v_mfma_f32_16x16x32_bf16 v[96:99], v[172:175], v[196:199], v[96:99]
	ds_read_b128 v[192:195], v212 offset:10240
	global_load_dwordx4 v[144:147], v67, s[84:85] offset:1024
	s_waitcnt lgkmcnt(4)
	v_mfma_f32_16x16x32_bf16 v[36:39], v[160:163], v[200:203], v[36:39]
	v_mfma_f32_16x16x32_bf16 v[12:15], v[164:167], v[200:203], v[12:15]
	v_mfma_f32_16x16x32_bf16 v[208:211], v[168:171], v[200:203], v[208:211]
	v_mfma_f32_16x16x32_bf16 v[100:103], v[172:175], v[200:203], v[100:103]
	ds_read_b128 v[196:199], v212 offset:12288
	global_load_dwordx4 v[148:151], v66, s[92:93] offset:1024
	s_waitcnt lgkmcnt(4)
	v_mfma_f32_16x16x32_bf16 v[40:43], v[160:163], v[176:179], v[40:43]
	v_mfma_f32_16x16x32_bf16 v[16:19], v[164:167], v[176:179], v[16:19]
	v_mfma_f32_16x16x32_bf16 v[232:235], v[168:171], v[176:179], v[232:235]
	v_mfma_f32_16x16x32_bf16 v[104:107], v[172:175], v[176:179], v[104:107]
	ds_read_b128 v[200:203], v212 offset:14336
	global_load_dwordx4 v[204:207], v67, s[92:93] offset:1024
	s_add_u32 s84, s84, 0x800
	s_addc_u32 s85, s85, 0
	s_add_u32 s92, s92, 0x800
	s_addc_u32 s93, s93, 0
	s_waitcnt lgkmcnt(4)
	v_mfma_f32_16x16x32_bf16 v[44:47], v[160:163], v[180:183], v[44:47]
	v_mfma_f32_16x16x32_bf16 v[20:23], v[164:167], v[180:183], v[20:23]
	v_mfma_f32_16x16x32_bf16 v[236:239], v[168:171], v[180:183], v[236:239]
	v_mfma_f32_16x16x32_bf16 v[108:111], v[172:175], v[180:183], v[108:111]
	ds_read_b128 v[176:179], v75 offset:16384
	s_add_u32 m0, s88, 49152
	s_nop 0
	global_load_lds_dwordx4 v68, s[86:87]
	s_waitcnt lgkmcnt(4)
	v_mfma_f32_16x16x32_bf16 v[48:51], v[160:163], v[184:187], v[48:51]
	v_mfma_f32_16x16x32_bf16 v[0:3], v[164:167], v[184:187], v[0:3]
	v_mfma_f32_16x16x32_bf16 v[240:243], v[168:171], v[184:187], v[240:243]
	v_mfma_f32_16x16x32_bf16 v[112:115], v[172:175], v[184:187], v[112:115]
	ds_read_b128 v[180:183], v75 offset:18432
	s_add_u32 m0, s88, 53248
	s_nop 0
	global_load_lds_dwordx4 v69, s[86:87]
	s_waitcnt lgkmcnt(4)
	v_mfma_f32_16x16x32_bf16 v[52:55], v[160:163], v[192:195], v[52:55]
	v_mfma_f32_16x16x32_bf16 v[8:11], v[164:167], v[192:195], v[8:11]
	v_mfma_f32_16x16x32_bf16 v[248:251], v[168:171], v[192:195], v[248:251]
	v_mfma_f32_16x16x32_bf16 v[116:119], v[172:175], v[192:195], v[116:119]
	ds_read_b128 v[184:187], v75 offset:20480
	s_add_u32 m0, s88, 57344
	s_nop 0
	global_load_lds_dwordx4 v71, s[86:87]
	s_waitcnt lgkmcnt(4)
	v_mfma_f32_16x16x32_bf16 v[56:59], v[160:163], v[196:199], v[56:59]
	v_mfma_f32_16x16x32_bf16 v[24:27], v[164:167], v[196:199], v[24:27]
	v_mfma_f32_16x16x32_bf16 v[252:255], v[168:171], v[196:199], v[252:255]
	v_mfma_f32_16x16x32_bf16 v[120:123], v[172:175], v[196:199], v[120:123]
	ds_read_b128 v[192:195], v75 offset:22528
	s_add_u32 m0, s88, 61440
	s_nop 0
	global_load_lds_dwordx4 v74, s[86:87]
	s_add_u32 s86, s86, 128
	s_addc_u32 s87, s87, 0
	s_waitcnt lgkmcnt(4)
	v_mfma_f32_16x16x32_bf16 v[60:63], v[160:163], v[200:203], v[60:63]
	v_mfma_f32_16x16x32_bf16 v[28:31], v[164:167], v[200:203], v[28:31]
	v_mfma_f32_16x16x32_bf16 v[92:95], v[168:171], v[200:203], v[92:95]
	v_mfma_f32_16x16x32_bf16 v[124:127], v[172:175], v[200:203], v[124:127]
	s_waitcnt vmcnt(8)
	ds_read_b128 v[196:199], v75 offset:24576
	global_load_dwordx4 v[160:163], v66, s[84:85] offset:0
	s_waitcnt lgkmcnt(4)
	v_mfma_f32_16x16x32_bf16 v[32:35], v[76:79], v[176:179], v[32:35]
	v_mfma_f32_16x16x32_bf16 v[4:7], v[80:83], v[176:179], v[4:7]
	v_mfma_f32_16x16x32_bf16 v[188:191], v[84:87], v[176:179], v[188:191]
	v_mfma_f32_16x16x32_bf16 v[96:99], v[88:91], v[176:179], v[96:99]
	ds_read_b128 v[200:203], v75 offset:26624
	global_load_dwordx4 v[164:167], v67, s[84:85] offset:0
	s_waitcnt lgkmcnt(4)
	v_mfma_f32_16x16x32_bf16 v[36:39], v[76:79], v[180:183], v[36:39]
	v_mfma_f32_16x16x32_bf16 v[12:15], v[80:83], v[180:183], v[12:15]
	v_mfma_f32_16x16x32_bf16 v[208:211], v[84:87], v[180:183], v[208:211]
	v_mfma_f32_16x16x32_bf16 v[100:103], v[88:91], v[180:183], v[100:103]
	ds_read_b128 v[176:179], v75 offset:28672
	global_load_dwordx4 v[168:171], v66, s[92:93] offset:0
	s_waitcnt lgkmcnt(4)
	v_mfma_f32_16x16x32_bf16 v[40:43], v[76:79], v[184:187], v[40:43]
	v_mfma_f32_16x16x32_bf16 v[16:19], v[80:83], v[184:187], v[16:19]
	v_mfma_f32_16x16x32_bf16 v[232:235], v[84:87], v[184:187], v[232:235]
	v_mfma_f32_16x16x32_bf16 v[104:107], v[88:91], v[184:187], v[104:107]
	ds_read_b128 v[180:183], v75 offset:30720
	global_load_dwordx4 v[172:175], v67, s[92:93] offset:0
	s_waitcnt lgkmcnt(4)
	v_mfma_f32_16x16x32_bf16 v[44:47], v[76:79], v[192:195], v[44:47]
	v_mfma_f32_16x16x32_bf16 v[20:23], v[80:83], v[192:195], v[20:23]
	v_mfma_f32_16x16x32_bf16 v[236:239], v[84:87], v[192:195], v[236:239]
	v_mfma_f32_16x16x32_bf16 v[108:111], v[88:91], v[192:195], v[108:111]
	ds_read_b128 v[184:187], v212 offset:16384
	s_waitcnt lgkmcnt(4)
	v_mfma_f32_16x16x32_bf16 v[48:51], v[76:79], v[196:199], v[48:51]
	v_mfma_f32_16x16x32_bf16 v[0:3], v[80:83], v[196:199], v[0:3]
	v_mfma_f32_16x16x32_bf16 v[240:243], v[84:87], v[196:199], v[240:243]
	v_mfma_f32_16x16x32_bf16 v[112:115], v[88:91], v[196:199], v[112:115]
	ds_read_b128 v[192:195], v212 offset:18432
	s_waitcnt lgkmcnt(4)
	v_mfma_f32_16x16x32_bf16 v[52:55], v[76:79], v[200:203], v[52:55]
	v_mfma_f32_16x16x32_bf16 v[8:11], v[80:83], v[200:203], v[8:11]
	v_mfma_f32_16x16x32_bf16 v[248:251], v[84:87], v[200:203], v[248:251]
	v_mfma_f32_16x16x32_bf16 v[116:119], v[88:91], v[200:203], v[116:119]
	ds_read_b128 v[196:199], v212 offset:20480
	s_waitcnt lgkmcnt(4)
	v_mfma_f32_16x16x32_bf16 v[56:59], v[76:79], v[176:179], v[56:59]
	v_mfma_f32_16x16x32_bf16 v[24:27], v[80:83], v[176:179], v[24:27]
	v_mfma_f32_16x16x32_bf16 v[252:255], v[84:87], v[176:179], v[252:255]
	v_mfma_f32_16x16x32_bf16 v[120:123], v[88:91], v[176:179], v[120:123]
	ds_read_b128 v[200:203], v212 offset:22528
	s_waitcnt lgkmcnt(4)
	v_mfma_f32_16x16x32_bf16 v[60:63], v[76:79], v[180:183], v[60:63]
	v_mfma_f32_16x16x32_bf16 v[28:31], v[80:83], v[180:183], v[28:31]
	v_mfma_f32_16x16x32_bf16 v[92:95], v[84:87], v[180:183], v[92:95]
	v_mfma_f32_16x16x32_bf16 v[124:127], v[88:91], v[180:183], v[124:127]
	s_waitcnt vmcnt(16)
	s_barrier
	s_waitcnt vmcnt(8)
	ds_read_b128 v[176:179], v212 offset:24576
	global_load_dwordx4 v[76:79], v66, s[84:85] offset:1024
	s_waitcnt lgkmcnt(4)
	v_mfma_f32_16x16x32_bf16 v[32:35], v[140:143], v[184:187], v[32:35]
	v_mfma_f32_16x16x32_bf16 v[4:7], v[144:147], v[184:187], v[4:7]
	v_mfma_f32_16x16x32_bf16 v[188:191], v[148:151], v[184:187], v[188:191]
	v_mfma_f32_16x16x32_bf16 v[96:99], v[204:207], v[184:187], v[96:99]
	ds_read_b128 v[180:183], v212 offset:26624
	global_load_dwordx4 v[80:83], v67, s[84:85] offset:1024
	s_waitcnt lgkmcnt(4)
	v_mfma_f32_16x16x32_bf16 v[36:39], v[140:143], v[192:195], v[36:39]
	v_mfma_f32_16x16x32_bf16 v[12:15], v[144:147], v[192:195], v[12:15]
	v_mfma_f32_16x16x32_bf16 v[208:211], v[148:151], v[192:195], v[208:211]
	v_mfma_f32_16x16x32_bf16 v[100:103], v[204:207], v[192:195], v[100:103]
	ds_read_b128 v[184:187], v212 offset:28672
	global_load_dwordx4 v[84:87], v66, s[92:93] offset:1024
	s_waitcnt lgkmcnt(4)
	v_mfma_f32_16x16x32_bf16 v[40:43], v[140:143], v[196:199], v[40:43]
	v_mfma_f32_16x16x32_bf16 v[16:19], v[144:147], v[196:199], v[16:19]
	v_mfma_f32_16x16x32_bf16 v[232:235], v[148:151], v[196:199], v[232:235]
	v_mfma_f32_16x16x32_bf16 v[104:107], v[204:207], v[196:199], v[104:107]
	ds_read_b128 v[192:195], v212 offset:30720
	global_load_dwordx4 v[88:91], v67, s[92:93] offset:1024
	s_add_u32 s84, s84, 0x800
	s_addc_u32 s85, s85, 0
	s_add_u32 s92, s92, 0x800
	s_addc_u32 s93, s93, 0
	s_waitcnt lgkmcnt(4)
	v_mfma_f32_16x16x32_bf16 v[44:47], v[140:143], v[200:203], v[44:47]
	v_mfma_f32_16x16x32_bf16 v[20:23], v[144:147], v[200:203], v[20:23]
	v_mfma_f32_16x16x32_bf16 v[236:239], v[148:151], v[200:203], v[236:239]
	v_mfma_f32_16x16x32_bf16 v[108:111], v[204:207], v[200:203], v[108:111]
	ds_read_b128 v[196:199], v75 offset:32768
	s_add_u32 m0, s88, 0
	s_nop 0
	global_load_lds_dwordx4 v68, s[86:87]
	s_waitcnt lgkmcnt(4)
	v_mfma_f32_16x16x32_bf16 v[48:51], v[140:143], v[176:179], v[48:51]
	v_mfma_f32_16x16x32_bf16 v[0:3], v[144:147], v[176:179], v[0:3]
	v_mfma_f32_16x16x32_bf16 v[240:243], v[148:151], v[176:179], v[240:243]
	v_mfma_f32_16x16x32_bf16 v[112:115], v[204:207], v[176:179], v[112:115]
	ds_read_b128 v[200:203], v75 offset:34816
	s_add_u32 m0, s88, 4096
	s_nop 0
	global_load_lds_dwordx4 v69, s[86:87]
	s_waitcnt lgkmcnt(4)
	v_mfma_f32_16x16x32_bf16 v[52:55], v[140:143], v[180:183], v[52:55]
	v_mfma_f32_16x16x32_bf16 v[8:11], v[144:147], v[180:183], v[8:11]
	v_mfma_f32_16x16x32_bf16 v[248:251], v[148:151], v[180:183], v[248:251]
	v_mfma_f32_16x16x32_bf16 v[116:119], v[204:207], v[180:183], v[116:119]
	ds_read_b128 v[176:179], v75 offset:36864
	s_add_u32 m0, s88, 8192
	s_nop 0
	global_load_lds_dwordx4 v71, s[86:87]
	s_waitcnt lgkmcnt(4)
	v_mfma_f32_16x16x32_bf16 v[56:59], v[140:143], v[184:187], v[56:59]
	v_mfma_f32_16x16x32_bf16 v[24:27], v[144:147], v[184:187], v[24:27]
	v_mfma_f32_16x16x32_bf16 v[252:255], v[148:151], v[184:187], v[252:255]
	v_mfma_f32_16x16x32_bf16 v[120:123], v[204:207], v[184:187], v[120:123]
	ds_read_b128 v[180:183], v75 offset:38912
	s_add_u32 m0, s88, 12288
	s_nop 0
	global_load_lds_dwordx4 v74, s[86:87]
	s_add_u32 s86, s86, 128
	s_addc_u32 s87, s87, 0
	s_waitcnt lgkmcnt(4)
	v_mfma_f32_16x16x32_bf16 v[60:63], v[140:143], v[192:195], v[60:63]
	v_mfma_f32_16x16x32_bf16 v[28:31], v[144:147], v[192:195], v[28:31]
	v_mfma_f32_16x16x32_bf16 v[92:95], v[148:151], v[192:195], v[92:95]
	v_mfma_f32_16x16x32_bf16 v[124:127], v[204:207], v[192:195], v[124:127]
	s_waitcnt vmcnt(8)
	ds_read_b128 v[184:187], v75 offset:40960
	global_load_dwordx4 v[140:143], v66, s[84:85] offset:0
	s_waitcnt lgkmcnt(4)
	v_mfma_f32_16x16x32_bf16 v[32:35], v[160:163], v[196:199], v[32:35]
	v_mfma_f32_16x16x32_bf16 v[4:7], v[164:167], v[196:199], v[4:7]
	v_mfma_f32_16x16x32_bf16 v[188:191], v[168:171], v[196:199], v[188:191]
	v_mfma_f32_16x16x32_bf16 v[96:99], v[172:175], v[196:199], v[96:99]
	ds_read_b128 v[192:195], v75 offset:43008
	global_load_dwordx4 v[144:147], v67, s[84:85] offset:0
	s_waitcnt lgkmcnt(4)
	v_mfma_f32_16x16x32_bf16 v[36:39], v[160:163], v[200:203], v[36:39]
	v_mfma_f32_16x16x32_bf16 v[12:15], v[164:167], v[200:203], v[12:15]
	v_mfma_f32_16x16x32_bf16 v[208:211], v[168:171], v[200:203], v[208:211]
	v_mfma_f32_16x16x32_bf16 v[100:103], v[172:175], v[200:203], v[100:103]
	ds_read_b128 v[196:199], v75 offset:45056
	global_load_dwordx4 v[148:151], v66, s[92:93] offset:0
	s_waitcnt lgkmcnt(4)
	v_mfma_f32_16x16x32_bf16 v[40:43], v[160:163], v[176:179], v[40:43]
	v_mfma_f32_16x16x32_bf16 v[16:19], v[164:167], v[176:179], v[16:19]
	v_mfma_f32_16x16x32_bf16 v[232:235], v[168:171], v[176:179], v[232:235]
	v_mfma_f32_16x16x32_bf16 v[104:107], v[172:175], v[176:179], v[104:107]
	ds_read_b128 v[200:203], v75 offset:47104
	global_load_dwordx4 v[204:207], v67, s[92:93] offset:0
	s_waitcnt lgkmcnt(4)
	v_mfma_f32_16x16x32_bf16 v[44:47], v[160:163], v[180:183], v[44:47]
	v_mfma_f32_16x16x32_bf16 v[20:23], v[164:167], v[180:183], v[20:23]
	v_mfma_f32_16x16x32_bf16 v[236:239], v[168:171], v[180:183], v[236:239]
	v_mfma_f32_16x16x32_bf16 v[108:111], v[172:175], v[180:183], v[108:111]
	ds_read_b128 v[176:179], v212 offset:32768
	s_waitcnt lgkmcnt(4)
	v_mfma_f32_16x16x32_bf16 v[48:51], v[160:163], v[184:187], v[48:51]
	v_mfma_f32_16x16x32_bf16 v[0:3], v[164:167], v[184:187], v[0:3]
	v_mfma_f32_16x16x32_bf16 v[240:243], v[168:171], v[184:187], v[240:243]
	v_mfma_f32_16x16x32_bf16 v[112:115], v[172:175], v[184:187], v[112:115]
	ds_read_b128 v[180:183], v212 offset:34816
	s_waitcnt lgkmcnt(4)
	v_mfma_f32_16x16x32_bf16 v[52:55], v[160:163], v[192:195], v[52:55]
	v_mfma_f32_16x16x32_bf16 v[8:11], v[164:167], v[192:195], v[8:11]
	v_mfma_f32_16x16x32_bf16 v[248:251], v[168:171], v[192:195], v[248:251]
	v_mfma_f32_16x16x32_bf16 v[116:119], v[172:175], v[192:195], v[116:119]
	ds_read_b128 v[184:187], v212 offset:36864
	s_waitcnt lgkmcnt(4)
	v_mfma_f32_16x16x32_bf16 v[56:59], v[160:163], v[196:199], v[56:59]
	v_mfma_f32_16x16x32_bf16 v[24:27], v[164:167], v[196:199], v[24:27]
	v_mfma_f32_16x16x32_bf16 v[252:255], v[168:171], v[196:199], v[252:255]
	v_mfma_f32_16x16x32_bf16 v[120:123], v[172:175], v[196:199], v[120:123]
	ds_read_b128 v[192:195], v212 offset:38912
	s_waitcnt lgkmcnt(4)
	v_mfma_f32_16x16x32_bf16 v[60:63], v[160:163], v[200:203], v[60:63]
	v_mfma_f32_16x16x32_bf16 v[28:31], v[164:167], v[200:203], v[28:31]
	v_mfma_f32_16x16x32_bf16 v[92:95], v[168:171], v[200:203], v[92:95]
	v_mfma_f32_16x16x32_bf16 v[124:127], v[172:175], v[200:203], v[124:127]
	s_waitcnt vmcnt(16)
	s_barrier
	s_waitcnt vmcnt(8)
	ds_read_b128 v[196:199], v212 offset:40960
	global_load_dwordx4 v[160:163], v66, s[84:85] offset:1024
	s_waitcnt lgkmcnt(4)
	v_mfma_f32_16x16x32_bf16 v[32:35], v[76:79], v[176:179], v[32:35]
	v_mfma_f32_16x16x32_bf16 v[4:7], v[80:83], v[176:179], v[4:7]
	v_mfma_f32_16x16x32_bf16 v[188:191], v[84:87], v[176:179], v[188:191]
	v_mfma_f32_16x16x32_bf16 v[96:99], v[88:91], v[176:179], v[96:99]
	ds_read_b128 v[200:203], v212 offset:43008
	global_load_dwordx4 v[164:167], v67, s[84:85] offset:1024
	s_waitcnt lgkmcnt(4)
	v_mfma_f32_16x16x32_bf16 v[36:39], v[76:79], v[180:183], v[36:39]
	v_mfma_f32_16x16x32_bf16 v[12:15], v[80:83], v[180:183], v[12:15]
	v_mfma_f32_16x16x32_bf16 v[208:211], v[84:87], v[180:183], v[208:211]
	v_mfma_f32_16x16x32_bf16 v[100:103], v[88:91], v[180:183], v[100:103]
	ds_read_b128 v[176:179], v212 offset:45056
	global_load_dwordx4 v[168:171], v66, s[92:93] offset:1024
	s_waitcnt lgkmcnt(4)
	v_mfma_f32_16x16x32_bf16 v[40:43], v[76:79], v[184:187], v[40:43]
	v_mfma_f32_16x16x32_bf16 v[16:19], v[80:83], v[184:187], v[16:19]
	v_mfma_f32_16x16x32_bf16 v[232:235], v[84:87], v[184:187], v[232:235]
	v_mfma_f32_16x16x32_bf16 v[104:107], v[88:91], v[184:187], v[104:107]
	ds_read_b128 v[180:183], v212 offset:47104
	global_load_dwordx4 v[172:175], v67, s[92:93] offset:1024
	s_add_u32 s84, s84, 0x800
	s_addc_u32 s85, s85, 0
	s_add_u32 s92, s92, 0x800
	s_addc_u32 s93, s93, 0
	s_waitcnt lgkmcnt(4)
	v_mfma_f32_16x16x32_bf16 v[44:47], v[76:79], v[192:195], v[44:47]
	v_mfma_f32_16x16x32_bf16 v[20:23], v[80:83], v[192:195], v[20:23]
	v_mfma_f32_16x16x32_bf16 v[236:239], v[84:87], v[192:195], v[236:239]
	v_mfma_f32_16x16x32_bf16 v[108:111], v[88:91], v[192:195], v[108:111]
	ds_read_b128 v[184:187], v75 offset:49152
	s_add_u32 m0, s88, 16384
	s_nop 0
	global_load_lds_dwordx4 v68, s[86:87]
	s_waitcnt lgkmcnt(4)
	v_mfma_f32_16x16x32_bf16 v[48:51], v[76:79], v[196:199], v[48:51]
	v_mfma_f32_16x16x32_bf16 v[0:3], v[80:83], v[196:199], v[0:3]
	v_mfma_f32_16x16x32_bf16 v[240:243], v[84:87], v[196:199], v[240:243]
	v_mfma_f32_16x16x32_bf16 v[112:115], v[88:91], v[196:199], v[112:115]
	ds_read_b128 v[192:195], v75 offset:51200
	s_add_u32 m0, s88, 20480
	s_nop 0
	global_load_lds_dwordx4 v69, s[86:87]
	s_waitcnt lgkmcnt(4)
	v_mfma_f32_16x16x32_bf16 v[52:55], v[76:79], v[200:203], v[52:55]
	v_mfma_f32_16x16x32_bf16 v[8:11], v[80:83], v[200:203], v[8:11]
	v_mfma_f32_16x16x32_bf16 v[248:251], v[84:87], v[200:203], v[248:251]
	v_mfma_f32_16x16x32_bf16 v[116:119], v[88:91], v[200:203], v[116:119]
	ds_read_b128 v[196:199], v75 offset:53248
	s_add_u32 m0, s88, 24576
	s_nop 0
	global_load_lds_dwordx4 v71, s[86:87]
	s_waitcnt lgkmcnt(4)
	v_mfma_f32_16x16x32_bf16 v[56:59], v[76:79], v[176:179], v[56:59]
	v_mfma_f32_16x16x32_bf16 v[24:27], v[80:83], v[176:179], v[24:27]
	v_mfma_f32_16x16x32_bf16 v[252:255], v[84:87], v[176:179], v[252:255]
	v_mfma_f32_16x16x32_bf16 v[120:123], v[88:91], v[176:179], v[120:123]
	ds_read_b128 v[200:203], v75 offset:55296
	s_add_u32 m0, s88, 28672
	s_nop 0
	global_load_lds_dwordx4 v74, s[86:87]
	s_add_u32 s86, s86, 128
	s_addc_u32 s87, s87, 0
	s_waitcnt lgkmcnt(4)
	v_mfma_f32_16x16x32_bf16 v[60:63], v[76:79], v[180:183], v[60:63]
	v_mfma_f32_16x16x32_bf16 v[28:31], v[80:83], v[180:183], v[28:31]
	v_mfma_f32_16x16x32_bf16 v[92:95], v[84:87], v[180:183], v[92:95]
	v_mfma_f32_16x16x32_bf16 v[124:127], v[88:91], v[180:183], v[124:127]
	s_waitcnt vmcnt(8)
	ds_read_b128 v[176:179], v75 offset:57344
	global_load_dwordx4 v[76:79], v66, s[84:85] offset:0
	s_waitcnt lgkmcnt(4)
	v_mfma_f32_16x16x32_bf16 v[32:35], v[140:143], v[184:187], v[32:35]
	v_mfma_f32_16x16x32_bf16 v[4:7], v[144:147], v[184:187], v[4:7]
	v_mfma_f32_16x16x32_bf16 v[188:191], v[148:151], v[184:187], v[188:191]
	v_mfma_f32_16x16x32_bf16 v[96:99], v[204:207], v[184:187], v[96:99]
	ds_read_b128 v[180:183], v75 offset:59392
	global_load_dwordx4 v[80:83], v67, s[84:85] offset:0
	s_waitcnt lgkmcnt(4)
	v_mfma_f32_16x16x32_bf16 v[36:39], v[140:143], v[192:195], v[36:39]
	v_mfma_f32_16x16x32_bf16 v[12:15], v[144:147], v[192:195], v[12:15]
	v_mfma_f32_16x16x32_bf16 v[208:211], v[148:151], v[192:195], v[208:211]
	v_mfma_f32_16x16x32_bf16 v[100:103], v[204:207], v[192:195], v[100:103]
	ds_read_b128 v[184:187], v75 offset:61440
	global_load_dwordx4 v[84:87], v66, s[92:93] offset:0
	s_waitcnt lgkmcnt(4)
	v_mfma_f32_16x16x32_bf16 v[40:43], v[140:143], v[196:199], v[40:43]
	v_mfma_f32_16x16x32_bf16 v[16:19], v[144:147], v[196:199], v[16:19]
	v_mfma_f32_16x16x32_bf16 v[232:235], v[148:151], v[196:199], v[232:235]
	v_mfma_f32_16x16x32_bf16 v[104:107], v[204:207], v[196:199], v[104:107]
	ds_read_b128 v[192:195], v75 offset:63488
	global_load_dwordx4 v[88:91], v67, s[92:93] offset:0
	s_waitcnt lgkmcnt(4)
	v_mfma_f32_16x16x32_bf16 v[44:47], v[140:143], v[200:203], v[44:47]
	v_mfma_f32_16x16x32_bf16 v[20:23], v[144:147], v[200:203], v[20:23]
	v_mfma_f32_16x16x32_bf16 v[236:239], v[148:151], v[200:203], v[236:239]
	v_mfma_f32_16x16x32_bf16 v[108:111], v[204:207], v[200:203], v[108:111]
	ds_read_b128 v[196:199], v212 offset:49152
	s_waitcnt lgkmcnt(4)
	v_mfma_f32_16x16x32_bf16 v[48:51], v[140:143], v[176:179], v[48:51]
	v_mfma_f32_16x16x32_bf16 v[0:3], v[144:147], v[176:179], v[0:3]
	v_mfma_f32_16x16x32_bf16 v[240:243], v[148:151], v[176:179], v[240:243]
	v_mfma_f32_16x16x32_bf16 v[112:115], v[204:207], v[176:179], v[112:115]
	ds_read_b128 v[200:203], v212 offset:51200
	s_waitcnt lgkmcnt(4)
	v_mfma_f32_16x16x32_bf16 v[52:55], v[140:143], v[180:183], v[52:55]
	v_mfma_f32_16x16x32_bf16 v[8:11], v[144:147], v[180:183], v[8:11]
	v_mfma_f32_16x16x32_bf16 v[248:251], v[148:151], v[180:183], v[248:251]
	v_mfma_f32_16x16x32_bf16 v[116:119], v[204:207], v[180:183], v[116:119]
	ds_read_b128 v[176:179], v212 offset:53248
	s_waitcnt lgkmcnt(4)
	v_mfma_f32_16x16x32_bf16 v[56:59], v[140:143], v[184:187], v[56:59]
	v_mfma_f32_16x16x32_bf16 v[24:27], v[144:147], v[184:187], v[24:27]
	v_mfma_f32_16x16x32_bf16 v[252:255], v[148:151], v[184:187], v[252:255]
	v_mfma_f32_16x16x32_bf16 v[120:123], v[204:207], v[184:187], v[120:123]
	ds_read_b128 v[180:183], v212 offset:55296
	s_waitcnt lgkmcnt(4)
	v_mfma_f32_16x16x32_bf16 v[60:63], v[140:143], v[192:195], v[60:63]
	v_mfma_f32_16x16x32_bf16 v[28:31], v[144:147], v[192:195], v[28:31]
	v_mfma_f32_16x16x32_bf16 v[92:95], v[148:151], v[192:195], v[92:95]
	v_mfma_f32_16x16x32_bf16 v[124:127], v[204:207], v[192:195], v[124:127]
	s_waitcnt vmcnt(16)
	s_barrier
	s_waitcnt vmcnt(8)
	ds_read_b128 v[184:187], v212 offset:57344
	global_load_dwordx4 v[140:143], v66, s[84:85] offset:1024
	s_waitcnt lgkmcnt(4)
	v_mfma_f32_16x16x32_bf16 v[32:35], v[160:163], v[196:199], v[32:35]
	v_mfma_f32_16x16x32_bf16 v[4:7], v[164:167], v[196:199], v[4:7]
	v_mfma_f32_16x16x32_bf16 v[188:191], v[168:171], v[196:199], v[188:191]
	v_mfma_f32_16x16x32_bf16 v[96:99], v[172:175], v[196:199], v[96:99]
	ds_read_b128 v[192:195], v212 offset:59392
	global_load_dwordx4 v[144:147], v67, s[84:85] offset:1024
	s_waitcnt lgkmcnt(4)
	v_mfma_f32_16x16x32_bf16 v[36:39], v[160:163], v[200:203], v[36:39]
	v_mfma_f32_16x16x32_bf16 v[12:15], v[164:167], v[200:203], v[12:15]
	v_mfma_f32_16x16x32_bf16 v[208:211], v[168:171], v[200:203], v[208:211]
	v_mfma_f32_16x16x32_bf16 v[100:103], v[172:175], v[200:203], v[100:103]
	ds_read_b128 v[196:199], v212 offset:61440
	global_load_dwordx4 v[148:151], v66, s[92:93] offset:1024
	s_waitcnt lgkmcnt(4)
	v_mfma_f32_16x16x32_bf16 v[40:43], v[160:163], v[176:179], v[40:43]
	v_mfma_f32_16x16x32_bf16 v[16:19], v[164:167], v[176:179], v[16:19]
	v_mfma_f32_16x16x32_bf16 v[232:235], v[168:171], v[176:179], v[232:235]
	v_mfma_f32_16x16x32_bf16 v[104:107], v[172:175], v[176:179], v[104:107]
	ds_read_b128 v[200:203], v212 offset:63488
	global_load_dwordx4 v[204:207], v67, s[92:93] offset:1024
	s_add_u32 s84, s84, 0x800
	s_addc_u32 s85, s85, 0
	s_add_u32 s92, s92, 0x800
	s_addc_u32 s93, s93, 0
	s_waitcnt lgkmcnt(4)
	v_mfma_f32_16x16x32_bf16 v[44:47], v[160:163], v[180:183], v[44:47]
	v_mfma_f32_16x16x32_bf16 v[20:23], v[164:167], v[180:183], v[20:23]
	v_mfma_f32_16x16x32_bf16 v[236:239], v[168:171], v[180:183], v[236:239]
	v_mfma_f32_16x16x32_bf16 v[108:111], v[172:175], v[180:183], v[108:111]
	ds_read_b128 v[176:179], v75 offset:0
	s_add_u32 m0, s88, 32768
	s_nop 0
	global_load_lds_dwordx4 v68, s[86:87]
	s_waitcnt lgkmcnt(4)
	v_mfma_f32_16x16x32_bf16 v[48:51], v[160:163], v[184:187], v[48:51]
	v_mfma_f32_16x16x32_bf16 v[0:3], v[164:167], v[184:187], v[0:3]
	v_mfma_f32_16x16x32_bf16 v[240:243], v[168:171], v[184:187], v[240:243]
	v_mfma_f32_16x16x32_bf16 v[112:115], v[172:175], v[184:187], v[112:115]
	ds_read_b128 v[180:183], v75 offset:2048
	s_add_u32 m0, s88, 36864
	s_nop 0
	global_load_lds_dwordx4 v69, s[86:87]
	s_waitcnt lgkmcnt(4)
	v_mfma_f32_16x16x32_bf16 v[52:55], v[160:163], v[192:195], v[52:55]
	v_mfma_f32_16x16x32_bf16 v[8:11], v[164:167], v[192:195], v[8:11]
	v_mfma_f32_16x16x32_bf16 v[248:251], v[168:171], v[192:195], v[248:251]
	v_mfma_f32_16x16x32_bf16 v[116:119], v[172:175], v[192:195], v[116:119]
	ds_read_b128 v[184:187], v75 offset:4096
	s_add_u32 m0, s88, 40960
	s_nop 0
	global_load_lds_dwordx4 v71, s[86:87]
	s_waitcnt lgkmcnt(4)
	v_mfma_f32_16x16x32_bf16 v[56:59], v[160:163], v[196:199], v[56:59]
	v_mfma_f32_16x16x32_bf16 v[24:27], v[164:167], v[196:199], v[24:27]
	v_mfma_f32_16x16x32_bf16 v[252:255], v[168:171], v[196:199], v[252:255]
	v_mfma_f32_16x16x32_bf16 v[120:123], v[172:175], v[196:199], v[120:123]
	ds_read_b128 v[192:195], v75 offset:6144
	s_add_u32 m0, s88, 45056
	s_nop 0
	global_load_lds_dwordx4 v74, s[86:87]
	s_add_u32 s86, s86, 128
	s_addc_u32 s87, s87, 0
	s_waitcnt lgkmcnt(4)
	v_mfma_f32_16x16x32_bf16 v[60:63], v[160:163], v[200:203], v[60:63]
	v_mfma_f32_16x16x32_bf16 v[28:31], v[164:167], v[200:203], v[28:31]
	v_mfma_f32_16x16x32_bf16 v[92:95], v[168:171], v[200:203], v[92:95]
	v_mfma_f32_16x16x32_bf16 v[124:127], v[172:175], v[200:203], v[124:127]
	s_waitcnt vmcnt(8)
	ds_read_b128 v[196:199], v75 offset:8192
	global_load_dwordx4 v[160:163], v66, s[84:85] offset:0
	s_waitcnt lgkmcnt(4)
	v_mfma_f32_16x16x32_bf16 v[32:35], v[76:79], v[176:179], v[32:35]
	v_mfma_f32_16x16x32_bf16 v[4:7], v[80:83], v[176:179], v[4:7]
	v_mfma_f32_16x16x32_bf16 v[188:191], v[84:87], v[176:179], v[188:191]
	v_mfma_f32_16x16x32_bf16 v[96:99], v[88:91], v[176:179], v[96:99]
	ds_read_b128 v[200:203], v75 offset:10240
	global_load_dwordx4 v[164:167], v67, s[84:85] offset:0
	s_waitcnt lgkmcnt(4)
	v_mfma_f32_16x16x32_bf16 v[36:39], v[76:79], v[180:183], v[36:39]
	v_mfma_f32_16x16x32_bf16 v[12:15], v[80:83], v[180:183], v[12:15]
	v_mfma_f32_16x16x32_bf16 v[208:211], v[84:87], v[180:183], v[208:211]
	v_mfma_f32_16x16x32_bf16 v[100:103], v[88:91], v[180:183], v[100:103]
	ds_read_b128 v[176:179], v75 offset:12288
	global_load_dwordx4 v[168:171], v66, s[92:93] offset:0
	s_waitcnt lgkmcnt(4)
	v_mfma_f32_16x16x32_bf16 v[40:43], v[76:79], v[184:187], v[40:43]
	v_mfma_f32_16x16x32_bf16 v[16:19], v[80:83], v[184:187], v[16:19]
	v_mfma_f32_16x16x32_bf16 v[232:235], v[84:87], v[184:187], v[232:235]
	v_mfma_f32_16x16x32_bf16 v[104:107], v[88:91], v[184:187], v[104:107]
	ds_read_b128 v[180:183], v75 offset:14336
	global_load_dwordx4 v[172:175], v67, s[92:93] offset:0
	s_waitcnt lgkmcnt(4)
	v_mfma_f32_16x16x32_bf16 v[44:47], v[76:79], v[192:195], v[44:47]
	v_mfma_f32_16x16x32_bf16 v[20:23], v[80:83], v[192:195], v[20:23]
	v_mfma_f32_16x16x32_bf16 v[236:239], v[84:87], v[192:195], v[236:239]
	v_mfma_f32_16x16x32_bf16 v[108:111], v[88:91], v[192:195], v[108:111]
	ds_read_b128 v[184:187], v212 offset:0
	s_waitcnt lgkmcnt(4)
	v_mfma_f32_16x16x32_bf16 v[48:51], v[76:79], v[196:199], v[48:51]
	v_mfma_f32_16x16x32_bf16 v[0:3], v[80:83], v[196:199], v[0:3]
	v_mfma_f32_16x16x32_bf16 v[240:243], v[84:87], v[196:199], v[240:243]
	v_mfma_f32_16x16x32_bf16 v[112:115], v[88:91], v[196:199], v[112:115]
	ds_read_b128 v[192:195], v212 offset:2048
	s_waitcnt lgkmcnt(4)
	v_mfma_f32_16x16x32_bf16 v[52:55], v[76:79], v[200:203], v[52:55]
	v_mfma_f32_16x16x32_bf16 v[8:11], v[80:83], v[200:203], v[8:11]
	v_mfma_f32_16x16x32_bf16 v[248:251], v[84:87], v[200:203], v[248:251]
	v_mfma_f32_16x16x32_bf16 v[116:119], v[88:91], v[200:203], v[116:119]
	ds_read_b128 v[196:199], v212 offset:4096
	s_waitcnt lgkmcnt(4)
	v_mfma_f32_16x16x32_bf16 v[56:59], v[76:79], v[176:179], v[56:59]
	v_mfma_f32_16x16x32_bf16 v[24:27], v[80:83], v[176:179], v[24:27]
	v_mfma_f32_16x16x32_bf16 v[252:255], v[84:87], v[176:179], v[252:255]
	v_mfma_f32_16x16x32_bf16 v[120:123], v[88:91], v[176:179], v[120:123]
	ds_read_b128 v[200:203], v212 offset:6144
	s_waitcnt lgkmcnt(4)
	v_mfma_f32_16x16x32_bf16 v[60:63], v[76:79], v[180:183], v[60:63]
	v_mfma_f32_16x16x32_bf16 v[28:31], v[80:83], v[180:183], v[28:31]
	v_mfma_f32_16x16x32_bf16 v[92:95], v[84:87], v[180:183], v[92:95]
	v_mfma_f32_16x16x32_bf16 v[124:127], v[88:91], v[180:183], v[124:127]
	s_waitcnt vmcnt(16)
	s_barrier
	s_waitcnt vmcnt(8)
	ds_read_b128 v[176:179], v212 offset:8192
	global_load_dwordx4 v[76:79], v66, s[84:85] offset:1024
	s_waitcnt lgkmcnt(4)
	v_mfma_f32_16x16x32_bf16 v[32:35], v[140:143], v[184:187], v[32:35]
	v_mfma_f32_16x16x32_bf16 v[4:7], v[144:147], v[184:187], v[4:7]
	v_mfma_f32_16x16x32_bf16 v[188:191], v[148:151], v[184:187], v[188:191]
	v_mfma_f32_16x16x32_bf16 v[96:99], v[204:207], v[184:187], v[96:99]
	ds_read_b128 v[180:183], v212 offset:10240
	global_load_dwordx4 v[80:83], v67, s[84:85] offset:1024
	s_waitcnt lgkmcnt(4)
	v_mfma_f32_16x16x32_bf16 v[36:39], v[140:143], v[192:195], v[36:39]
	v_mfma_f32_16x16x32_bf16 v[12:15], v[144:147], v[192:195], v[12:15]
	v_mfma_f32_16x16x32_bf16 v[208:211], v[148:151], v[192:195], v[208:211]
	v_mfma_f32_16x16x32_bf16 v[100:103], v[204:207], v[192:195], v[100:103]
	ds_read_b128 v[184:187], v212 offset:12288
	global_load_dwordx4 v[84:87], v66, s[92:93] offset:1024
	s_waitcnt lgkmcnt(4)
	v_mfma_f32_16x16x32_bf16 v[40:43], v[140:143], v[196:199], v[40:43]
	v_mfma_f32_16x16x32_bf16 v[16:19], v[144:147], v[196:199], v[16:19]
	v_mfma_f32_16x16x32_bf16 v[232:235], v[148:151], v[196:199], v[232:235]
	v_mfma_f32_16x16x32_bf16 v[104:107], v[204:207], v[196:199], v[104:107]
	ds_read_b128 v[192:195], v212 offset:14336
	global_load_dwordx4 v[88:91], v67, s[92:93] offset:1024
	s_add_u32 s84, s84, 0x800
	s_addc_u32 s85, s85, 0
	s_add_u32 s92, s92, 0x800
	s_addc_u32 s93, s93, 0
	s_waitcnt lgkmcnt(4)
	v_mfma_f32_16x16x32_bf16 v[44:47], v[140:143], v[200:203], v[44:47]
	v_mfma_f32_16x16x32_bf16 v[20:23], v[144:147], v[200:203], v[20:23]
	v_mfma_f32_16x16x32_bf16 v[236:239], v[148:151], v[200:203], v[236:239]
	v_mfma_f32_16x16x32_bf16 v[108:111], v[204:207], v[200:203], v[108:111]
	ds_read_b128 v[196:199], v75 offset:16384
	s_add_u32 m0, s88, 49152
	s_nop 0
	global_load_lds_dwordx4 v68, s[86:87]
	s_waitcnt lgkmcnt(4)
	v_mfma_f32_16x16x32_bf16 v[48:51], v[140:143], v[176:179], v[48:51]
	v_mfma_f32_16x16x32_bf16 v[0:3], v[144:147], v[176:179], v[0:3]
	v_mfma_f32_16x16x32_bf16 v[240:243], v[148:151], v[176:179], v[240:243]
	v_mfma_f32_16x16x32_bf16 v[112:115], v[204:207], v[176:179], v[112:115]
	ds_read_b128 v[200:203], v75 offset:18432
	s_add_u32 m0, s88, 53248
	s_nop 0
	global_load_lds_dwordx4 v69, s[86:87]
	s_waitcnt lgkmcnt(4)
	v_mfma_f32_16x16x32_bf16 v[52:55], v[140:143], v[180:183], v[52:55]
	v_mfma_f32_16x16x32_bf16 v[8:11], v[144:147], v[180:183], v[8:11]
	v_mfma_f32_16x16x32_bf16 v[248:251], v[148:151], v[180:183], v[248:251]
	v_mfma_f32_16x16x32_bf16 v[116:119], v[204:207], v[180:183], v[116:119]
	ds_read_b128 v[176:179], v75 offset:20480
	s_add_u32 m0, s88, 57344
	s_nop 0
	global_load_lds_dwordx4 v71, s[86:87]
	s_waitcnt lgkmcnt(4)
	v_mfma_f32_16x16x32_bf16 v[56:59], v[140:143], v[184:187], v[56:59]
	v_mfma_f32_16x16x32_bf16 v[24:27], v[144:147], v[184:187], v[24:27]
	v_mfma_f32_16x16x32_bf16 v[252:255], v[148:151], v[184:187], v[252:255]
	v_mfma_f32_16x16x32_bf16 v[120:123], v[204:207], v[184:187], v[120:123]
	ds_read_b128 v[180:183], v75 offset:22528
	s_add_u32 m0, s88, 61440
	s_nop 0
	global_load_lds_dwordx4 v74, s[86:87]
	s_add_u32 s86, s86, 128
	s_addc_u32 s87, s87, 0
	s_waitcnt lgkmcnt(4)
	v_mfma_f32_16x16x32_bf16 v[60:63], v[140:143], v[192:195], v[60:63]
	v_mfma_f32_16x16x32_bf16 v[28:31], v[144:147], v[192:195], v[28:31]
	v_mfma_f32_16x16x32_bf16 v[92:95], v[148:151], v[192:195], v[92:95]
	v_mfma_f32_16x16x32_bf16 v[124:127], v[204:207], v[192:195], v[124:127]
	s_waitcnt vmcnt(8)
	ds_read_b128 v[184:187], v75 offset:24576
	global_load_dwordx4 v[140:143], v66, s[84:85] offset:0
	s_waitcnt lgkmcnt(4)
	v_mfma_f32_16x16x32_bf16 v[32:35], v[160:163], v[196:199], v[32:35]
	v_mfma_f32_16x16x32_bf16 v[4:7], v[164:167], v[196:199], v[4:7]
	v_mfma_f32_16x16x32_bf16 v[188:191], v[168:171], v[196:199], v[188:191]
	v_mfma_f32_16x16x32_bf16 v[96:99], v[172:175], v[196:199], v[96:99]
	ds_read_b128 v[192:195], v75 offset:26624
	global_load_dwordx4 v[144:147], v67, s[84:85] offset:0
	s_waitcnt lgkmcnt(4)
	v_mfma_f32_16x16x32_bf16 v[36:39], v[160:163], v[200:203], v[36:39]
	v_mfma_f32_16x16x32_bf16 v[12:15], v[164:167], v[200:203], v[12:15]
	v_mfma_f32_16x16x32_bf16 v[208:211], v[168:171], v[200:203], v[208:211]
	v_mfma_f32_16x16x32_bf16 v[100:103], v[172:175], v[200:203], v[100:103]
	ds_read_b128 v[196:199], v75 offset:28672
	global_load_dwordx4 v[148:151], v66, s[92:93] offset:0
	s_waitcnt lgkmcnt(4)
	v_mfma_f32_16x16x32_bf16 v[40:43], v[160:163], v[176:179], v[40:43]
	v_mfma_f32_16x16x32_bf16 v[16:19], v[164:167], v[176:179], v[16:19]
	v_mfma_f32_16x16x32_bf16 v[232:235], v[168:171], v[176:179], v[232:235]
	v_mfma_f32_16x16x32_bf16 v[104:107], v[172:175], v[176:179], v[104:107]
	ds_read_b128 v[200:203], v75 offset:30720
	global_load_dwordx4 v[204:207], v67, s[92:93] offset:0
	s_waitcnt lgkmcnt(4)
	v_mfma_f32_16x16x32_bf16 v[44:47], v[160:163], v[180:183], v[44:47]
	v_mfma_f32_16x16x32_bf16 v[20:23], v[164:167], v[180:183], v[20:23]
	v_mfma_f32_16x16x32_bf16 v[236:239], v[168:171], v[180:183], v[236:239]
	v_mfma_f32_16x16x32_bf16 v[108:111], v[172:175], v[180:183], v[108:111]
	ds_read_b128 v[176:179], v212 offset:16384
	s_waitcnt lgkmcnt(4)
	v_mfma_f32_16x16x32_bf16 v[48:51], v[160:163], v[184:187], v[48:51]
	v_mfma_f32_16x16x32_bf16 v[0:3], v[164:167], v[184:187], v[0:3]
	v_mfma_f32_16x16x32_bf16 v[240:243], v[168:171], v[184:187], v[240:243]
	v_mfma_f32_16x16x32_bf16 v[112:115], v[172:175], v[184:187], v[112:115]
	ds_read_b128 v[180:183], v212 offset:18432
	s_waitcnt lgkmcnt(4)
	v_mfma_f32_16x16x32_bf16 v[52:55], v[160:163], v[192:195], v[52:55]
	v_mfma_f32_16x16x32_bf16 v[8:11], v[164:167], v[192:195], v[8:11]
	v_mfma_f32_16x16x32_bf16 v[248:251], v[168:171], v[192:195], v[248:251]
	v_mfma_f32_16x16x32_bf16 v[116:119], v[172:175], v[192:195], v[116:119]
	ds_read_b128 v[184:187], v212 offset:20480
	s_waitcnt lgkmcnt(4)
	v_mfma_f32_16x16x32_bf16 v[56:59], v[160:163], v[196:199], v[56:59]
	v_mfma_f32_16x16x32_bf16 v[24:27], v[164:167], v[196:199], v[24:27]
	v_mfma_f32_16x16x32_bf16 v[252:255], v[168:171], v[196:199], v[252:255]
	v_mfma_f32_16x16x32_bf16 v[120:123], v[172:175], v[196:199], v[120:123]
	ds_read_b128 v[192:195], v212 offset:22528
	s_waitcnt lgkmcnt(4)
	v_mfma_f32_16x16x32_bf16 v[60:63], v[160:163], v[200:203], v[60:63]
	v_mfma_f32_16x16x32_bf16 v[28:31], v[164:167], v[200:203], v[28:31]
	v_mfma_f32_16x16x32_bf16 v[92:95], v[168:171], v[200:203], v[92:95]
	v_mfma_f32_16x16x32_bf16 v[124:127], v[172:175], v[200:203], v[124:127]
	s_waitcnt vmcnt(16)
	s_barrier
	s_waitcnt vmcnt(8)
	ds_read_b128 v[196:199], v212 offset:24576
	global_load_dwordx4 v[160:163], v66, s[84:85] offset:1024
	s_waitcnt lgkmcnt(4)
	v_mfma_f32_16x16x32_bf16 v[32:35], v[76:79], v[176:179], v[32:35]
	v_mfma_f32_16x16x32_bf16 v[4:7], v[80:83], v[176:179], v[4:7]
	v_mfma_f32_16x16x32_bf16 v[188:191], v[84:87], v[176:179], v[188:191]
	v_mfma_f32_16x16x32_bf16 v[96:99], v[88:91], v[176:179], v[96:99]
	ds_read_b128 v[200:203], v212 offset:26624
	global_load_dwordx4 v[164:167], v67, s[84:85] offset:1024
	s_waitcnt lgkmcnt(4)
	v_mfma_f32_16x16x32_bf16 v[36:39], v[76:79], v[180:183], v[36:39]
	v_mfma_f32_16x16x32_bf16 v[12:15], v[80:83], v[180:183], v[12:15]
	v_mfma_f32_16x16x32_bf16 v[208:211], v[84:87], v[180:183], v[208:211]
	v_mfma_f32_16x16x32_bf16 v[100:103], v[88:91], v[180:183], v[100:103]
	ds_read_b128 v[176:179], v212 offset:28672
	global_load_dwordx4 v[168:171], v66, s[92:93] offset:1024
	s_waitcnt lgkmcnt(4)
	v_mfma_f32_16x16x32_bf16 v[40:43], v[76:79], v[184:187], v[40:43]
	v_mfma_f32_16x16x32_bf16 v[16:19], v[80:83], v[184:187], v[16:19]
	v_mfma_f32_16x16x32_bf16 v[232:235], v[84:87], v[184:187], v[232:235]
	v_mfma_f32_16x16x32_bf16 v[104:107], v[88:91], v[184:187], v[104:107]
	ds_read_b128 v[180:183], v212 offset:30720
	global_load_dwordx4 v[172:175], v67, s[92:93] offset:1024
	s_add_u32 s84, s84, 0x800
	s_addc_u32 s85, s85, 0
	s_add_u32 s92, s92, 0x800
	s_addc_u32 s93, s93, 0
	s_waitcnt lgkmcnt(4)
	v_mfma_f32_16x16x32_bf16 v[44:47], v[76:79], v[192:195], v[44:47]
	v_mfma_f32_16x16x32_bf16 v[20:23], v[80:83], v[192:195], v[20:23]
	v_mfma_f32_16x16x32_bf16 v[236:239], v[84:87], v[192:195], v[236:239]
	v_mfma_f32_16x16x32_bf16 v[108:111], v[88:91], v[192:195], v[108:111]
	ds_read_b128 v[184:187], v75 offset:32768
	s_waitcnt lgkmcnt(4)
	v_mfma_f32_16x16x32_bf16 v[48:51], v[76:79], v[196:199], v[48:51]
	v_mfma_f32_16x16x32_bf16 v[0:3], v[80:83], v[196:199], v[0:3]
	v_mfma_f32_16x16x32_bf16 v[240:243], v[84:87], v[196:199], v[240:243]
	v_mfma_f32_16x16x32_bf16 v[112:115], v[88:91], v[196:199], v[112:115]
	ds_read_b128 v[192:195], v75 offset:34816
	s_waitcnt lgkmcnt(4)
	v_mfma_f32_16x16x32_bf16 v[52:55], v[76:79], v[200:203], v[52:55]
	v_mfma_f32_16x16x32_bf16 v[8:11], v[80:83], v[200:203], v[8:11]
	v_mfma_f32_16x16x32_bf16 v[248:251], v[84:87], v[200:203], v[248:251]
	v_mfma_f32_16x16x32_bf16 v[116:119], v[88:91], v[200:203], v[116:119]
	ds_read_b128 v[196:199], v75 offset:36864
	s_waitcnt lgkmcnt(4)
	v_mfma_f32_16x16x32_bf16 v[56:59], v[76:79], v[176:179], v[56:59]
	v_mfma_f32_16x16x32_bf16 v[24:27], v[80:83], v[176:179], v[24:27]
	v_mfma_f32_16x16x32_bf16 v[252:255], v[84:87], v[176:179], v[252:255]
	v_mfma_f32_16x16x32_bf16 v[120:123], v[88:91], v[176:179], v[120:123]
	ds_read_b128 v[200:203], v75 offset:38912
	s_waitcnt lgkmcnt(4)
	v_mfma_f32_16x16x32_bf16 v[60:63], v[76:79], v[180:183], v[60:63]
	v_mfma_f32_16x16x32_bf16 v[28:31], v[80:83], v[180:183], v[28:31]
	v_mfma_f32_16x16x32_bf16 v[92:95], v[84:87], v[180:183], v[92:95]
	v_mfma_f32_16x16x32_bf16 v[124:127], v[88:91], v[180:183], v[124:127]
	s_waitcnt vmcnt(4)
	ds_read_b128 v[176:179], v75 offset:40960
	global_load_dwordx4 v[76:79], v66, s[84:85] offset:0
	s_waitcnt lgkmcnt(4)
	v_mfma_f32_16x16x32_bf16 v[32:35], v[140:143], v[184:187], v[32:35]
	v_mfma_f32_16x16x32_bf16 v[4:7], v[144:147], v[184:187], v[4:7]
	v_mfma_f32_16x16x32_bf16 v[188:191], v[148:151], v[184:187], v[188:191]
	v_mfma_f32_16x16x32_bf16 v[96:99], v[204:207], v[184:187], v[96:99]
	ds_read_b128 v[180:183], v75 offset:43008
	global_load_dwordx4 v[80:83], v67, s[84:85] offset:0
	s_waitcnt lgkmcnt(4)
	v_mfma_f32_16x16x32_bf16 v[36:39], v[140:143], v[192:195], v[36:39]
	v_mfma_f32_16x16x32_bf16 v[12:15], v[144:147], v[192:195], v[12:15]
	v_mfma_f32_16x16x32_bf16 v[208:211], v[148:151], v[192:195], v[208:211]
	v_mfma_f32_16x16x32_bf16 v[100:103], v[204:207], v[192:195], v[100:103]
	ds_read_b128 v[184:187], v75 offset:45056
	global_load_dwordx4 v[84:87], v66, s[92:93] offset:0
	s_waitcnt lgkmcnt(4)
	v_mfma_f32_16x16x32_bf16 v[40:43], v[140:143], v[196:199], v[40:43]
	v_mfma_f32_16x16x32_bf16 v[16:19], v[144:147], v[196:199], v[16:19]
	v_mfma_f32_16x16x32_bf16 v[232:235], v[148:151], v[196:199], v[232:235]
	v_mfma_f32_16x16x32_bf16 v[104:107], v[204:207], v[196:199], v[104:107]
	ds_read_b128 v[192:195], v75 offset:47104
	global_load_dwordx4 v[88:91], v67, s[92:93] offset:0
	s_waitcnt lgkmcnt(4)
	v_mfma_f32_16x16x32_bf16 v[44:47], v[140:143], v[200:203], v[44:47]
	v_mfma_f32_16x16x32_bf16 v[20:23], v[144:147], v[200:203], v[20:23]
	v_mfma_f32_16x16x32_bf16 v[236:239], v[148:151], v[200:203], v[236:239]
	v_mfma_f32_16x16x32_bf16 v[108:111], v[204:207], v[200:203], v[108:111]
	ds_read_b128 v[196:199], v212 offset:32768
	s_waitcnt lgkmcnt(4)
	v_mfma_f32_16x16x32_bf16 v[48:51], v[140:143], v[176:179], v[48:51]
	v_mfma_f32_16x16x32_bf16 v[0:3], v[144:147], v[176:179], v[0:3]
	v_mfma_f32_16x16x32_bf16 v[240:243], v[148:151], v[176:179], v[240:243]
	v_mfma_f32_16x16x32_bf16 v[112:115], v[204:207], v[176:179], v[112:115]
	ds_read_b128 v[200:203], v212 offset:34816
	s_waitcnt lgkmcnt(4)
	v_mfma_f32_16x16x32_bf16 v[52:55], v[140:143], v[180:183], v[52:55]
	v_mfma_f32_16x16x32_bf16 v[8:11], v[144:147], v[180:183], v[8:11]
	v_mfma_f32_16x16x32_bf16 v[248:251], v[148:151], v[180:183], v[248:251]
	v_mfma_f32_16x16x32_bf16 v[116:119], v[204:207], v[180:183], v[116:119]
	ds_read_b128 v[176:179], v212 offset:36864
	s_waitcnt lgkmcnt(4)
	v_mfma_f32_16x16x32_bf16 v[56:59], v[140:143], v[184:187], v[56:59]
	v_mfma_f32_16x16x32_bf16 v[24:27], v[144:147], v[184:187], v[24:27]
	v_mfma_f32_16x16x32_bf16 v[252:255], v[148:151], v[184:187], v[252:255]
	v_mfma_f32_16x16x32_bf16 v[120:123], v[204:207], v[184:187], v[120:123]
	ds_read_b128 v[180:183], v212 offset:38912
	s_waitcnt lgkmcnt(4)
	v_mfma_f32_16x16x32_bf16 v[60:63], v[140:143], v[192:195], v[60:63]
	v_mfma_f32_16x16x32_bf16 v[28:31], v[144:147], v[192:195], v[28:31]
	v_mfma_f32_16x16x32_bf16 v[92:95], v[148:151], v[192:195], v[92:95]
	v_mfma_f32_16x16x32_bf16 v[124:127], v[204:207], v[192:195], v[124:127]
	s_waitcnt vmcnt(12)
	s_barrier
	s_waitcnt vmcnt(4)
	ds_read_b128 v[184:187], v212 offset:40960
	global_load_dwordx4 v[140:143], v66, s[84:85] offset:1024
	s_waitcnt lgkmcnt(4)
	v_mfma_f32_16x16x32_bf16 v[32:35], v[160:163], v[196:199], v[32:35]
	v_mfma_f32_16x16x32_bf16 v[4:7], v[164:167], v[196:199], v[4:7]
	v_mfma_f32_16x16x32_bf16 v[188:191], v[168:171], v[196:199], v[188:191]
	v_mfma_f32_16x16x32_bf16 v[96:99], v[172:175], v[196:199], v[96:99]
	ds_read_b128 v[192:195], v212 offset:43008
	global_load_dwordx4 v[144:147], v67, s[84:85] offset:1024
	s_waitcnt lgkmcnt(4)
	v_mfma_f32_16x16x32_bf16 v[36:39], v[160:163], v[200:203], v[36:39]
	v_mfma_f32_16x16x32_bf16 v[12:15], v[164:167], v[200:203], v[12:15]
	v_mfma_f32_16x16x32_bf16 v[208:211], v[168:171], v[200:203], v[208:211]
	v_mfma_f32_16x16x32_bf16 v[100:103], v[172:175], v[200:203], v[100:103]
	ds_read_b128 v[196:199], v212 offset:45056
	global_load_dwordx4 v[148:151], v66, s[92:93] offset:1024
	s_waitcnt lgkmcnt(4)
	v_mfma_f32_16x16x32_bf16 v[40:43], v[160:163], v[176:179], v[40:43]
	v_mfma_f32_16x16x32_bf16 v[16:19], v[164:167], v[176:179], v[16:19]
	v_mfma_f32_16x16x32_bf16 v[232:235], v[168:171], v[176:179], v[232:235]
	v_mfma_f32_16x16x32_bf16 v[104:107], v[172:175], v[176:179], v[104:107]
	ds_read_b128 v[200:203], v212 offset:47104
	global_load_dwordx4 v[204:207], v67, s[92:93] offset:1024
	s_add_u32 s84, s84, 0x800
	s_addc_u32 s85, s85, 0
	s_add_u32 s92, s92, 0x800
	s_addc_u32 s93, s93, 0
	s_waitcnt lgkmcnt(4)
	v_mfma_f32_16x16x32_bf16 v[44:47], v[160:163], v[180:183], v[44:47]
	v_mfma_f32_16x16x32_bf16 v[20:23], v[164:167], v[180:183], v[20:23]
	v_mfma_f32_16x16x32_bf16 v[236:239], v[168:171], v[180:183], v[236:239]
	v_mfma_f32_16x16x32_bf16 v[108:111], v[172:175], v[180:183], v[108:111]
	ds_read_b128 v[176:179], v75 offset:49152
	s_waitcnt lgkmcnt(4)
	v_mfma_f32_16x16x32_bf16 v[48:51], v[160:163], v[184:187], v[48:51]
	v_mfma_f32_16x16x32_bf16 v[0:3], v[164:167], v[184:187], v[0:3]
	v_mfma_f32_16x16x32_bf16 v[240:243], v[168:171], v[184:187], v[240:243]
	v_mfma_f32_16x16x32_bf16 v[112:115], v[172:175], v[184:187], v[112:115]
	ds_read_b128 v[180:183], v75 offset:51200
	s_waitcnt lgkmcnt(4)
	v_mfma_f32_16x16x32_bf16 v[52:55], v[160:163], v[192:195], v[52:55]
	v_mfma_f32_16x16x32_bf16 v[8:11], v[164:167], v[192:195], v[8:11]
	v_mfma_f32_16x16x32_bf16 v[248:251], v[168:171], v[192:195], v[248:251]
	v_mfma_f32_16x16x32_bf16 v[116:119], v[172:175], v[192:195], v[116:119]
	ds_read_b128 v[184:187], v75 offset:53248
	s_waitcnt lgkmcnt(4)
	v_mfma_f32_16x16x32_bf16 v[56:59], v[160:163], v[196:199], v[56:59]
	v_mfma_f32_16x16x32_bf16 v[24:27], v[164:167], v[196:199], v[24:27]
	v_mfma_f32_16x16x32_bf16 v[252:255], v[168:171], v[196:199], v[252:255]
	v_mfma_f32_16x16x32_bf16 v[120:123], v[172:175], v[196:199], v[120:123]
	ds_read_b128 v[192:195], v75 offset:55296
	s_waitcnt lgkmcnt(4)
	v_mfma_f32_16x16x32_bf16 v[60:63], v[160:163], v[200:203], v[60:63]
	v_mfma_f32_16x16x32_bf16 v[28:31], v[164:167], v[200:203], v[28:31]
	v_mfma_f32_16x16x32_bf16 v[92:95], v[168:171], v[200:203], v[92:95]
	v_mfma_f32_16x16x32_bf16 v[124:127], v[172:175], v[200:203], v[124:127]
	s_waitcnt vmcnt(4)
	ds_read_b128 v[196:199], v75 offset:57344
	s_waitcnt lgkmcnt(4)
	v_mfma_f32_16x16x32_bf16 v[32:35], v[76:79], v[176:179], v[32:35]
	v_mfma_f32_16x16x32_bf16 v[4:7], v[80:83], v[176:179], v[4:7]
	v_mfma_f32_16x16x32_bf16 v[188:191], v[84:87], v[176:179], v[188:191]
	v_mfma_f32_16x16x32_bf16 v[96:99], v[88:91], v[176:179], v[96:99]
	ds_read_b128 v[200:203], v75 offset:59392
	s_waitcnt lgkmcnt(4)
	v_mfma_f32_16x16x32_bf16 v[36:39], v[76:79], v[180:183], v[36:39]
	v_mfma_f32_16x16x32_bf16 v[12:15], v[80:83], v[180:183], v[12:15]
	v_mfma_f32_16x16x32_bf16 v[208:211], v[84:87], v[180:183], v[208:211]
	v_mfma_f32_16x16x32_bf16 v[100:103], v[88:91], v[180:183], v[100:103]
	ds_read_b128 v[176:179], v75 offset:61440
	s_waitcnt lgkmcnt(4)
	v_mfma_f32_16x16x32_bf16 v[40:43], v[76:79], v[184:187], v[40:43]
	v_mfma_f32_16x16x32_bf16 v[16:19], v[80:83], v[184:187], v[16:19]
	v_mfma_f32_16x16x32_bf16 v[232:235], v[84:87], v[184:187], v[232:235]
	v_mfma_f32_16x16x32_bf16 v[104:107], v[88:91], v[184:187], v[104:107]
	ds_read_b128 v[180:183], v75 offset:63488
	s_waitcnt lgkmcnt(4)
	v_mfma_f32_16x16x32_bf16 v[44:47], v[76:79], v[192:195], v[44:47]
	v_mfma_f32_16x16x32_bf16 v[20:23], v[80:83], v[192:195], v[20:23]
	v_mfma_f32_16x16x32_bf16 v[236:239], v[84:87], v[192:195], v[236:239]
	v_mfma_f32_16x16x32_bf16 v[108:111], v[88:91], v[192:195], v[108:111]
	ds_read_b128 v[184:187], v212 offset:49152
	s_waitcnt lgkmcnt(4)
	v_mfma_f32_16x16x32_bf16 v[48:51], v[76:79], v[196:199], v[48:51]
	v_mfma_f32_16x16x32_bf16 v[0:3], v[80:83], v[196:199], v[0:3]
	v_mfma_f32_16x16x32_bf16 v[240:243], v[84:87], v[196:199], v[240:243]
	v_mfma_f32_16x16x32_bf16 v[112:115], v[88:91], v[196:199], v[112:115]
	ds_read_b128 v[192:195], v212 offset:51200
	s_waitcnt lgkmcnt(4)
	v_mfma_f32_16x16x32_bf16 v[52:55], v[76:79], v[200:203], v[52:55]
	v_mfma_f32_16x16x32_bf16 v[8:11], v[80:83], v[200:203], v[8:11]
	v_mfma_f32_16x16x32_bf16 v[248:251], v[84:87], v[200:203], v[248:251]
	v_mfma_f32_16x16x32_bf16 v[116:119], v[88:91], v[200:203], v[116:119]
	ds_read_b128 v[196:199], v212 offset:53248
	s_waitcnt lgkmcnt(4)
	v_mfma_f32_16x16x32_bf16 v[56:59], v[76:79], v[176:179], v[56:59]
	v_mfma_f32_16x16x32_bf16 v[24:27], v[80:83], v[176:179], v[24:27]
	v_mfma_f32_16x16x32_bf16 v[252:255], v[84:87], v[176:179], v[252:255]
	v_mfma_f32_16x16x32_bf16 v[120:123], v[88:91], v[176:179], v[120:123]
	ds_read_b128 v[200:203], v212 offset:55296
	s_waitcnt lgkmcnt(4)
	v_mfma_f32_16x16x32_bf16 v[60:63], v[76:79], v[180:183], v[60:63]
	v_mfma_f32_16x16x32_bf16 v[28:31], v[80:83], v[180:183], v[28:31]
	v_mfma_f32_16x16x32_bf16 v[92:95], v[84:87], v[180:183], v[92:95]
	v_mfma_f32_16x16x32_bf16 v[124:127], v[88:91], v[180:183], v[124:127]
	s_waitcnt vmcnt(0)
	ds_read_b128 v[176:179], v212 offset:57344
	s_waitcnt lgkmcnt(4)
	v_mfma_f32_16x16x32_bf16 v[32:35], v[140:143], v[184:187], v[32:35]
	v_mfma_f32_16x16x32_bf16 v[4:7], v[144:147], v[184:187], v[4:7]
	v_mfma_f32_16x16x32_bf16 v[188:191], v[148:151], v[184:187], v[188:191]
	v_mfma_f32_16x16x32_bf16 v[96:99], v[204:207], v[184:187], v[96:99]
	ds_read_b128 v[180:183], v212 offset:59392
	s_waitcnt lgkmcnt(4)
	v_mfma_f32_16x16x32_bf16 v[36:39], v[140:143], v[192:195], v[36:39]
	v_mfma_f32_16x16x32_bf16 v[12:15], v[144:147], v[192:195], v[12:15]
	v_mfma_f32_16x16x32_bf16 v[208:211], v[148:151], v[192:195], v[208:211]
	v_mfma_f32_16x16x32_bf16 v[100:103], v[204:207], v[192:195], v[100:103]
	ds_read_b128 v[184:187], v212 offset:61440
	s_waitcnt lgkmcnt(4)
	v_mfma_f32_16x16x32_bf16 v[40:43], v[140:143], v[196:199], v[40:43]
	v_mfma_f32_16x16x32_bf16 v[16:19], v[144:147], v[196:199], v[16:19]
	v_mfma_f32_16x16x32_bf16 v[232:235], v[148:151], v[196:199], v[232:235]
	v_mfma_f32_16x16x32_bf16 v[104:107], v[204:207], v[196:199], v[104:107]
	ds_read_b128 v[192:195], v212 offset:63488
	s_waitcnt lgkmcnt(4)
	v_mfma_f32_16x16x32_bf16 v[44:47], v[140:143], v[200:203], v[44:47]
	v_mfma_f32_16x16x32_bf16 v[20:23], v[144:147], v[200:203], v[20:23]
	v_mfma_f32_16x16x32_bf16 v[236:239], v[148:151], v[200:203], v[236:239]
	v_mfma_f32_16x16x32_bf16 v[108:111], v[204:207], v[200:203], v[108:111]
	s_waitcnt lgkmcnt(3)
	v_mfma_f32_16x16x32_bf16 v[48:51], v[140:143], v[176:179], v[48:51]
	v_mfma_f32_16x16x32_bf16 v[0:3], v[144:147], v[176:179], v[0:3]
	v_mfma_f32_16x16x32_bf16 v[240:243], v[148:151], v[176:179], v[240:243]
	v_mfma_f32_16x16x32_bf16 v[112:115], v[204:207], v[176:179], v[112:115]
	s_waitcnt lgkmcnt(2)
	v_mfma_f32_16x16x32_bf16 v[52:55], v[140:143], v[180:183], v[52:55]
	v_mfma_f32_16x16x32_bf16 v[8:11], v[144:147], v[180:183], v[8:11]
	v_mfma_f32_16x16x32_bf16 v[248:251], v[148:151], v[180:183], v[248:251]
	v_mfma_f32_16x16x32_bf16 v[116:119], v[204:207], v[180:183], v[116:119]
	s_waitcnt lgkmcnt(1)
	v_mfma_f32_16x16x32_bf16 v[56:59], v[140:143], v[184:187], v[56:59]
	v_mfma_f32_16x16x32_bf16 v[24:27], v[144:147], v[184:187], v[24:27]
	v_mfma_f32_16x16x32_bf16 v[252:255], v[148:151], v[184:187], v[252:255]
	v_mfma_f32_16x16x32_bf16 v[120:123], v[204:207], v[184:187], v[120:123]
	s_waitcnt lgkmcnt(0)
	v_mfma_f32_16x16x32_bf16 v[60:63], v[140:143], v[192:195], v[60:63]
	v_mfma_f32_16x16x32_bf16 v[28:31], v[144:147], v[192:195], v[28:31]
	v_mfma_f32_16x16x32_bf16 v[92:95], v[148:151], v[192:195], v[92:95]
	v_mfma_f32_16x16x32_bf16 v[124:127], v[204:207], v[192:195], v[124:127]
	s_nop 7
	s_nop 7
	s_waitcnt vmcnt(0) lgkmcnt(0)
	s_setprio 0
	s_barrier
	v_mov_b32_e32 v66, v92
	v_mov_b32_e32 v67, v93
	v_mov_b32_e32 v68, v94
	v_mov_b32_e32 v69, v95
	v_mov_b32_e32 v71, v96
	v_mov_b32_e32 v74, v97
	v_mov_b32_e32 v75, v98
	v_mov_b32_e32 v160, v99
	v_mov_b32_e32 v161, v100
	v_mov_b32_e32 v162, v101
	v_mov_b32_e32 v185, v102
	v_mov_b32_e32 v186, v103
	v_mov_b32_e32 v187, v104
	v_mov_b32_e32 v207, v105
	v_mov_b32_e32 v212, v106
	v_mov_b32_e32 v213, v107
	v_mov_b32_e32 v214, v108
	v_mov_b32_e32 v216, v109
	v_mov_b32_e32 v218, v110
	v_mov_b32_e32 v220, v111
	v_mov_b32_e32 v222, v112
	v_mov_b32_e32 v224, v113
	v_mov_b32_e32 v226, v114
	v_mov_b32_e32 v228, v115
	v_mov_b32_e32 v230, v116
	v_mov_b32_e32 v231, v117
	v_mov_b32_e32 v244, v118
	v_mov_b32_e32 v245, v119
	ds_write_b128 v129, v[120:123] offset:36864
	ds_write_b128 v129, v[124:127] offset:40960
	v_lshlrev_b32_e32 v77, 13, v135
	v_lshl_add_u32 v78, v134, 3, v138
	v_lshl_or_b32 v79, v134, 11, v77
	v_lshlrev_b32_e32 v81, 5, v138
	v_or3_b32 v163, v77, v137, v81
	v_lshl_or_b32 v164, v78, 2, v79
	v_add_u32_e32 v81, 0x60, v78
	v_add_u32_e32 v78, 0x70, v78
	v_and_b32_e32 v81, 0x7f, v81
	v_and_b32_e32 v78, 0x7f, v78
	v_lshl_or_b32 v165, v81, 2, v79
	v_lshl_or_b32 v166, v78, 2, v79
	v_add_u32_e32 v79, 8, v133
	v_and_b32_e32 v79, 0x78, v79
	v_lshlrev_b32_e32 v78, 9, v136
	v_lshlrev_b32_e32 v79, 2, v79
	v_or3_b32 v168, v77, v78, v79
	v_add_u32_e32 v79, 16, v133
	v_and_b32_e32 v79, 0x78, v79
	v_lshlrev_b32_e32 v78, 9, v132
	v_lshlrev_b32_e32 v79, 2, v79
	v_or3_b32 v170, v77, v78, v79
	v_add_u32_e32 v79, 24, v133
	v_and_b32_e32 v79, 0x78, v79
	v_lshlrev_b32_e32 v80, 5, v135
	v_lshlrev_b32_e32 v78, 9, v130
	v_lshlrev_b32_e32 v79, 2, v79
	v_or3_b32 v172, v77, v78, v79
	v_or_b32_e32 v77, 16, v80
	v_add_u32_e32 v81, 0x100, v131
	v_add_u32_e32 v82, 0x200, v131
	v_add_u32_e32 v83, 0x300, v131
	v_add_u32_e32 v84, 0x500, v131
	v_add_u32_e32 v85, 0x600, v131
	v_add_u32_e32 v86, 0x700, v131
	v_or_b32_e32 v174, v77, v134
	v_or_b32_e32 v175, v136, v77
	v_or_b32_e32 v176, v132, v77
	v_or_b32_e32 v177, v130, v77
	v_and_b32_e32 v77, 24, v153
	s_movk_i32 s94, 0x3c0
	v_lshrrev_b32_e32 v178, 4, v81
	v_lshrrev_b32_e32 v179, 4, v82
	v_lshrrev_b32_e32 v180, 4, v83
	v_lshrrev_b32_e32 v182, 4, v84
	v_lshrrev_b32_e32 v183, 4, v85
	v_lshrrev_b32_e32 v184, 4, v86
	v_or_b32_e32 v167, v134, v80
	v_or_b32_e32 v169, v136, v80
	v_or_b32_e32 v171, v132, v80
	v_or_b32_e32 v173, v130, v80
	v_and_or_b32 v77, v131, s94, v77
	v_mul_u32_u24_e32 v78, 0x110, v138
	v_lshlrev_b32_e32 v79, 4, v138
	v_mul_u32_u24_e32 v80, 0x110, v128
	v_mul_u32_u24_e32 v81, 0x110, v178
	v_mul_u32_u24_e32 v82, 0x110, v179
	v_mul_u32_u24_e32 v83, 0x110, v180
	v_mul_u32_u24_e32 v84, 0x110, v182
	v_mul_u32_u24_e32 v85, 0x110, v183
	v_mul_u32_u24_e32 v86, 0x110, v184
	v_or_b32_e32 v181, 64, v128
	v_lshlrev_b32_e32 v192, 2, v138
	v_add_u32_e32 v193, v77, v78
	v_add_u32_e32 v194, v79, v80
	v_add_u32_e32 v195, v79, v81
	v_add_u32_e32 v196, v79, v82
	v_add_u32_e32 v197, v79, v83
	v_add_u32_e32 v198, v79, v84
	v_add_u32_e32 v199, v79, v85
	v_add_u32_e32 v200, v79, v86
	v_mbcnt_hi_u32_b32 v201, -1, v155
	v_mov_b32_e32 v202, 0x3db504f3
	s_waitcnt lgkmcnt(0)
	s_mov_b64 s[58:59], -1
	s_cmp_lt_i32 s65, 4
	s_branch .Lmy_ip1_epi
